# GEMM K-loops: issue the two k-steps of each accumulator back to back (m,n,k order instead of k,m,n) in 9 of 10 MFMA mainloops; bit-identical
# speedup vs baseline: 1.0074x; 1.0074x over previous
; #define PG8_STAGE(bufoff, gbase, voff) do { _Pragma("unroll") for (int _i = 0; _i < 2; ++_i) \
;         __builtin_amdgcn_global_load_lds((const unsigned*)((const char*)(gbase) + (voff)[_i]), (LAS unsigned*)(lds + (bufoff) + ldsw + _i * 8192), 16, 0, 0); } while (0)
; #define PG8_LDA(dst, b, h) do { _Pragma("unroll") for (int m = 0; m < 4; ++m) _Pragma("unroll") for (int k = 0; k < 2; ++k) dst[m][k] = *(const LAS bf16x8*)(lds + PG8_SA(b, h) + aoff + m * 2048 + k * 1024); } while (0)
; #define PG8_LDB(dst, b, h) do { _Pragma("unroll") for (int n = 0; n < 2; ++n) _Pragma("unroll") for (int k = 0; k < 2; ++k) dst[n][k] = *(const LAS bf16x8*)(lds + PG8_SB(b, h) + boff + n * 2048 + k * 1024); } while (0)
; #define PG8_WAIT_V(n) asm volatile("s_waitcnt vmcnt(" #n ")" ::: "memory")
; #define PG8_WAIT_L(n) asm volatile("s_waitcnt lgkmcnt(" #n ")" ::: "memory")
; #define PG8_BAR __builtin_amdgcn_s_barrier()
; #define PG8_SCHED __builtin_amdgcn_sched_barrier(0)
; template <class Epi, class Sched, class Ptrs, bool ALIGN_EPI, bool I8 = false>
; __device__ __forceinline__ void gemm_phase(LAS unsigned char* lds, const Ptrs& P, const Sched& S, const Epi& E) {
;     ...
;             PG8_LDB(B0, 0, 0); PG8_LDB(B1, 0, 1); PG8_SCHED; PG8_LDA(At, 0, 0); PG8_STAGE(PG8_SA(1, 1), a1 + hstepA, voffA);
;             PG8_WAIT_V(8); PG8_WAIT_L(0); PG8_BAR; PG8_MMA(0, 0, At, B0); PG8_MMA(0, 1, At, B1); PG8_BAR; PG8_SCHED;
.LBB0_234:
	ds_read_b128 v[148:151], v178
	ds_read_b128 v[154:157], v178 offset:1024
	ds_read_b128 v[184:187], v178 offset:2048
	ds_read_b128 v[188:191], v178 offset:3072
	ds_read_b128 v[192:195], v179
	ds_read_b128 v[196:199], v179 offset:1024
	ds_read_b128 v[200:203], v179 offset:2048
	ds_read_b128 v[204:207], v179 offset:3072
	s_add_u32 s38, s36, 0xfff00080
	s_addc_u32 s39, s37, -1
	s_cmp_eq_u32 s64, 60
	s_cselect_b32 s41, s9, s39
	s_cselect_b32 s40, s27, s38
	s_cselect_b32 s39, s25, s63
	s_cselect_b32 s38, s55, s62
	v_lshl_add_u64 v[164:165], s[36:37], 0, v[138:139]
	s_add_i32 m0, s35, 0xc000
	ds_read_b128 v[208:211], v180
	ds_read_b128 v[212:215], v180 offset:1024
	ds_read_b128 v[216:219], v180 offset:2048
	ds_read_b128 v[220:223], v180 offset:3072
	ds_read_b128 v[224:227], v180 offset:4096
	ds_read_b128 v[228:231], v180 offset:5120
	ds_read_b128 v[232:235], v180 offset:6144
	ds_read_b128 v[236:239], v180 offset:7168
	global_load_lds_dwordx4 v[164:165], off
	v_lshl_add_u64 v[164:165], s[36:37], 0, v[140:141]
	s_add_i32 m0, s35, 0xe000
	s_nop 0
	global_load_lds_dwordx4 v[164:165], off
	s_waitcnt vmcnt(8)
	s_waitcnt lgkmcnt(0)
	s_barrier
	s_setprio 1
	s_waitcnt lgkmcnt(0)
	v_mfma_f32_16x16x32_bf16 v[126:129], v[148:151], v[208:211], v[126:129]
	v_mfma_f32_16x16x32_bf16 v[126:129], v[154:157], v[212:215], v[126:129]
	v_mfma_f32_16x16x32_bf16 v[122:125], v[184:187], v[208:211], v[122:125]
	v_mfma_f32_16x16x32_bf16 v[122:125], v[188:191], v[212:215], v[122:125]
	v_mfma_f32_16x16x32_bf16 v[114:117], v[148:151], v[216:219], v[114:117]
	v_mfma_f32_16x16x32_bf16 v[114:117], v[154:157], v[220:223], v[114:117]
	v_mfma_f32_16x16x32_bf16 v[106:109], v[184:187], v[216:219], v[106:109]
	v_mfma_f32_16x16x32_bf16 v[106:109], v[188:191], v[220:223], v[106:109]
	v_mfma_f32_16x16x32_bf16 v[98:101], v[148:151], v[224:227], v[98:101]
	v_mfma_f32_16x16x32_bf16 v[98:101], v[154:157], v[228:231], v[98:101]
	v_mfma_f32_16x16x32_bf16 v[90:93], v[184:187], v[224:227], v[90:93]
	v_mfma_f32_16x16x32_bf16 v[90:93], v[188:191], v[228:231], v[90:93]
	v_mfma_f32_16x16x32_bf16 v[82:85], v[148:151], v[232:235], v[82:85]
	v_mfma_f32_16x16x32_bf16 v[82:85], v[154:157], v[236:239], v[82:85]
	v_mfma_f32_16x16x32_bf16 v[74:77], v[184:187], v[232:235], v[74:77]
	v_mfma_f32_16x16x32_bf16 v[74:77], v[188:191], v[236:239], v[74:77]
	s_setprio 0
	s_setprio 1
	v_mfma_f32_16x16x32_bf16 v[118:121], v[192:195], v[208:211], v[118:121]
	v_mfma_f32_16x16x32_bf16 v[118:121], v[196:199], v[212:215], v[118:121]
	v_mfma_f32_16x16x32_bf16 v[110:113], v[200:203], v[208:211], v[110:113]
	v_mfma_f32_16x16x32_bf16 v[110:113], v[204:207], v[212:215], v[110:113]
	v_mfma_f32_16x16x32_bf16 v[102:105], v[192:195], v[216:219], v[102:105]
	v_mfma_f32_16x16x32_bf16 v[102:105], v[196:199], v[220:223], v[102:105]
	v_mfma_f32_16x16x32_bf16 v[94:97], v[200:203], v[216:219], v[94:97]
	v_mfma_f32_16x16x32_bf16 v[94:97], v[204:207], v[220:223], v[94:97]
	v_mfma_f32_16x16x32_bf16 v[86:89], v[192:195], v[224:227], v[86:89]
	v_mfma_f32_16x16x32_bf16 v[86:89], v[196:199], v[228:231], v[86:89]
	v_mfma_f32_16x16x32_bf16 v[78:81], v[200:203], v[224:227], v[78:81]
	v_mfma_f32_16x16x32_bf16 v[78:81], v[204:207], v[228:231], v[78:81]
	v_mfma_f32_16x16x32_bf16 v[70:73], v[192:195], v[232:235], v[70:73]
	v_mfma_f32_16x16x32_bf16 v[70:73], v[196:199], v[236:239], v[70:73]
	v_mfma_f32_16x16x32_bf16 v[66:69], v[200:203], v[232:235], v[66:69]
	v_mfma_f32_16x16x32_bf16 v[66:69], v[204:207], v[236:239], v[66:69]
	s_setprio 0
	s_barrier
	s_add_i32 s65, s52, s42
	v_lshl_add_u64 v[164:165], s[38:39], 0, v[132:133]
	s_mov_b32 m0, s65
	ds_read_b128 v[208:211], v180 offset:16384
	ds_read_b128 v[212:215], v180 offset:17408
	ds_read_b128 v[216:219], v180 offset:18432
	ds_read_b128 v[220:223], v180 offset:19456
	ds_read_b128 v[224:227], v180 offset:20480
	ds_read_b128 v[228:231], v180 offset:21504
	ds_read_b128 v[232:235], v180 offset:22528
	ds_read_b128 v[236:239], v180 offset:23552
	global_load_lds_dwordx4 v[164:165], off
	s_add_i32 m0, s65, 0x2000
	s_add_u32 s66, s38, 0x100000
	v_lshl_add_u64 v[240:241], s[38:39], 0, v[136:137]
	s_addc_u32 s67, s39, 0
	s_add_i32 s65, s53, s42
	global_load_lds_dwordx4 v[240:241], off
	v_lshl_add_u64 v[242:243], s[66:67], 0, v[132:133]
	s_mov_b32 m0, s65
	v_lshl_add_u64 v[244:245], s[40:41], 0, v[134:135]
	global_load_lds_dwordx4 v[242:243], off
	v_lshl_add_u64 v[242:243], s[66:67], 0, v[136:137]
	s_add_i32 m0, s65, 0x2000
	s_nop 0
	global_load_lds_dwordx4 v[242:243], off
	v_lshl_add_u64 v[242:243], s[40:41], 0, v[130:131]
	s_mov_b32 m0, s35
	s_nop 0
	global_load_lds_dwordx4 v[242:243], off
	s_mov_b32 m0, s43
	s_nop 0
	global_load_lds_dwordx4 v[244:245], off
	s_waitcnt vmcnt(8)
	s_waitcnt lgkmcnt(0)
	s_barrier
; #define PG8_STAGE(bufoff, gbase, voff) do { _Pragma("unroll") for (int _i = 0; _i < 2; ++_i) \
;         __builtin_amdgcn_global_load_lds((const unsigned*)((const char*)(gbase) + (voff)[_i]), (LAS unsigned*)(lds + (bufoff) + ldsw + _i * 8192), 16, 0, 0); } while (0)
; #define PG8_LDA(dst, b, h) do { _Pragma("unroll") for (int m = 0; m < 4; ++m) _Pragma("unroll") for (int k = 0; k < 2; ++k) dst[m][k] = *(const LAS bf16x8*)(lds + PG8_SA(b, h) + aoff + m * 2048 + k * 1024); } while (0)
; #define PG8_LDB(dst, b, h) do { _Pragma("unroll") for (int n = 0; n < 2; ++n) _Pragma("unroll") for (int k = 0; k < 2; ++k) dst[n][k] = *(const LAS bf16x8*)(lds + PG8_SB(b, h) + boff + n * 2048 + k * 1024); } while (0)
; #define PG8_WAIT_V(n) asm volatile("s_waitcnt vmcnt(" #n ")" ::: "memory")
; #define PG8_WAIT_L(n) asm volatile("s_waitcnt lgkmcnt(" #n ")" ::: "memory")
; #define PG8_BAR __builtin_amdgcn_s_barrier()
; #define PG8_SCHED __builtin_amdgcn_sched_barrier(0)
; template <class Epi, class Sched, class Ptrs, bool ALIGN_EPI, bool I8 = false>
; __device__ __forceinline__ void gemm_phase(LAS unsigned char* lds, const Ptrs& P, const Sched& S, const Epi& E) {
;     ...
;             PG8_LDA(At, 0, 1); PG8_STAGE(PG8_SB(0, 0), b2, voffB); PG8_STAGE(PG8_SB(0, 1), b2 + hstepB, voffB); PG8_STAGE(PG8_SA(0, 0), a2, voffA);
;             PG8_WAIT_V(8); PG8_WAIT_L(0); PG8_BAR; PG8_MMA(1, 0, At, B0); PG8_MMA(1, 1, At, B1); PG8_BAR; PG8_SCHED;
;             PG8_LDB(B0, 1, 0); PG8_LDB(B1, 1, 1); PG8_SCHED; PG8_LDA(At, 1, 0); PG8_STAGE(PG8_SA(0, 1), a2 + hstepA, voffA);
;             PG8_WAIT_V(8); PG8_WAIT_L(0); PG8_BAR; PG8_MMA(0, 0, At, B0); PG8_MMA(0, 1, At, B1); PG8_BAR; PG8_SCHED;
	s_setprio 1
	s_waitcnt lgkmcnt(0)
	v_mfma_f32_16x16x32_bf16 v[62:65], v[148:151], v[208:211], v[62:65]
	v_mfma_f32_16x16x32_bf16 v[62:65], v[154:157], v[212:215], v[62:65]
	v_mfma_f32_16x16x32_bf16 v[58:61], v[184:187], v[208:211], v[58:61]
	v_mfma_f32_16x16x32_bf16 v[58:61], v[188:191], v[212:215], v[58:61]
	v_mfma_f32_16x16x32_bf16 v[50:53], v[148:151], v[216:219], v[50:53]
	v_mfma_f32_16x16x32_bf16 v[50:53], v[154:157], v[220:223], v[50:53]
	v_mfma_f32_16x16x32_bf16 v[42:45], v[184:187], v[216:219], v[42:45]
	v_mfma_f32_16x16x32_bf16 v[42:45], v[188:191], v[220:223], v[42:45]
	v_mfma_f32_16x16x32_bf16 v[34:37], v[148:151], v[224:227], v[34:37]
	v_mfma_f32_16x16x32_bf16 v[34:37], v[154:157], v[228:231], v[34:37]
	v_mfma_f32_16x16x32_bf16 v[26:29], v[184:187], v[224:227], v[26:29]
	v_mfma_f32_16x16x32_bf16 v[26:29], v[188:191], v[228:231], v[26:29]
	v_mfma_f32_16x16x32_bf16 v[18:21], v[148:151], v[232:235], v[18:21]
	v_mfma_f32_16x16x32_bf16 v[18:21], v[154:157], v[236:239], v[18:21]
	v_mfma_f32_16x16x32_bf16 v[10:13], v[184:187], v[232:235], v[10:13]
	v_mfma_f32_16x16x32_bf16 v[10:13], v[188:191], v[236:239], v[10:13]
	s_setprio 0
	s_setprio 1
	v_mfma_f32_16x16x32_bf16 v[54:57], v[192:195], v[208:211], v[54:57]
	v_mfma_f32_16x16x32_bf16 v[54:57], v[196:199], v[212:215], v[54:57]
	v_mfma_f32_16x16x32_bf16 v[46:49], v[200:203], v[208:211], v[46:49]
	v_mfma_f32_16x16x32_bf16 v[46:49], v[204:207], v[212:215], v[46:49]
	v_mfma_f32_16x16x32_bf16 v[38:41], v[192:195], v[216:219], v[38:41]
	v_mfma_f32_16x16x32_bf16 v[38:41], v[196:199], v[220:223], v[38:41]
	v_mfma_f32_16x16x32_bf16 v[30:33], v[200:203], v[216:219], v[30:33]
	v_mfma_f32_16x16x32_bf16 v[30:33], v[204:207], v[220:223], v[30:33]
	v_mfma_f32_16x16x32_bf16 v[22:25], v[192:195], v[224:227], v[22:25]
	v_mfma_f32_16x16x32_bf16 v[22:25], v[196:199], v[228:231], v[22:25]
	v_mfma_f32_16x16x32_bf16 v[14:17], v[200:203], v[224:227], v[14:17]
	v_mfma_f32_16x16x32_bf16 v[14:17], v[204:207], v[228:231], v[14:17]
	v_mfma_f32_16x16x32_bf16 v[6:9], v[192:195], v[232:235], v[6:9]
	v_mfma_f32_16x16x32_bf16 v[6:9], v[196:199], v[236:239], v[6:9]
	v_mfma_f32_16x16x32_bf16 v[2:5], v[200:203], v[232:235], v[2:5]
	v_mfma_f32_16x16x32_bf16 v[2:5], v[204:207], v[236:239], v[2:5]
	s_setprio 0
	s_barrier
	s_add_i32 s65, 0, 0x18000
	v_add_u32_e32 v146, s65, v176
	s_add_i32 s66, 0, 0x1c000
	ds_read_b128 v[148:151], v146
	ds_read_b128 v[154:157], v146 offset:1024
	ds_read_b128 v[184:187], v146 offset:2048
	ds_read_b128 v[188:191], v146 offset:3072
	v_add_u32_e32 v146, s66, v176
	ds_read_b128 v[192:195], v146
	ds_read_b128 v[196:199], v146 offset:1024
	ds_read_b128 v[200:203], v146 offset:2048
	ds_read_b128 v[204:207], v146 offset:3072
	s_add_u32 s40, s40, 0x100000
	s_addc_u32 s41, s41, 0
	s_mov_b32 m0, s44
	v_lshl_add_u64 v[246:247], s[40:41], 0, v[130:131]
	ds_read_b128 v[208:211], v180 offset:32768
	ds_read_b128 v[212:215], v180 offset:33792
	ds_read_b128 v[216:219], v180 offset:34816
	ds_read_b128 v[220:223], v180 offset:35840
	ds_read_b128 v[224:227], v180 offset:36864
	ds_read_b128 v[228:231], v180 offset:37888
	ds_read_b128 v[232:235], v180 offset:38912
	ds_read_b128 v[236:239], v180 offset:39936
	global_load_lds_dwordx4 v[246:247], off
	v_lshl_add_u64 v[246:247], s[40:41], 0, v[134:135]
	s_mov_b32 m0, s45
	s_nop 0
	global_load_lds_dwordx4 v[246:247], off
	s_waitcnt vmcnt(8)
	s_waitcnt lgkmcnt(0)
	s_barrier
	s_setprio 1
	s_waitcnt lgkmcnt(0)
	v_mfma_f32_16x16x32_bf16 v[126:129], v[148:151], v[208:211], v[126:129]
	v_mfma_f32_16x16x32_bf16 v[126:129], v[154:157], v[212:215], v[126:129]
	v_mfma_f32_16x16x32_bf16 v[122:125], v[184:187], v[208:211], v[122:125]
	v_mfma_f32_16x16x32_bf16 v[122:125], v[188:191], v[212:215], v[122:125]
	v_mfma_f32_16x16x32_bf16 v[114:117], v[148:151], v[216:219], v[114:117]
	v_mfma_f32_16x16x32_bf16 v[114:117], v[154:157], v[220:223], v[114:117]
	v_mfma_f32_16x16x32_bf16 v[106:109], v[184:187], v[216:219], v[106:109]
	v_mfma_f32_16x16x32_bf16 v[106:109], v[188:191], v[220:223], v[106:109]
	v_mfma_f32_16x16x32_bf16 v[98:101], v[148:151], v[224:227], v[98:101]
	v_mfma_f32_16x16x32_bf16 v[98:101], v[154:157], v[228:231], v[98:101]
	v_mfma_f32_16x16x32_bf16 v[90:93], v[184:187], v[224:227], v[90:93]
	v_mfma_f32_16x16x32_bf16 v[90:93], v[188:191], v[228:231], v[90:93]
	v_mfma_f32_16x16x32_bf16 v[82:85], v[148:151], v[232:235], v[82:85]
	v_mfma_f32_16x16x32_bf16 v[82:85], v[154:157], v[236:239], v[82:85]
	v_mfma_f32_16x16x32_bf16 v[74:77], v[184:187], v[232:235], v[74:77]
	v_mfma_f32_16x16x32_bf16 v[74:77], v[188:191], v[236:239], v[74:77]
	s_setprio 0
	s_setprio 1
	v_mfma_f32_16x16x32_bf16 v[118:121], v[192:195], v[208:211], v[118:121]
	v_mfma_f32_16x16x32_bf16 v[118:121], v[196:199], v[212:215], v[118:121]
	v_mfma_f32_16x16x32_bf16 v[110:113], v[200:203], v[208:211], v[110:113]
	v_mfma_f32_16x16x32_bf16 v[110:113], v[204:207], v[212:215], v[110:113]
	v_mfma_f32_16x16x32_bf16 v[102:105], v[192:195], v[216:219], v[102:105]
	v_mfma_f32_16x16x32_bf16 v[102:105], v[196:199], v[220:223], v[102:105]
	v_mfma_f32_16x16x32_bf16 v[94:97], v[200:203], v[216:219], v[94:97]
	v_mfma_f32_16x16x32_bf16 v[94:97], v[204:207], v[220:223], v[94:97]
	v_mfma_f32_16x16x32_bf16 v[86:89], v[192:195], v[224:227], v[86:89]
	v_mfma_f32_16x16x32_bf16 v[86:89], v[196:199], v[228:231], v[86:89]
	v_mfma_f32_16x16x32_bf16 v[78:81], v[200:203], v[224:227], v[78:81]
	v_mfma_f32_16x16x32_bf16 v[78:81], v[204:207], v[228:231], v[78:81]
	v_mfma_f32_16x16x32_bf16 v[70:73], v[192:195], v[232:235], v[70:73]
	v_mfma_f32_16x16x32_bf16 v[70:73], v[196:199], v[236:239], v[70:73]
	v_mfma_f32_16x16x32_bf16 v[66:69], v[200:203], v[232:235], v[66:69]
	v_mfma_f32_16x16x32_bf16 v[66:69], v[204:207], v[236:239], v[66:69]
	s_setprio 0
	s_barrier
; #define PG8_STAGE(bufoff, gbase, voff) do { _Pragma("unroll") for (int _i = 0; _i < 2; ++_i) \
;         __builtin_amdgcn_global_load_lds((const unsigned*)((const char*)(gbase) + (voff)[_i]), (LAS unsigned*)(lds + (bufoff) + ldsw + _i * 8192), 16, 0, 0); } while (0)
; #define PG8_LDA(dst, b, h) do { _Pragma("unroll") for (int m = 0; m < 4; ++m) _Pragma("unroll") for (int k = 0; k < 2; ++k) dst[m][k] = *(const LAS bf16x8*)(lds + PG8_SA(b, h) + aoff + m * 2048 + k * 1024); } while (0)
; #define PG8_WAIT_V(n) asm volatile("s_waitcnt vmcnt(" #n ")" ::: "memory")
; #define PG8_WAIT_L(n) asm volatile("s_waitcnt lgkmcnt(" #n ")" ::: "memory")
; #define PG8_BAR __builtin_amdgcn_s_barrier()
; #define PG8_SCHED __builtin_amdgcn_sched_barrier(0)
; template <class Epi, class Sched, class Ptrs, bool ALIGN_EPI, bool I8 = false>
; __device__ __forceinline__ void gemm_phase(LAS unsigned char* lds, const Ptrs& P, const Sched& S, const Epi& E) {
;     ...
;             PG8_LDA(At, 1, 1); PG8_STAGE(PG8_SB(1, 0), b3, voffB); PG8_STAGE(PG8_SB(1, 1), b3 + hstepB, voffB); PG8_STAGE(PG8_SA(1, 0), a3, voffA);
;             PG8_WAIT_V(8); PG8_WAIT_L(0); PG8_BAR; PG8_MMA(1, 0, At, B0); PG8_MMA(1, 1, At, B1); PG8_BAR; PG8_SCHED;
;         }
	s_add_i32 s40, s65, s42
	v_lshl_add_u64 v[164:165], v[164:165], 0, s[10:11]
	s_mov_b32 m0, s40
	ds_read_b128 v[208:211], v180 offset:49152
	ds_read_b128 v[212:215], v180 offset:50176
	ds_read_b128 v[216:219], v180 offset:51200
	ds_read_b128 v[220:223], v180 offset:52224
	ds_read_b128 v[224:227], v180 offset:53248
	ds_read_b128 v[228:231], v180 offset:54272
	ds_read_b128 v[232:235], v180 offset:55296
	ds_read_b128 v[236:239], v180 offset:56320
	global_load_lds_dwordx4 v[164:165], off
	s_add_i32 m0, s40, 0x2000
	s_add_u32 s38, s38, 0x100080
	v_lshl_add_u64 v[164:165], v[240:241], 0, s[10:11]
	s_addc_u32 s39, s39, 0
	s_add_i32 s40, s66, s42
	global_load_lds_dwordx4 v[164:165], off
	v_lshl_add_u64 v[164:165], s[38:39], 0, v[132:133]
	s_mov_b32 m0, s40
	s_nop 0
	global_load_lds_dwordx4 v[164:165], off
	v_lshl_add_u64 v[164:165], s[38:39], 0, v[136:137]
	s_add_i32 m0, s40, 0x2000
	s_nop 0
	global_load_lds_dwordx4 v[164:165], off
	v_lshl_add_u64 v[164:165], v[242:243], 0, s[10:11]
	s_mov_b32 m0, s47
	s_nop 0
	global_load_lds_dwordx4 v[164:165], off
	v_lshl_add_u64 v[164:165], v[244:245], 0, s[10:11]
	s_mov_b32 m0, s48
	s_nop 0
	global_load_lds_dwordx4 v[164:165], off
	s_waitcnt vmcnt(8)
	s_waitcnt lgkmcnt(0)
	s_barrier
	s_setprio 1
	s_waitcnt lgkmcnt(0)
	v_mfma_f32_16x16x32_bf16 v[62:65], v[148:151], v[208:211], v[62:65]
	v_mfma_f32_16x16x32_bf16 v[62:65], v[154:157], v[212:215], v[62:65]
	v_mfma_f32_16x16x32_bf16 v[58:61], v[184:187], v[208:211], v[58:61]
	v_mfma_f32_16x16x32_bf16 v[58:61], v[188:191], v[212:215], v[58:61]
	v_mfma_f32_16x16x32_bf16 v[50:53], v[148:151], v[216:219], v[50:53]
	v_mfma_f32_16x16x32_bf16 v[50:53], v[154:157], v[220:223], v[50:53]
	v_mfma_f32_16x16x32_bf16 v[42:45], v[184:187], v[216:219], v[42:45]
	v_mfma_f32_16x16x32_bf16 v[42:45], v[188:191], v[220:223], v[42:45]
	v_mfma_f32_16x16x32_bf16 v[34:37], v[148:151], v[224:227], v[34:37]
	v_mfma_f32_16x16x32_bf16 v[34:37], v[154:157], v[228:231], v[34:37]
	v_mfma_f32_16x16x32_bf16 v[26:29], v[184:187], v[224:227], v[26:29]
	v_mfma_f32_16x16x32_bf16 v[26:29], v[188:191], v[228:231], v[26:29]
	v_mfma_f32_16x16x32_bf16 v[18:21], v[148:151], v[232:235], v[18:21]
	v_mfma_f32_16x16x32_bf16 v[18:21], v[154:157], v[236:239], v[18:21]
	v_mfma_f32_16x16x32_bf16 v[10:13], v[184:187], v[232:235], v[10:13]
	v_mfma_f32_16x16x32_bf16 v[10:13], v[188:191], v[236:239], v[10:13]
	s_setprio 0
	s_setprio 1
	v_mfma_f32_16x16x32_bf16 v[54:57], v[192:195], v[208:211], v[54:57]
	v_mfma_f32_16x16x32_bf16 v[54:57], v[196:199], v[212:215], v[54:57]
	v_mfma_f32_16x16x32_bf16 v[46:49], v[200:203], v[208:211], v[46:49]
	v_mfma_f32_16x16x32_bf16 v[46:49], v[204:207], v[212:215], v[46:49]
	v_mfma_f32_16x16x32_bf16 v[38:41], v[192:195], v[216:219], v[38:41]
	v_mfma_f32_16x16x32_bf16 v[38:41], v[196:199], v[220:223], v[38:41]
	v_mfma_f32_16x16x32_bf16 v[30:33], v[200:203], v[216:219], v[30:33]
	v_mfma_f32_16x16x32_bf16 v[30:33], v[204:207], v[220:223], v[30:33]
	v_mfma_f32_16x16x32_bf16 v[22:25], v[192:195], v[224:227], v[22:25]
	v_mfma_f32_16x16x32_bf16 v[22:25], v[196:199], v[228:231], v[22:25]
	v_mfma_f32_16x16x32_bf16 v[14:17], v[200:203], v[224:227], v[14:17]
	v_mfma_f32_16x16x32_bf16 v[14:17], v[204:207], v[228:231], v[14:17]
	v_mfma_f32_16x16x32_bf16 v[6:9], v[192:195], v[232:235], v[6:9]
	v_mfma_f32_16x16x32_bf16 v[6:9], v[196:199], v[236:239], v[6:9]
	v_mfma_f32_16x16x32_bf16 v[2:5], v[200:203], v[232:235], v[2:5]
	v_mfma_f32_16x16x32_bf16 v[2:5], v[204:207], v[236:239], v[2:5]
	s_setprio 0
	s_barrier
	s_add_i32 s64, s64, 2
	s_add_u32 s36, s36, 0x100
	s_addc_u32 s37, s37, 0
	s_add_u32 s62, s62, 0x100
	s_addc_u32 s63, s63, 0
	s_cmp_gt_u32 s64, 61
	s_cbranch_scc0 .LBB0_234
	s_and_b64 vcc, exec, s[12:13]
	s_cbranch_vccz .LBB0_237
	s_barrier

; #define PG8_STAGE(bufoff, gbase, voff) do { _Pragma("unroll") for (int _i = 0; _i < 2; ++_i) \
;         __builtin_amdgcn_global_load_lds((const unsigned*)((const char*)(gbase) + (voff)[_i]), (LAS unsigned*)(lds + (bufoff) + ldsw + _i * 8192), 16, 0, 0); } while (0)
; #define PG8_LDA(dst, b, h) do { _Pragma("unroll") for (int m = 0; m < 4; ++m) _Pragma("unroll") for (int k = 0; k < 2; ++k) dst[m][k] = *(const LAS bf16x8*)(lds + PG8_SA(b, h) + aoff + m * 2048 + k * 1024); } while (0)
; #define PG8_LDB(dst, b, h) do { _Pragma("unroll") for (int n = 0; n < 2; ++n) _Pragma("unroll") for (int k = 0; k < 2; ++k) dst[n][k] = *(const LAS bf16x8*)(lds + PG8_SB(b, h) + boff + n * 2048 + k * 1024); } while (0)
; #define PG8_WAIT_V(n) asm volatile("s_waitcnt vmcnt(" #n ")" ::: "memory")
; #define PG8_WAIT_L(n) asm volatile("s_waitcnt lgkmcnt(" #n ")" ::: "memory")
; #define PG8_BAR __builtin_amdgcn_s_barrier()
; #define PG8_SCHED __builtin_amdgcn_sched_barrier(0)
; template <class Epi, class Sched, class Ptrs, bool ALIGN_EPI, bool I8 = false>
; __device__ __forceinline__ void gemm_phase(LAS unsigned char* lds, const Ptrs& P, const Sched& S, const Epi& E) {
;     ...
;             PG8_LDB(B0, 0, 0); PG8_LDB(B1, 0, 1); PG8_SCHED; PG8_LDA(At, 0, 0); PG8_STAGE(PG8_SA(1, 1), a1 + hstepA, voffA);
;             PG8_WAIT_V(8); PG8_WAIT_L(0); PG8_BAR; PG8_MMA(0, 0, At, B0); PG8_MMA(0, 1, At, B1); PG8_BAR; PG8_SCHED;
.LBB0_615:
	ds_read_b128 v[158:161], v154
	ds_read_b128 v[162:165], v154 offset:1024
	ds_read_b128 v[166:169], v154 offset:2048
	ds_read_b128 v[170:173], v154 offset:3072
	ds_read_b128 v[174:177], v155
	ds_read_b128 v[178:181], v155 offset:1024
	ds_read_b128 v[184:187], v155 offset:2048
	ds_read_b128 v[188:191], v155 offset:3072
	s_add_u32 s36, s34, 0xfff00080
	s_addc_u32 s37, s35, -1
	s_cmp_eq_u32 s62, 60
	s_cselect_b32 s39, s25, s37
	s_cselect_b32 s38, s55, s36
	s_cselect_b32 s37, s23, s61
	s_cselect_b32 s36, s57, s60
	v_lshl_add_u64 v[148:149], s[34:35], 0, v[140:141]
	s_add_i32 m0, s31, 0xc000
	ds_read_b128 v[192:195], v156
	ds_read_b128 v[196:199], v156 offset:1024
	ds_read_b128 v[200:203], v156 offset:2048
	ds_read_b128 v[204:207], v156 offset:3072
	ds_read_b128 v[208:211], v156 offset:4096
	ds_read_b128 v[212:215], v156 offset:5120
	ds_read_b128 v[216:219], v156 offset:6144
	ds_read_b128 v[220:223], v156 offset:7168
	global_load_lds_dwordx4 v[148:149], off
	v_lshl_add_u64 v[148:149], s[34:35], 0, v[142:143]
	s_add_i32 m0, s31, 0xe000
	s_nop 0
	global_load_lds_dwordx4 v[148:149], off
	s_waitcnt vmcnt(8)
	s_waitcnt lgkmcnt(0)
	s_barrier
	s_setprio 1
	s_waitcnt lgkmcnt(0)
	v_mfma_f32_16x16x32_bf16 v[126:129], v[158:161], v[192:195], v[126:129]
	v_mfma_f32_16x16x32_bf16 v[126:129], v[162:165], v[196:199], v[126:129]
	v_mfma_f32_16x16x32_bf16 v[122:125], v[166:169], v[192:195], v[122:125]
	v_mfma_f32_16x16x32_bf16 v[122:125], v[170:173], v[196:199], v[122:125]
	v_mfma_f32_16x16x32_bf16 v[118:121], v[158:161], v[200:203], v[118:121]
	v_mfma_f32_16x16x32_bf16 v[118:121], v[162:165], v[204:207], v[118:121]
	v_mfma_f32_16x16x32_bf16 v[110:113], v[166:169], v[200:203], v[110:113]
	v_mfma_f32_16x16x32_bf16 v[110:113], v[170:173], v[204:207], v[110:113]
	v_mfma_f32_16x16x32_bf16 v[102:105], v[158:161], v[208:211], v[102:105]
	v_mfma_f32_16x16x32_bf16 v[102:105], v[162:165], v[212:215], v[102:105]
	v_mfma_f32_16x16x32_bf16 v[94:97], v[166:169], v[208:211], v[94:97]
	v_mfma_f32_16x16x32_bf16 v[94:97], v[170:173], v[212:215], v[94:97]
	v_mfma_f32_16x16x32_bf16 v[86:89], v[158:161], v[216:219], v[86:89]
	v_mfma_f32_16x16x32_bf16 v[86:89], v[162:165], v[220:223], v[86:89]
	v_mfma_f32_16x16x32_bf16 v[78:81], v[166:169], v[216:219], v[78:81]
	v_mfma_f32_16x16x32_bf16 v[78:81], v[170:173], v[220:223], v[78:81]
	s_setprio 0
	s_setprio 1
	v_mfma_f32_16x16x32_bf16 v[114:117], v[174:177], v[192:195], v[114:117]
	v_mfma_f32_16x16x32_bf16 v[114:117], v[178:181], v[196:199], v[114:117]
	v_mfma_f32_16x16x32_bf16 v[106:109], v[184:187], v[192:195], v[106:109]
	v_mfma_f32_16x16x32_bf16 v[106:109], v[188:191], v[196:199], v[106:109]
	v_mfma_f32_16x16x32_bf16 v[98:101], v[174:177], v[200:203], v[98:101]
	v_mfma_f32_16x16x32_bf16 v[98:101], v[178:181], v[204:207], v[98:101]
	v_mfma_f32_16x16x32_bf16 v[90:93], v[184:187], v[200:203], v[90:93]
	v_mfma_f32_16x16x32_bf16 v[90:93], v[188:191], v[204:207], v[90:93]
	v_mfma_f32_16x16x32_bf16 v[82:85], v[174:177], v[208:211], v[82:85]
	v_mfma_f32_16x16x32_bf16 v[82:85], v[178:181], v[212:215], v[82:85]
	v_mfma_f32_16x16x32_bf16 v[74:77], v[184:187], v[208:211], v[74:77]
	v_mfma_f32_16x16x32_bf16 v[74:77], v[188:191], v[212:215], v[74:77]
	v_mfma_f32_16x16x32_bf16 v[70:73], v[174:177], v[216:219], v[70:73]
	v_mfma_f32_16x16x32_bf16 v[70:73], v[178:181], v[220:223], v[70:73]
	v_mfma_f32_16x16x32_bf16 v[66:69], v[184:187], v[216:219], v[66:69]
	v_mfma_f32_16x16x32_bf16 v[66:69], v[188:191], v[220:223], v[66:69]
	s_setprio 0
	s_barrier
	s_add_i32 s63, s50, s40
	v_lshl_add_u64 v[148:149], s[36:37], 0, v[134:135]
	s_mov_b32 m0, s63
	ds_read_b128 v[192:195], v156 offset:16384
	ds_read_b128 v[196:199], v156 offset:17408
	ds_read_b128 v[200:203], v156 offset:18432
	ds_read_b128 v[204:207], v156 offset:19456
	ds_read_b128 v[208:211], v156 offset:20480
	ds_read_b128 v[212:215], v156 offset:21504
	ds_read_b128 v[216:219], v156 offset:22528
	ds_read_b128 v[220:223], v156 offset:23552
	global_load_lds_dwordx4 v[148:149], off
	s_add_i32 m0, s63, 0x2000
	s_add_u32 s64, s36, 0x100000
	v_lshl_add_u64 v[224:225], s[36:37], 0, v[138:139]
	s_addc_u32 s65, s37, 0
	s_add_i32 s63, s51, s40
	global_load_lds_dwordx4 v[224:225], off
	v_lshl_add_u64 v[226:227], s[64:65], 0, v[134:135]
	s_mov_b32 m0, s63
	v_lshl_add_u64 v[228:229], s[38:39], 0, v[136:137]
	global_load_lds_dwordx4 v[226:227], off
	v_lshl_add_u64 v[226:227], s[64:65], 0, v[138:139]
	s_add_i32 m0, s63, 0x2000
	s_nop 0
	global_load_lds_dwordx4 v[226:227], off
	v_lshl_add_u64 v[226:227], s[38:39], 0, v[132:133]
	s_mov_b32 m0, s31
	s_nop 0
	global_load_lds_dwordx4 v[226:227], off
	s_mov_b32 m0, s43
	s_nop 0
	global_load_lds_dwordx4 v[228:229], off
	s_waitcnt vmcnt(8)
	s_waitcnt lgkmcnt(0)
	s_barrier
; #define PG8_STAGE(bufoff, gbase, voff) do { _Pragma("unroll") for (int _i = 0; _i < 2; ++_i) \
;         __builtin_amdgcn_global_load_lds((const unsigned*)((const char*)(gbase) + (voff)[_i]), (LAS unsigned*)(lds + (bufoff) + ldsw + _i * 8192), 16, 0, 0); } while (0)
; #define PG8_LDA(dst, b, h) do { _Pragma("unroll") for (int m = 0; m < 4; ++m) _Pragma("unroll") for (int k = 0; k < 2; ++k) dst[m][k] = *(const LAS bf16x8*)(lds + PG8_SA(b, h) + aoff + m * 2048 + k * 1024); } while (0)
; #define PG8_LDB(dst, b, h) do { _Pragma("unroll") for (int n = 0; n < 2; ++n) _Pragma("unroll") for (int k = 0; k < 2; ++k) dst[n][k] = *(const LAS bf16x8*)(lds + PG8_SB(b, h) + boff + n * 2048 + k * 1024); } while (0)
; #define PG8_WAIT_V(n) asm volatile("s_waitcnt vmcnt(" #n ")" ::: "memory")
; #define PG8_WAIT_L(n) asm volatile("s_waitcnt lgkmcnt(" #n ")" ::: "memory")
; #define PG8_BAR __builtin_amdgcn_s_barrier()
; #define PG8_SCHED __builtin_amdgcn_sched_barrier(0)
; template <class Epi, class Sched, class Ptrs, bool ALIGN_EPI, bool I8 = false>
; __device__ __forceinline__ void gemm_phase(LAS unsigned char* lds, const Ptrs& P, const Sched& S, const Epi& E) {
;     ...
;             PG8_LDA(At, 0, 1); PG8_STAGE(PG8_SB(0, 0), b2, voffB); PG8_STAGE(PG8_SB(0, 1), b2 + hstepB, voffB); PG8_STAGE(PG8_SA(0, 0), a2, voffA);
;             PG8_WAIT_V(8); PG8_WAIT_L(0); PG8_BAR; PG8_MMA(1, 0, At, B0); PG8_MMA(1, 1, At, B1); PG8_BAR; PG8_SCHED;
;             PG8_LDB(B0, 1, 0); PG8_LDB(B1, 1, 1); PG8_SCHED; PG8_LDA(At, 1, 0); PG8_STAGE(PG8_SA(0, 1), a2 + hstepA, voffA);
;             PG8_WAIT_V(8); PG8_WAIT_L(0); PG8_BAR; PG8_MMA(0, 0, At, B0); PG8_MMA(0, 1, At, B1); PG8_BAR; PG8_SCHED;
	s_setprio 1
	s_waitcnt lgkmcnt(0)
	v_mfma_f32_16x16x32_bf16 v[62:65], v[158:161], v[192:195], v[62:65]
	v_mfma_f32_16x16x32_bf16 v[62:65], v[162:165], v[196:199], v[62:65]
	v_mfma_f32_16x16x32_bf16 v[58:61], v[166:169], v[192:195], v[58:61]
	v_mfma_f32_16x16x32_bf16 v[58:61], v[170:173], v[196:199], v[58:61]
	v_mfma_f32_16x16x32_bf16 v[54:57], v[158:161], v[200:203], v[54:57]
	v_mfma_f32_16x16x32_bf16 v[54:57], v[162:165], v[204:207], v[54:57]
	v_mfma_f32_16x16x32_bf16 v[46:49], v[166:169], v[200:203], v[46:49]
	v_mfma_f32_16x16x32_bf16 v[46:49], v[170:173], v[204:207], v[46:49]
	v_mfma_f32_16x16x32_bf16 v[38:41], v[158:161], v[208:211], v[38:41]
	v_mfma_f32_16x16x32_bf16 v[38:41], v[162:165], v[212:215], v[38:41]
	v_mfma_f32_16x16x32_bf16 v[30:33], v[166:169], v[208:211], v[30:33]
	v_mfma_f32_16x16x32_bf16 v[30:33], v[170:173], v[212:215], v[30:33]
	v_mfma_f32_16x16x32_bf16 v[22:25], v[158:161], v[216:219], v[22:25]
	v_mfma_f32_16x16x32_bf16 v[22:25], v[162:165], v[220:223], v[22:25]
	v_mfma_f32_16x16x32_bf16 v[14:17], v[166:169], v[216:219], v[14:17]
	v_mfma_f32_16x16x32_bf16 v[14:17], v[170:173], v[220:223], v[14:17]
	s_setprio 0
	s_setprio 1
	v_mfma_f32_16x16x32_bf16 v[50:53], v[174:177], v[192:195], v[50:53]
	v_mfma_f32_16x16x32_bf16 v[50:53], v[178:181], v[196:199], v[50:53]
	v_mfma_f32_16x16x32_bf16 v[42:45], v[184:187], v[192:195], v[42:45]
	v_mfma_f32_16x16x32_bf16 v[42:45], v[188:191], v[196:199], v[42:45]
	v_mfma_f32_16x16x32_bf16 v[34:37], v[174:177], v[200:203], v[34:37]
	v_mfma_f32_16x16x32_bf16 v[34:37], v[178:181], v[204:207], v[34:37]
	v_mfma_f32_16x16x32_bf16 v[26:29], v[184:187], v[200:203], v[26:29]
	v_mfma_f32_16x16x32_bf16 v[26:29], v[188:191], v[204:207], v[26:29]
	v_mfma_f32_16x16x32_bf16 v[18:21], v[174:177], v[208:211], v[18:21]
	v_mfma_f32_16x16x32_bf16 v[18:21], v[178:181], v[212:215], v[18:21]
	v_mfma_f32_16x16x32_bf16 v[10:13], v[184:187], v[208:211], v[10:13]
	v_mfma_f32_16x16x32_bf16 v[10:13], v[188:191], v[212:215], v[10:13]
	v_mfma_f32_16x16x32_bf16 v[6:9], v[174:177], v[216:219], v[6:9]
	v_mfma_f32_16x16x32_bf16 v[6:9], v[178:181], v[220:223], v[6:9]
	v_mfma_f32_16x16x32_bf16 v[2:5], v[184:187], v[216:219], v[2:5]
	v_mfma_f32_16x16x32_bf16 v[2:5], v[188:191], v[220:223], v[2:5]
	s_setprio 0
	s_barrier
	s_add_i32 s63, 0, 0x18000
	v_add_u32_e32 v157, s63, v152
	s_add_i32 s64, 0, 0x1c000
	ds_read_b128 v[158:161], v157
	ds_read_b128 v[162:165], v157 offset:1024
	ds_read_b128 v[166:169], v157 offset:2048
	ds_read_b128 v[170:173], v157 offset:3072
	v_add_u32_e32 v157, s64, v152
	ds_read_b128 v[174:177], v157
	ds_read_b128 v[178:181], v157 offset:1024
	ds_read_b128 v[184:187], v157 offset:2048
	ds_read_b128 v[188:191], v157 offset:3072
	s_add_u32 s38, s38, 0x100000
	s_addc_u32 s39, s39, 0
	s_mov_b32 m0, s44
	v_lshl_add_u64 v[230:231], s[38:39], 0, v[132:133]
	ds_read_b128 v[192:195], v156 offset:32768
	ds_read_b128 v[196:199], v156 offset:33792
	ds_read_b128 v[200:203], v156 offset:34816
	ds_read_b128 v[204:207], v156 offset:35840
	ds_read_b128 v[208:211], v156 offset:36864
	ds_read_b128 v[212:215], v156 offset:37888
	ds_read_b128 v[216:219], v156 offset:38912
	ds_read_b128 v[220:223], v156 offset:39936
	global_load_lds_dwordx4 v[230:231], off
	v_lshl_add_u64 v[230:231], s[38:39], 0, v[136:137]
	s_mov_b32 m0, s45
	s_nop 0
	global_load_lds_dwordx4 v[230:231], off
	s_waitcnt vmcnt(8)
	s_waitcnt lgkmcnt(0)
	s_barrier
	s_setprio 1
	s_waitcnt lgkmcnt(0)
	v_mfma_f32_16x16x32_bf16 v[126:129], v[158:161], v[192:195], v[126:129]
	v_mfma_f32_16x16x32_bf16 v[126:129], v[162:165], v[196:199], v[126:129]
	v_mfma_f32_16x16x32_bf16 v[122:125], v[166:169], v[192:195], v[122:125]
	v_mfma_f32_16x16x32_bf16 v[122:125], v[170:173], v[196:199], v[122:125]
	v_mfma_f32_16x16x32_bf16 v[118:121], v[158:161], v[200:203], v[118:121]
	v_mfma_f32_16x16x32_bf16 v[118:121], v[162:165], v[204:207], v[118:121]
	v_mfma_f32_16x16x32_bf16 v[110:113], v[166:169], v[200:203], v[110:113]
	v_mfma_f32_16x16x32_bf16 v[110:113], v[170:173], v[204:207], v[110:113]
	v_mfma_f32_16x16x32_bf16 v[102:105], v[158:161], v[208:211], v[102:105]
	v_mfma_f32_16x16x32_bf16 v[102:105], v[162:165], v[212:215], v[102:105]
	v_mfma_f32_16x16x32_bf16 v[94:97], v[166:169], v[208:211], v[94:97]
	v_mfma_f32_16x16x32_bf16 v[94:97], v[170:173], v[212:215], v[94:97]
	v_mfma_f32_16x16x32_bf16 v[86:89], v[158:161], v[216:219], v[86:89]
	v_mfma_f32_16x16x32_bf16 v[86:89], v[162:165], v[220:223], v[86:89]
	v_mfma_f32_16x16x32_bf16 v[78:81], v[166:169], v[216:219], v[78:81]
	v_mfma_f32_16x16x32_bf16 v[78:81], v[170:173], v[220:223], v[78:81]
	s_setprio 0
	s_setprio 1
	v_mfma_f32_16x16x32_bf16 v[114:117], v[174:177], v[192:195], v[114:117]
	v_mfma_f32_16x16x32_bf16 v[114:117], v[178:181], v[196:199], v[114:117]
	v_mfma_f32_16x16x32_bf16 v[106:109], v[184:187], v[192:195], v[106:109]
	v_mfma_f32_16x16x32_bf16 v[106:109], v[188:191], v[196:199], v[106:109]
	v_mfma_f32_16x16x32_bf16 v[98:101], v[174:177], v[200:203], v[98:101]
	v_mfma_f32_16x16x32_bf16 v[98:101], v[178:181], v[204:207], v[98:101]
	v_mfma_f32_16x16x32_bf16 v[90:93], v[184:187], v[200:203], v[90:93]
	v_mfma_f32_16x16x32_bf16 v[90:93], v[188:191], v[204:207], v[90:93]
	v_mfma_f32_16x16x32_bf16 v[82:85], v[174:177], v[208:211], v[82:85]
	v_mfma_f32_16x16x32_bf16 v[82:85], v[178:181], v[212:215], v[82:85]
	v_mfma_f32_16x16x32_bf16 v[74:77], v[184:187], v[208:211], v[74:77]
	v_mfma_f32_16x16x32_bf16 v[74:77], v[188:191], v[212:215], v[74:77]
	v_mfma_f32_16x16x32_bf16 v[70:73], v[174:177], v[216:219], v[70:73]
	v_mfma_f32_16x16x32_bf16 v[70:73], v[178:181], v[220:223], v[70:73]
	v_mfma_f32_16x16x32_bf16 v[66:69], v[184:187], v[216:219], v[66:69]
	v_mfma_f32_16x16x32_bf16 v[66:69], v[188:191], v[220:223], v[66:69]
	s_setprio 0
	s_barrier
; #define PG8_STAGE(bufoff, gbase, voff) do { _Pragma("unroll") for (int _i = 0; _i < 2; ++_i) \
;         __builtin_amdgcn_global_load_lds((const unsigned*)((const char*)(gbase) + (voff)[_i]), (LAS unsigned*)(lds + (bufoff) + ldsw + _i * 8192), 16, 0, 0); } while (0)
; #define PG8_LDA(dst, b, h) do { _Pragma("unroll") for (int m = 0; m < 4; ++m) _Pragma("unroll") for (int k = 0; k < 2; ++k) dst[m][k] = *(const LAS bf16x8*)(lds + PG8_SA(b, h) + aoff + m * 2048 + k * 1024); } while (0)
; #define PG8_WAIT_V(n) asm volatile("s_waitcnt vmcnt(" #n ")" ::: "memory")
; #define PG8_WAIT_L(n) asm volatile("s_waitcnt lgkmcnt(" #n ")" ::: "memory")
; #define PG8_BAR __builtin_amdgcn_s_barrier()
; #define PG8_SCHED __builtin_amdgcn_sched_barrier(0)
; template <class Epi, class Sched, class Ptrs, bool ALIGN_EPI, bool I8 = false>
; __device__ __forceinline__ void gemm_phase(LAS unsigned char* lds, const Ptrs& P, const Sched& S, const Epi& E) {
;     ...
;             PG8_LDA(At, 1, 1); PG8_STAGE(PG8_SB(1, 0), b3, voffB); PG8_STAGE(PG8_SB(1, 1), b3 + hstepB, voffB); PG8_STAGE(PG8_SA(1, 0), a3, voffA);
;             PG8_WAIT_V(8); PG8_WAIT_L(0); PG8_BAR; PG8_MMA(1, 0, At, B0); PG8_MMA(1, 1, At, B1); PG8_BAR; PG8_SCHED;
;         }
	s_add_i32 s38, s63, s40
	v_lshl_add_u64 v[148:149], v[148:149], 0, s[10:11]
	s_mov_b32 m0, s38
	ds_read_b128 v[192:195], v156 offset:49152
	ds_read_b128 v[196:199], v156 offset:50176
	ds_read_b128 v[200:203], v156 offset:51200
	ds_read_b128 v[204:207], v156 offset:52224
	ds_read_b128 v[208:211], v156 offset:53248
	ds_read_b128 v[212:215], v156 offset:54272
	ds_read_b128 v[216:219], v156 offset:55296
	ds_read_b128 v[220:223], v156 offset:56320
	global_load_lds_dwordx4 v[148:149], off
	s_add_i32 m0, s38, 0x2000
	s_add_u32 s36, s36, 0x100080
	v_lshl_add_u64 v[148:149], v[224:225], 0, s[10:11]
	s_addc_u32 s37, s37, 0
	s_add_i32 s38, s64, s40
	global_load_lds_dwordx4 v[148:149], off
	v_lshl_add_u64 v[148:149], s[36:37], 0, v[134:135]
	s_mov_b32 m0, s38
	s_nop 0
	global_load_lds_dwordx4 v[148:149], off
	v_lshl_add_u64 v[148:149], s[36:37], 0, v[138:139]
	s_add_i32 m0, s38, 0x2000
	s_nop 0
	global_load_lds_dwordx4 v[148:149], off
	v_lshl_add_u64 v[148:149], v[226:227], 0, s[10:11]
	s_mov_b32 m0, s47
	s_nop 0
	global_load_lds_dwordx4 v[148:149], off
	v_lshl_add_u64 v[148:149], v[228:229], 0, s[10:11]
	s_mov_b32 m0, s48
	s_nop 0
	global_load_lds_dwordx4 v[148:149], off
	s_waitcnt vmcnt(8)
	s_waitcnt lgkmcnt(0)
	s_barrier
	s_setprio 1
	s_waitcnt lgkmcnt(0)
	v_mfma_f32_16x16x32_bf16 v[62:65], v[158:161], v[192:195], v[62:65]
	v_mfma_f32_16x16x32_bf16 v[62:65], v[162:165], v[196:199], v[62:65]
	v_mfma_f32_16x16x32_bf16 v[58:61], v[166:169], v[192:195], v[58:61]
	v_mfma_f32_16x16x32_bf16 v[58:61], v[170:173], v[196:199], v[58:61]
	v_mfma_f32_16x16x32_bf16 v[54:57], v[158:161], v[200:203], v[54:57]
	v_mfma_f32_16x16x32_bf16 v[54:57], v[162:165], v[204:207], v[54:57]
	v_mfma_f32_16x16x32_bf16 v[46:49], v[166:169], v[200:203], v[46:49]
	v_mfma_f32_16x16x32_bf16 v[46:49], v[170:173], v[204:207], v[46:49]
	v_mfma_f32_16x16x32_bf16 v[38:41], v[158:161], v[208:211], v[38:41]
	v_mfma_f32_16x16x32_bf16 v[38:41], v[162:165], v[212:215], v[38:41]
	v_mfma_f32_16x16x32_bf16 v[30:33], v[166:169], v[208:211], v[30:33]
	v_mfma_f32_16x16x32_bf16 v[30:33], v[170:173], v[212:215], v[30:33]
	v_mfma_f32_16x16x32_bf16 v[22:25], v[158:161], v[216:219], v[22:25]
	v_mfma_f32_16x16x32_bf16 v[22:25], v[162:165], v[220:223], v[22:25]
	v_mfma_f32_16x16x32_bf16 v[14:17], v[166:169], v[216:219], v[14:17]
	v_mfma_f32_16x16x32_bf16 v[14:17], v[170:173], v[220:223], v[14:17]
	s_setprio 0
	s_setprio 1
	v_mfma_f32_16x16x32_bf16 v[50:53], v[174:177], v[192:195], v[50:53]
	v_mfma_f32_16x16x32_bf16 v[50:53], v[178:181], v[196:199], v[50:53]
	v_mfma_f32_16x16x32_bf16 v[42:45], v[184:187], v[192:195], v[42:45]
	v_mfma_f32_16x16x32_bf16 v[42:45], v[188:191], v[196:199], v[42:45]
	v_mfma_f32_16x16x32_bf16 v[34:37], v[174:177], v[200:203], v[34:37]
	v_mfma_f32_16x16x32_bf16 v[34:37], v[178:181], v[204:207], v[34:37]
	v_mfma_f32_16x16x32_bf16 v[26:29], v[184:187], v[200:203], v[26:29]
	v_mfma_f32_16x16x32_bf16 v[26:29], v[188:191], v[204:207], v[26:29]
	v_mfma_f32_16x16x32_bf16 v[18:21], v[174:177], v[208:211], v[18:21]
	v_mfma_f32_16x16x32_bf16 v[18:21], v[178:181], v[212:215], v[18:21]
	v_mfma_f32_16x16x32_bf16 v[10:13], v[184:187], v[208:211], v[10:13]
	v_mfma_f32_16x16x32_bf16 v[10:13], v[188:191], v[212:215], v[10:13]
	v_mfma_f32_16x16x32_bf16 v[6:9], v[174:177], v[216:219], v[6:9]
	v_mfma_f32_16x16x32_bf16 v[6:9], v[178:181], v[220:223], v[6:9]
	v_mfma_f32_16x16x32_bf16 v[2:5], v[184:187], v[216:219], v[2:5]
	v_mfma_f32_16x16x32_bf16 v[2:5], v[188:191], v[220:223], v[2:5]
	s_setprio 0
	s_barrier
	s_add_i32 s62, s62, 2
	s_add_u32 s34, s34, 0x100
	s_addc_u32 s35, s35, 0
	s_add_u32 s60, s60, 0x100
	s_addc_u32 s61, s61, 0
	s_cmp_gt_u32 s62, 61
	s_cbranch_scc0 .LBB0_615
	s_and_b64 vcc, exec, s[12:13]
	s_cbranch_vccz .LBB0_618
	s_barrier

; #define PG8_STAGE(bufoff, gbase, voff) do { _Pragma("unroll") for (int _i = 0; _i < 2; ++_i) \
;         __builtin_amdgcn_global_load_lds((const unsigned*)((const char*)(gbase) + (voff)[_i]), (LAS unsigned*)(lds + (bufoff) + ldsw + _i * 8192), 16, 0, 0); } while (0)
; #define PG8_LDA(dst, b, h) do { _Pragma("unroll") for (int m = 0; m < 4; ++m) _Pragma("unroll") for (int k = 0; k < 2; ++k) dst[m][k] = *(const LAS bf16x8*)(lds + PG8_SA(b, h) + aoff + m * 2048 + k * 1024); } while (0)
; #define PG8_LDB(dst, b, h) do { _Pragma("unroll") for (int n = 0; n < 2; ++n) _Pragma("unroll") for (int k = 0; k < 2; ++k) dst[n][k] = *(const LAS bf16x8*)(lds + PG8_SB(b, h) + boff + n * 2048 + k * 1024); } while (0)
; #define PG8_WAIT_V(n) asm volatile("s_waitcnt vmcnt(" #n ")" ::: "memory")
; #define PG8_WAIT_L(n) asm volatile("s_waitcnt lgkmcnt(" #n ")" ::: "memory")
; #define PG8_BAR __builtin_amdgcn_s_barrier()
; #define PG8_SCHED __builtin_amdgcn_sched_barrier(0)
; template <class Epi, class Sched, class Ptrs, bool ALIGN_EPI, bool I8 = false>
; __device__ __forceinline__ void gemm_phase(LAS unsigned char* lds, const Ptrs& P, const Sched& S, const Epi& E) {
;     ...
;             PG8_LDB(B0, 0, 0); PG8_LDB(B1, 0, 1); PG8_SCHED; PG8_LDA(At, 0, 0); PG8_STAGE(PG8_SA(1, 1), a1 + hstepA, voffA);
;             PG8_WAIT_V(8); PG8_WAIT_L(0); PG8_BAR; PG8_MMA(0, 0, At, B0); PG8_MMA(0, 1, At, B1); PG8_BAR; PG8_SCHED;
.LBB0_710:
	ds_read_b128 v[178:181], v173
	ds_read_b128 v[184:187], v173 offset:1024
	ds_read_b128 v[188:191], v173 offset:2048
	ds_read_b128 v[192:195], v173 offset:3072
	ds_read_b128 v[196:199], v174
	ds_read_b128 v[200:203], v174 offset:1024
	ds_read_b128 v[204:207], v174 offset:2048
	ds_read_b128 v[208:211], v174 offset:3072
	s_add_u32 s22, s20, 0xffe00080
	s_addc_u32 s23, s21, -1
	s_cmp_eq_u32 s48, 12
	s_cselect_b32 s25, s17, s23
	s_cselect_b32 s24, s16, s22
	s_cselect_b32 s23, s19, s47
	s_cselect_b32 s22, s18, s46
	s_mov_b32 m0, s34
	v_lshl_add_u64 v[244:245], s[20:21], 0, v[156:157]
	ds_read_b128 v[212:215], v175
	ds_read_b128 v[216:219], v175 offset:1024
	ds_read_b128 v[220:223], v175 offset:2048
	ds_read_b128 v[224:227], v175 offset:3072
	ds_read_b128 v[228:231], v175 offset:4096
	ds_read_b128 v[232:235], v175 offset:5120
	ds_read_b128 v[236:239], v175 offset:6144
	ds_read_b128 v[240:243], v175 offset:7168
	global_load_lds_dwordx4 v[244:245], off
	v_lshl_add_u64 v[244:245], s[20:21], 0, v[158:159]
	s_mov_b32 m0, s35
	s_nop 0
	global_load_lds_dwordx4 v[244:245], off
	s_waitcnt vmcnt(8)
	s_waitcnt lgkmcnt(0)
	s_barrier
	s_setprio 1
	s_waitcnt lgkmcnt(0)
	v_mfma_f32_16x16x32_bf16 v[126:129], v[178:181], v[212:215], v[126:129]
	v_mfma_f32_16x16x32_bf16 v[126:129], v[184:187], v[216:219], v[126:129]
	v_mfma_f32_16x16x32_bf16 v[122:125], v[188:191], v[212:215], v[122:125]
	v_mfma_f32_16x16x32_bf16 v[122:125], v[192:195], v[216:219], v[122:125]
	v_mfma_f32_16x16x32_bf16 v[118:121], v[178:181], v[220:223], v[118:121]
	v_mfma_f32_16x16x32_bf16 v[118:121], v[184:187], v[224:227], v[118:121]
	v_mfma_f32_16x16x32_bf16 v[110:113], v[188:191], v[220:223], v[110:113]
	v_mfma_f32_16x16x32_bf16 v[110:113], v[192:195], v[224:227], v[110:113]
	v_mfma_f32_16x16x32_bf16 v[102:105], v[178:181], v[228:231], v[102:105]
	v_mfma_f32_16x16x32_bf16 v[102:105], v[184:187], v[232:235], v[102:105]
	v_mfma_f32_16x16x32_bf16 v[94:97], v[188:191], v[228:231], v[94:97]
	v_mfma_f32_16x16x32_bf16 v[94:97], v[192:195], v[232:235], v[94:97]
	v_mfma_f32_16x16x32_bf16 v[86:89], v[178:181], v[236:239], v[86:89]
	v_mfma_f32_16x16x32_bf16 v[86:89], v[184:187], v[240:243], v[86:89]
	v_mfma_f32_16x16x32_bf16 v[78:81], v[188:191], v[236:239], v[78:81]
	v_mfma_f32_16x16x32_bf16 v[78:81], v[192:195], v[240:243], v[78:81]
	s_setprio 0
	s_setprio 1
	v_mfma_f32_16x16x32_bf16 v[114:117], v[196:199], v[212:215], v[114:117]
	v_mfma_f32_16x16x32_bf16 v[114:117], v[200:203], v[216:219], v[114:117]
	v_mfma_f32_16x16x32_bf16 v[106:109], v[204:207], v[212:215], v[106:109]
	v_mfma_f32_16x16x32_bf16 v[106:109], v[208:211], v[216:219], v[106:109]
	v_mfma_f32_16x16x32_bf16 v[98:101], v[196:199], v[220:223], v[98:101]
	v_mfma_f32_16x16x32_bf16 v[98:101], v[200:203], v[224:227], v[98:101]
	v_mfma_f32_16x16x32_bf16 v[90:93], v[204:207], v[220:223], v[90:93]
	v_mfma_f32_16x16x32_bf16 v[90:93], v[208:211], v[224:227], v[90:93]
	v_mfma_f32_16x16x32_bf16 v[82:85], v[196:199], v[228:231], v[82:85]
	v_mfma_f32_16x16x32_bf16 v[82:85], v[200:203], v[232:235], v[82:85]
	v_mfma_f32_16x16x32_bf16 v[74:77], v[204:207], v[228:231], v[74:77]
	v_mfma_f32_16x16x32_bf16 v[74:77], v[208:211], v[232:235], v[74:77]
	v_mfma_f32_16x16x32_bf16 v[70:73], v[196:199], v[236:239], v[70:73]
	v_mfma_f32_16x16x32_bf16 v[70:73], v[200:203], v[240:243], v[70:73]
	v_mfma_f32_16x16x32_bf16 v[66:69], v[204:207], v[236:239], v[66:69]
	v_mfma_f32_16x16x32_bf16 v[66:69], v[208:211], v[240:243], v[66:69]
	s_setprio 0
	s_barrier
	s_mov_b32 m0, s36
	v_lshl_add_u64 v[244:245], s[22:23], 0, v[134:135]
	s_add_u32 s50, s22, 0x100000
	ds_read_b128 v[212:215], v175 offset:16384
	ds_read_b128 v[216:219], v175 offset:17408
	ds_read_b128 v[220:223], v175 offset:18432
	ds_read_b128 v[224:227], v175 offset:19456
	ds_read_b128 v[228:231], v175 offset:20480
	ds_read_b128 v[232:235], v175 offset:21504
	ds_read_b128 v[236:239], v175 offset:22528
	ds_read_b128 v[240:243], v175 offset:23552
	global_load_lds_dwordx4 v[244:245], off
	v_lshl_add_u64 v[246:247], s[22:23], 0, v[130:131]
	s_mov_b32 m0, s37
	s_addc_u32 s51, s23, 0
	global_load_lds_dwordx4 v[246:247], off
	v_lshl_add_u64 v[248:249], s[50:51], 0, v[134:135]
	s_mov_b32 m0, s38
	v_lshl_add_u64 v[250:251], s[24:25], 0, v[132:133]
	global_load_lds_dwordx4 v[248:249], off
	v_lshl_add_u64 v[248:249], s[50:51], 0, v[130:131]
	s_mov_b32 m0, s39
	s_nop 0
	global_load_lds_dwordx4 v[248:249], off
	v_lshl_add_u64 v[248:249], s[24:25], 0, v[136:137]
	s_mov_b32 m0, s26
	s_nop 0
	global_load_lds_dwordx4 v[248:249], off
	s_mov_b32 m0, s27
	s_nop 0
	global_load_lds_dwordx4 v[250:251], off
	s_waitcnt vmcnt(8)
	s_waitcnt lgkmcnt(0)
	s_barrier
; #define PG8_STAGE(bufoff, gbase, voff) do { _Pragma("unroll") for (int _i = 0; _i < 2; ++_i) \
;         __builtin_amdgcn_global_load_lds((const unsigned*)((const char*)(gbase) + (voff)[_i]), (LAS unsigned*)(lds + (bufoff) + ldsw + _i * 8192), 16, 0, 0); } while (0)
; #define PG8_LDA(dst, b, h) do { _Pragma("unroll") for (int m = 0; m < 4; ++m) _Pragma("unroll") for (int k = 0; k < 2; ++k) dst[m][k] = *(const LAS bf16x8*)(lds + PG8_SA(b, h) + aoff + m * 2048 + k * 1024); } while (0)
; #define PG8_LDB(dst, b, h) do { _Pragma("unroll") for (int n = 0; n < 2; ++n) _Pragma("unroll") for (int k = 0; k < 2; ++k) dst[n][k] = *(const LAS bf16x8*)(lds + PG8_SB(b, h) + boff + n * 2048 + k * 1024); } while (0)
; #define PG8_WAIT_V(n) asm volatile("s_waitcnt vmcnt(" #n ")" ::: "memory")
; #define PG8_WAIT_L(n) asm volatile("s_waitcnt lgkmcnt(" #n ")" ::: "memory")
; #define PG8_BAR __builtin_amdgcn_s_barrier()
; #define PG8_SCHED __builtin_amdgcn_sched_barrier(0)
; template <class Epi, class Sched, class Ptrs, bool ALIGN_EPI, bool I8 = false>
; __device__ __forceinline__ void gemm_phase(LAS unsigned char* lds, const Ptrs& P, const Sched& S, const Epi& E) {
;     ...
;             PG8_LDA(At, 0, 1); PG8_STAGE(PG8_SB(0, 0), b2, voffB); PG8_STAGE(PG8_SB(0, 1), b2 + hstepB, voffB); PG8_STAGE(PG8_SA(0, 0), a2, voffA);
;             PG8_WAIT_V(8); PG8_WAIT_L(0); PG8_BAR; PG8_MMA(1, 0, At, B0); PG8_MMA(1, 1, At, B1); PG8_BAR; PG8_SCHED;
;             PG8_LDB(B0, 1, 0); PG8_LDB(B1, 1, 1); PG8_SCHED; PG8_LDA(At, 1, 0); PG8_STAGE(PG8_SA(0, 1), a2 + hstepA, voffA);
;             PG8_WAIT_V(8); PG8_WAIT_L(0); PG8_BAR; PG8_MMA(0, 0, At, B0); PG8_MMA(0, 1, At, B1); PG8_BAR; PG8_SCHED;
	s_setprio 1
	s_waitcnt lgkmcnt(0)
	v_mfma_f32_16x16x32_bf16 v[62:65], v[178:181], v[212:215], v[62:65]
	v_mfma_f32_16x16x32_bf16 v[62:65], v[184:187], v[216:219], v[62:65]
	v_mfma_f32_16x16x32_bf16 v[58:61], v[188:191], v[212:215], v[58:61]
	v_mfma_f32_16x16x32_bf16 v[58:61], v[192:195], v[216:219], v[58:61]
	v_mfma_f32_16x16x32_bf16 v[54:57], v[178:181], v[220:223], v[54:57]
	v_mfma_f32_16x16x32_bf16 v[54:57], v[184:187], v[224:227], v[54:57]
	v_mfma_f32_16x16x32_bf16 v[46:49], v[188:191], v[220:223], v[46:49]
	v_mfma_f32_16x16x32_bf16 v[46:49], v[192:195], v[224:227], v[46:49]
	v_mfma_f32_16x16x32_bf16 v[38:41], v[178:181], v[228:231], v[38:41]
	v_mfma_f32_16x16x32_bf16 v[38:41], v[184:187], v[232:235], v[38:41]
	v_mfma_f32_16x16x32_bf16 v[30:33], v[188:191], v[228:231], v[30:33]
	v_mfma_f32_16x16x32_bf16 v[30:33], v[192:195], v[232:235], v[30:33]
	v_mfma_f32_16x16x32_bf16 v[22:25], v[178:181], v[236:239], v[22:25]
	v_mfma_f32_16x16x32_bf16 v[22:25], v[184:187], v[240:243], v[22:25]
	v_mfma_f32_16x16x32_bf16 v[14:17], v[188:191], v[236:239], v[14:17]
	v_mfma_f32_16x16x32_bf16 v[14:17], v[192:195], v[240:243], v[14:17]
	s_setprio 0
	s_setprio 1
	v_mfma_f32_16x16x32_bf16 v[50:53], v[196:199], v[212:215], v[50:53]
	v_mfma_f32_16x16x32_bf16 v[50:53], v[200:203], v[216:219], v[50:53]
	v_mfma_f32_16x16x32_bf16 v[42:45], v[204:207], v[212:215], v[42:45]
	v_mfma_f32_16x16x32_bf16 v[42:45], v[208:211], v[216:219], v[42:45]
	v_mfma_f32_16x16x32_bf16 v[34:37], v[196:199], v[220:223], v[34:37]
	v_mfma_f32_16x16x32_bf16 v[34:37], v[200:203], v[224:227], v[34:37]
	v_mfma_f32_16x16x32_bf16 v[26:29], v[204:207], v[220:223], v[26:29]
	v_mfma_f32_16x16x32_bf16 v[26:29], v[208:211], v[224:227], v[26:29]
	v_mfma_f32_16x16x32_bf16 v[18:21], v[196:199], v[228:231], v[18:21]
	v_mfma_f32_16x16x32_bf16 v[18:21], v[200:203], v[232:235], v[18:21]
	v_mfma_f32_16x16x32_bf16 v[10:13], v[204:207], v[228:231], v[10:13]
	v_mfma_f32_16x16x32_bf16 v[10:13], v[208:211], v[232:235], v[10:13]
	v_mfma_f32_16x16x32_bf16 v[6:9], v[196:199], v[236:239], v[6:9]
	v_mfma_f32_16x16x32_bf16 v[6:9], v[200:203], v[240:243], v[6:9]
	v_mfma_f32_16x16x32_bf16 v[2:5], v[204:207], v[236:239], v[2:5]
	v_mfma_f32_16x16x32_bf16 v[2:5], v[208:211], v[240:243], v[2:5]
	s_setprio 0
	s_barrier
	ds_read_b128 v[178:181], v176
	ds_read_b128 v[184:187], v176 offset:1024
	ds_read_b128 v[188:191], v176 offset:2048
	ds_read_b128 v[192:195], v176 offset:3072
	ds_read_b128 v[196:199], v177
	ds_read_b128 v[200:203], v177 offset:1024
	ds_read_b128 v[204:207], v177 offset:2048
	ds_read_b128 v[208:211], v177 offset:3072
	s_add_u32 s24, s24, 0x200000
	s_addc_u32 s25, s25, 0
	s_mov_b32 m0, s28
	v_lshl_add_u64 v[252:253], s[24:25], 0, v[136:137]
	ds_read_b128 v[212:215], v175 offset:32768
	ds_read_b128 v[216:219], v175 offset:33792
	ds_read_b128 v[220:223], v175 offset:34816
	ds_read_b128 v[224:227], v175 offset:35840
	ds_read_b128 v[228:231], v175 offset:36864
	ds_read_b128 v[232:235], v175 offset:37888
	ds_read_b128 v[236:239], v175 offset:38912
	ds_read_b128 v[240:243], v175 offset:39936
	global_load_lds_dwordx4 v[252:253], off
	v_lshl_add_u64 v[252:253], s[24:25], 0, v[132:133]
	s_mov_b32 m0, s29
	s_nop 0
	global_load_lds_dwordx4 v[252:253], off
	s_waitcnt vmcnt(8)
	s_waitcnt lgkmcnt(0)
	s_barrier
	s_setprio 1
	s_waitcnt lgkmcnt(0)
	v_mfma_f32_16x16x32_bf16 v[126:129], v[178:181], v[212:215], v[126:129]
	v_mfma_f32_16x16x32_bf16 v[126:129], v[184:187], v[216:219], v[126:129]
	v_mfma_f32_16x16x32_bf16 v[122:125], v[188:191], v[212:215], v[122:125]
	v_mfma_f32_16x16x32_bf16 v[122:125], v[192:195], v[216:219], v[122:125]
	v_mfma_f32_16x16x32_bf16 v[118:121], v[178:181], v[220:223], v[118:121]
	v_mfma_f32_16x16x32_bf16 v[118:121], v[184:187], v[224:227], v[118:121]
	v_mfma_f32_16x16x32_bf16 v[110:113], v[188:191], v[220:223], v[110:113]
	v_mfma_f32_16x16x32_bf16 v[110:113], v[192:195], v[224:227], v[110:113]
	v_mfma_f32_16x16x32_bf16 v[102:105], v[178:181], v[228:231], v[102:105]
	v_mfma_f32_16x16x32_bf16 v[102:105], v[184:187], v[232:235], v[102:105]
	v_mfma_f32_16x16x32_bf16 v[94:97], v[188:191], v[228:231], v[94:97]
	v_mfma_f32_16x16x32_bf16 v[94:97], v[192:195], v[232:235], v[94:97]
	v_mfma_f32_16x16x32_bf16 v[86:89], v[178:181], v[236:239], v[86:89]
	v_mfma_f32_16x16x32_bf16 v[86:89], v[184:187], v[240:243], v[86:89]
	v_mfma_f32_16x16x32_bf16 v[78:81], v[188:191], v[236:239], v[78:81]
	v_mfma_f32_16x16x32_bf16 v[78:81], v[192:195], v[240:243], v[78:81]
	s_setprio 0
	s_setprio 1
	v_mfma_f32_16x16x32_bf16 v[114:117], v[196:199], v[212:215], v[114:117]
	v_mfma_f32_16x16x32_bf16 v[114:117], v[200:203], v[216:219], v[114:117]
	v_mfma_f32_16x16x32_bf16 v[106:109], v[204:207], v[212:215], v[106:109]
	v_mfma_f32_16x16x32_bf16 v[106:109], v[208:211], v[216:219], v[106:109]
	v_mfma_f32_16x16x32_bf16 v[98:101], v[196:199], v[220:223], v[98:101]
	v_mfma_f32_16x16x32_bf16 v[98:101], v[200:203], v[224:227], v[98:101]
	v_mfma_f32_16x16x32_bf16 v[90:93], v[204:207], v[220:223], v[90:93]
	v_mfma_f32_16x16x32_bf16 v[90:93], v[208:211], v[224:227], v[90:93]
	v_mfma_f32_16x16x32_bf16 v[82:85], v[196:199], v[228:231], v[82:85]
	v_mfma_f32_16x16x32_bf16 v[82:85], v[200:203], v[232:235], v[82:85]
	v_mfma_f32_16x16x32_bf16 v[74:77], v[204:207], v[228:231], v[74:77]
	v_mfma_f32_16x16x32_bf16 v[74:77], v[208:211], v[232:235], v[74:77]
	v_mfma_f32_16x16x32_bf16 v[70:73], v[196:199], v[236:239], v[70:73]
	v_mfma_f32_16x16x32_bf16 v[70:73], v[200:203], v[240:243], v[70:73]
	v_mfma_f32_16x16x32_bf16 v[66:69], v[204:207], v[236:239], v[66:69]
	v_mfma_f32_16x16x32_bf16 v[66:69], v[208:211], v[240:243], v[66:69]
	s_setprio 0
	s_barrier
; #define PG8_STAGE(bufoff, gbase, voff) do { _Pragma("unroll") for (int _i = 0; _i < 2; ++_i) \
;         __builtin_amdgcn_global_load_lds((const unsigned*)((const char*)(gbase) + (voff)[_i]), (LAS unsigned*)(lds + (bufoff) + ldsw + _i * 8192), 16, 0, 0); } while (0)
; #define PG8_LDA(dst, b, h) do { _Pragma("unroll") for (int m = 0; m < 4; ++m) _Pragma("unroll") for (int k = 0; k < 2; ++k) dst[m][k] = *(const LAS bf16x8*)(lds + PG8_SA(b, h) + aoff + m * 2048 + k * 1024); } while (0)
; #define PG8_WAIT_V(n) asm volatile("s_waitcnt vmcnt(" #n ")" ::: "memory")
; #define PG8_WAIT_L(n) asm volatile("s_waitcnt lgkmcnt(" #n ")" ::: "memory")
; #define PG8_BAR __builtin_amdgcn_s_barrier()
; #define PG8_SCHED __builtin_amdgcn_sched_barrier(0)
; template <class Epi, class Sched, class Ptrs, bool ALIGN_EPI, bool I8 = false>
; __device__ __forceinline__ void gemm_phase(LAS unsigned char* lds, const Ptrs& P, const Sched& S, const Epi& E) {
;     ...
;             PG8_LDA(At, 1, 1); PG8_STAGE(PG8_SB(1, 0), b3, voffB); PG8_STAGE(PG8_SB(1, 1), b3 + hstepB, voffB); PG8_STAGE(PG8_SA(1, 0), a3, voffA);
;             PG8_WAIT_V(8); PG8_WAIT_L(0); PG8_BAR; PG8_MMA(1, 0, At, B0); PG8_MMA(1, 1, At, B1); PG8_BAR; PG8_SCHED;
;         }
	s_mov_b32 m0, s40
	v_lshl_add_u64 v[244:245], v[244:245], 0, s[10:11]
	s_add_u32 s22, s22, 0x100080
	ds_read_b128 v[212:215], v175 offset:49152
	ds_read_b128 v[216:219], v175 offset:50176
	ds_read_b128 v[220:223], v175 offset:51200
	ds_read_b128 v[224:227], v175 offset:52224
	ds_read_b128 v[228:231], v175 offset:53248
	ds_read_b128 v[232:235], v175 offset:54272
	ds_read_b128 v[236:239], v175 offset:55296
	ds_read_b128 v[240:243], v175 offset:56320
	global_load_lds_dwordx4 v[244:245], off
	v_lshl_add_u64 v[244:245], v[246:247], 0, s[10:11]
	s_mov_b32 m0, s41
	s_addc_u32 s23, s23, 0
	global_load_lds_dwordx4 v[244:245], off
	v_lshl_add_u64 v[244:245], s[22:23], 0, v[134:135]
	s_mov_b32 m0, s42
	s_nop 0
	global_load_lds_dwordx4 v[244:245], off
	v_lshl_add_u64 v[244:245], s[22:23], 0, v[130:131]
	s_mov_b32 m0, s43
	s_nop 0
	global_load_lds_dwordx4 v[244:245], off
	v_lshl_add_u64 v[244:245], v[248:249], 0, s[10:11]
	s_mov_b32 m0, s31
	s_nop 0
	global_load_lds_dwordx4 v[244:245], off
	v_lshl_add_u64 v[244:245], v[250:251], 0, s[10:11]
	s_mov_b32 m0, s33
	s_nop 0
	global_load_lds_dwordx4 v[244:245], off
	s_waitcnt vmcnt(8)
	s_waitcnt lgkmcnt(0)
	s_barrier
	s_setprio 1
	s_waitcnt lgkmcnt(0)
	v_mfma_f32_16x16x32_bf16 v[62:65], v[178:181], v[212:215], v[62:65]
	v_mfma_f32_16x16x32_bf16 v[62:65], v[184:187], v[216:219], v[62:65]
	v_mfma_f32_16x16x32_bf16 v[58:61], v[188:191], v[212:215], v[58:61]
	v_mfma_f32_16x16x32_bf16 v[58:61], v[192:195], v[216:219], v[58:61]
	v_mfma_f32_16x16x32_bf16 v[54:57], v[178:181], v[220:223], v[54:57]
	v_mfma_f32_16x16x32_bf16 v[54:57], v[184:187], v[224:227], v[54:57]
	v_mfma_f32_16x16x32_bf16 v[46:49], v[188:191], v[220:223], v[46:49]
	v_mfma_f32_16x16x32_bf16 v[46:49], v[192:195], v[224:227], v[46:49]
	v_mfma_f32_16x16x32_bf16 v[38:41], v[178:181], v[228:231], v[38:41]
	v_mfma_f32_16x16x32_bf16 v[38:41], v[184:187], v[232:235], v[38:41]
	v_mfma_f32_16x16x32_bf16 v[30:33], v[188:191], v[228:231], v[30:33]
	v_mfma_f32_16x16x32_bf16 v[30:33], v[192:195], v[232:235], v[30:33]
	v_mfma_f32_16x16x32_bf16 v[22:25], v[178:181], v[236:239], v[22:25]
	v_mfma_f32_16x16x32_bf16 v[22:25], v[184:187], v[240:243], v[22:25]
	v_mfma_f32_16x16x32_bf16 v[14:17], v[188:191], v[236:239], v[14:17]
	v_mfma_f32_16x16x32_bf16 v[14:17], v[192:195], v[240:243], v[14:17]
	s_setprio 0
	s_setprio 1
	v_mfma_f32_16x16x32_bf16 v[50:53], v[196:199], v[212:215], v[50:53]
	v_mfma_f32_16x16x32_bf16 v[50:53], v[200:203], v[216:219], v[50:53]
	v_mfma_f32_16x16x32_bf16 v[42:45], v[204:207], v[212:215], v[42:45]
	v_mfma_f32_16x16x32_bf16 v[42:45], v[208:211], v[216:219], v[42:45]
	v_mfma_f32_16x16x32_bf16 v[34:37], v[196:199], v[220:223], v[34:37]
	v_mfma_f32_16x16x32_bf16 v[34:37], v[200:203], v[224:227], v[34:37]
	v_mfma_f32_16x16x32_bf16 v[26:29], v[204:207], v[220:223], v[26:29]
	v_mfma_f32_16x16x32_bf16 v[26:29], v[208:211], v[224:227], v[26:29]
	v_mfma_f32_16x16x32_bf16 v[18:21], v[196:199], v[228:231], v[18:21]
	v_mfma_f32_16x16x32_bf16 v[18:21], v[200:203], v[232:235], v[18:21]
	v_mfma_f32_16x16x32_bf16 v[10:13], v[204:207], v[228:231], v[10:13]
	v_mfma_f32_16x16x32_bf16 v[10:13], v[208:211], v[232:235], v[10:13]
	v_mfma_f32_16x16x32_bf16 v[6:9], v[196:199], v[236:239], v[6:9]
	v_mfma_f32_16x16x32_bf16 v[6:9], v[200:203], v[240:243], v[6:9]
	v_mfma_f32_16x16x32_bf16 v[2:5], v[204:207], v[236:239], v[2:5]
	v_mfma_f32_16x16x32_bf16 v[2:5], v[208:211], v[240:243], v[2:5]
	s_setprio 0
	s_barrier
	s_add_i32 s48, s48, 2
	s_add_u32 s20, s20, 0x100
	s_addc_u32 s21, s21, 0
	s_add_u32 s46, s46, 0x100
	s_addc_u32 s47, s47, 0
	s_cmp_gt_u32 s48, 13
	s_cbranch_scc0 .LBB0_710
	s_and_b64 vcc, exec, s[12:13]
	s_cbranch_vccz .LBB0_713
	s_barrier

; #define PG8_STAGE(bufoff, gbase, voff) do { _Pragma("unroll") for (int _i = 0; _i < 2; ++_i) \
;         __builtin_amdgcn_global_load_lds((const unsigned*)((const char*)(gbase) + (voff)[_i]), (LAS unsigned*)(lds + (bufoff) + ldsw + _i * 8192), 16, 0, 0); } while (0)
; #define PG8_LDA(dst, b, h) do { _Pragma("unroll") for (int m = 0; m < 4; ++m) _Pragma("unroll") for (int k = 0; k < 2; ++k) dst[m][k] = *(const LAS bf16x8*)(lds + PG8_SA(b, h) + aoff + m * 2048 + k * 1024); } while (0)
; #define PG8_LDB(dst, b, h) do { _Pragma("unroll") for (int n = 0; n < 2; ++n) _Pragma("unroll") for (int k = 0; k < 2; ++k) dst[n][k] = *(const LAS bf16x8*)(lds + PG8_SB(b, h) + boff + n * 2048 + k * 1024); } while (0)
; #define PG8_WAIT_V(n) asm volatile("s_waitcnt vmcnt(" #n ")" ::: "memory")
; #define PG8_WAIT_L(n) asm volatile("s_waitcnt lgkmcnt(" #n ")" ::: "memory")
; #define PG8_BAR __builtin_amdgcn_s_barrier()
; #define PG8_SCHED __builtin_amdgcn_sched_barrier(0)
; template <class Epi, class Sched, class Ptrs, bool ALIGN_EPI, bool I8 = false>
; __device__ __forceinline__ void gemm_phase(LAS unsigned char* lds, const Ptrs& P, const Sched& S, const Epi& E) {
;     ...
;             PG8_LDB(B0, 0, 0); PG8_LDB(B1, 0, 1); PG8_SCHED; PG8_LDA(At, 0, 0); PG8_STAGE(PG8_SA(1, 1), a1 + hstepA, voffA);
;             PG8_WAIT_V(8); PG8_WAIT_L(0); PG8_BAR; PG8_MMA(0, 0, At, B0); PG8_MMA(0, 1, At, B1); PG8_BAR; PG8_SCHED;
.LBB0_742:
	ds_read_b128 v[160:163], v143
	ds_read_b128 v[164:167], v143 offset:1024
	ds_read_b128 v[168:171], v143 offset:2048
	ds_read_b128 v[172:175], v143 offset:3072
	ds_read_b128 v[176:179], v145
	ds_read_b128 v[184:187], v145 offset:1024
	ds_read_b128 v[188:191], v145 offset:2048
	ds_read_b128 v[192:195], v145 offset:3072
	s_add_u32 s22, s20, 0xfff00080
	s_addc_u32 s23, s21, -1
	s_cmp_eq_u32 s44, 12
	s_cselect_b32 s25, s17, s23
	s_cselect_b32 s24, s16, s22
	s_cselect_b32 s23, s19, s43
	s_cselect_b32 s22, s18, s0
	s_mov_b32 m0, s34
	v_lshl_add_u64 v[180:181], s[20:21], 0, v[156:157]
	ds_read_b128 v[196:199], v147
	ds_read_b128 v[200:203], v147 offset:1024
	ds_read_b128 v[204:207], v147 offset:2048
	ds_read_b128 v[208:211], v147 offset:3072
	ds_read_b128 v[212:215], v147 offset:4096
	ds_read_b128 v[216:219], v147 offset:5120
	ds_read_b128 v[220:223], v147 offset:6144
	ds_read_b128 v[224:227], v147 offset:7168
	global_load_lds_dwordx4 v[180:181], off
	v_lshl_add_u64 v[180:181], s[20:21], 0, v[158:159]
	s_mov_b32 m0, s35
	s_nop 0
	global_load_lds_dwordx4 v[180:181], off
	s_waitcnt vmcnt(8)
	s_waitcnt lgkmcnt(0)
	s_barrier
	s_setprio 1
	s_waitcnt lgkmcnt(0)
	v_mfma_f32_16x16x32_bf16 v[126:129], v[160:163], v[196:199], v[126:129]
	v_mfma_f32_16x16x32_bf16 v[126:129], v[164:167], v[200:203], v[126:129]
	v_mfma_f32_16x16x32_bf16 v[122:125], v[168:171], v[196:199], v[122:125]
	v_mfma_f32_16x16x32_bf16 v[122:125], v[172:175], v[200:203], v[122:125]
	v_mfma_f32_16x16x32_bf16 v[118:121], v[160:163], v[204:207], v[118:121]
	v_mfma_f32_16x16x32_bf16 v[118:121], v[164:167], v[208:211], v[118:121]
	v_mfma_f32_16x16x32_bf16 v[110:113], v[168:171], v[204:207], v[110:113]
	v_mfma_f32_16x16x32_bf16 v[110:113], v[172:175], v[208:211], v[110:113]
	v_mfma_f32_16x16x32_bf16 v[102:105], v[160:163], v[212:215], v[102:105]
	v_mfma_f32_16x16x32_bf16 v[102:105], v[164:167], v[216:219], v[102:105]
	v_mfma_f32_16x16x32_bf16 v[94:97], v[168:171], v[212:215], v[94:97]
	v_mfma_f32_16x16x32_bf16 v[94:97], v[172:175], v[216:219], v[94:97]
	v_mfma_f32_16x16x32_bf16 v[86:89], v[160:163], v[220:223], v[86:89]
	v_mfma_f32_16x16x32_bf16 v[86:89], v[164:167], v[224:227], v[86:89]
	v_mfma_f32_16x16x32_bf16 v[78:81], v[168:171], v[220:223], v[78:81]
	v_mfma_f32_16x16x32_bf16 v[78:81], v[172:175], v[224:227], v[78:81]
	s_setprio 0
	s_setprio 1
	v_mfma_f32_16x16x32_bf16 v[114:117], v[176:179], v[196:199], v[114:117]
	v_mfma_f32_16x16x32_bf16 v[114:117], v[184:187], v[200:203], v[114:117]
	v_mfma_f32_16x16x32_bf16 v[106:109], v[188:191], v[196:199], v[106:109]
	v_mfma_f32_16x16x32_bf16 v[106:109], v[192:195], v[200:203], v[106:109]
	v_mfma_f32_16x16x32_bf16 v[98:101], v[176:179], v[204:207], v[98:101]
	v_mfma_f32_16x16x32_bf16 v[98:101], v[184:187], v[208:211], v[98:101]
	v_mfma_f32_16x16x32_bf16 v[90:93], v[188:191], v[204:207], v[90:93]
	v_mfma_f32_16x16x32_bf16 v[90:93], v[192:195], v[208:211], v[90:93]
	v_mfma_f32_16x16x32_bf16 v[82:85], v[176:179], v[212:215], v[82:85]
	v_mfma_f32_16x16x32_bf16 v[82:85], v[184:187], v[216:219], v[82:85]
	v_mfma_f32_16x16x32_bf16 v[74:77], v[188:191], v[212:215], v[74:77]
	v_mfma_f32_16x16x32_bf16 v[74:77], v[192:195], v[216:219], v[74:77]
	v_mfma_f32_16x16x32_bf16 v[70:73], v[176:179], v[220:223], v[70:73]
	v_mfma_f32_16x16x32_bf16 v[70:73], v[184:187], v[224:227], v[70:73]
	v_mfma_f32_16x16x32_bf16 v[66:69], v[188:191], v[220:223], v[66:69]
	v_mfma_f32_16x16x32_bf16 v[66:69], v[192:195], v[224:227], v[66:69]
	s_setprio 0
	s_barrier
	s_mov_b32 m0, s36
	v_lshl_add_u64 v[180:181], s[22:23], 0, v[132:133]
	s_add_u32 s46, s22, 0x200000
	ds_read_b128 v[196:199], v147 offset:16384
	ds_read_b128 v[200:203], v147 offset:17408
	ds_read_b128 v[204:207], v147 offset:18432
	ds_read_b128 v[208:211], v147 offset:19456
	ds_read_b128 v[212:215], v147 offset:20480
	ds_read_b128 v[216:219], v147 offset:21504
	ds_read_b128 v[220:223], v147 offset:22528
	ds_read_b128 v[224:227], v147 offset:23552
	global_load_lds_dwordx4 v[180:181], off
	v_lshl_add_u64 v[228:229], s[22:23], 0, v[136:137]
	s_mov_b32 m0, s37
	s_addc_u32 s47, s23, 0
	global_load_lds_dwordx4 v[228:229], off
	v_lshl_add_u64 v[230:231], s[46:47], 0, v[132:133]
	s_mov_b32 m0, s38
	v_lshl_add_u64 v[232:233], s[24:25], 0, v[134:135]
	global_load_lds_dwordx4 v[230:231], off
	v_lshl_add_u64 v[230:231], s[46:47], 0, v[136:137]
	s_mov_b32 m0, s39
	s_nop 0
	global_load_lds_dwordx4 v[230:231], off
	v_lshl_add_u64 v[230:231], s[24:25], 0, v[130:131]
	s_mov_b32 m0, s27
	s_nop 0
	global_load_lds_dwordx4 v[230:231], off
	s_mov_b32 m0, s28
	s_nop 0
	global_load_lds_dwordx4 v[232:233], off
	s_waitcnt vmcnt(8)
	s_waitcnt lgkmcnt(0)
	s_barrier
; #define PG8_STAGE(bufoff, gbase, voff) do { _Pragma("unroll") for (int _i = 0; _i < 2; ++_i) \
;         __builtin_amdgcn_global_load_lds((const unsigned*)((const char*)(gbase) + (voff)[_i]), (LAS unsigned*)(lds + (bufoff) + ldsw + _i * 8192), 16, 0, 0); } while (0)
; #define PG8_LDA(dst, b, h) do { _Pragma("unroll") for (int m = 0; m < 4; ++m) _Pragma("unroll") for (int k = 0; k < 2; ++k) dst[m][k] = *(const LAS bf16x8*)(lds + PG8_SA(b, h) + aoff + m * 2048 + k * 1024); } while (0)
; #define PG8_LDB(dst, b, h) do { _Pragma("unroll") for (int n = 0; n < 2; ++n) _Pragma("unroll") for (int k = 0; k < 2; ++k) dst[n][k] = *(const LAS bf16x8*)(lds + PG8_SB(b, h) + boff + n * 2048 + k * 1024); } while (0)
; #define PG8_WAIT_V(n) asm volatile("s_waitcnt vmcnt(" #n ")" ::: "memory")
; #define PG8_WAIT_L(n) asm volatile("s_waitcnt lgkmcnt(" #n ")" ::: "memory")
; #define PG8_BAR __builtin_amdgcn_s_barrier()
; #define PG8_SCHED __builtin_amdgcn_sched_barrier(0)
; template <class Epi, class Sched, class Ptrs, bool ALIGN_EPI, bool I8 = false>
; __device__ __forceinline__ void gemm_phase(LAS unsigned char* lds, const Ptrs& P, const Sched& S, const Epi& E) {
;     ...
;             PG8_LDA(At, 0, 1); PG8_STAGE(PG8_SB(0, 0), b2, voffB); PG8_STAGE(PG8_SB(0, 1), b2 + hstepB, voffB); PG8_STAGE(PG8_SA(0, 0), a2, voffA);
;             PG8_WAIT_V(8); PG8_WAIT_L(0); PG8_BAR; PG8_MMA(1, 0, At, B0); PG8_MMA(1, 1, At, B1); PG8_BAR; PG8_SCHED;
;             PG8_LDB(B0, 1, 0); PG8_LDB(B1, 1, 1); PG8_SCHED; PG8_LDA(At, 1, 0); PG8_STAGE(PG8_SA(0, 1), a2 + hstepA, voffA);
;             PG8_WAIT_V(8); PG8_WAIT_L(0); PG8_BAR; PG8_MMA(0, 0, At, B0); PG8_MMA(0, 1, At, B1); PG8_BAR; PG8_SCHED;
	s_setprio 1
	s_waitcnt lgkmcnt(0)
	v_mfma_f32_16x16x32_bf16 v[62:65], v[160:163], v[196:199], v[62:65]
	v_mfma_f32_16x16x32_bf16 v[62:65], v[164:167], v[200:203], v[62:65]
	v_mfma_f32_16x16x32_bf16 v[58:61], v[168:171], v[196:199], v[58:61]
	v_mfma_f32_16x16x32_bf16 v[58:61], v[172:175], v[200:203], v[58:61]
	v_mfma_f32_16x16x32_bf16 v[54:57], v[160:163], v[204:207], v[54:57]
	v_mfma_f32_16x16x32_bf16 v[54:57], v[164:167], v[208:211], v[54:57]
	v_mfma_f32_16x16x32_bf16 v[46:49], v[168:171], v[204:207], v[46:49]
	v_mfma_f32_16x16x32_bf16 v[46:49], v[172:175], v[208:211], v[46:49]
	v_mfma_f32_16x16x32_bf16 v[38:41], v[160:163], v[212:215], v[38:41]
	v_mfma_f32_16x16x32_bf16 v[38:41], v[164:167], v[216:219], v[38:41]
	v_mfma_f32_16x16x32_bf16 v[30:33], v[168:171], v[212:215], v[30:33]
	v_mfma_f32_16x16x32_bf16 v[30:33], v[172:175], v[216:219], v[30:33]
	v_mfma_f32_16x16x32_bf16 v[22:25], v[160:163], v[220:223], v[22:25]
	v_mfma_f32_16x16x32_bf16 v[22:25], v[164:167], v[224:227], v[22:25]
	v_mfma_f32_16x16x32_bf16 v[14:17], v[168:171], v[220:223], v[14:17]
	v_mfma_f32_16x16x32_bf16 v[14:17], v[172:175], v[224:227], v[14:17]
	s_setprio 0
	s_setprio 1
	v_mfma_f32_16x16x32_bf16 v[50:53], v[176:179], v[196:199], v[50:53]
	v_mfma_f32_16x16x32_bf16 v[50:53], v[184:187], v[200:203], v[50:53]
	v_mfma_f32_16x16x32_bf16 v[42:45], v[188:191], v[196:199], v[42:45]
	v_mfma_f32_16x16x32_bf16 v[42:45], v[192:195], v[200:203], v[42:45]
	v_mfma_f32_16x16x32_bf16 v[34:37], v[176:179], v[204:207], v[34:37]
	v_mfma_f32_16x16x32_bf16 v[34:37], v[184:187], v[208:211], v[34:37]
	v_mfma_f32_16x16x32_bf16 v[26:29], v[188:191], v[204:207], v[26:29]
	v_mfma_f32_16x16x32_bf16 v[26:29], v[192:195], v[208:211], v[26:29]
	v_mfma_f32_16x16x32_bf16 v[18:21], v[176:179], v[212:215], v[18:21]
	v_mfma_f32_16x16x32_bf16 v[18:21], v[184:187], v[216:219], v[18:21]
	v_mfma_f32_16x16x32_bf16 v[10:13], v[188:191], v[212:215], v[10:13]
	v_mfma_f32_16x16x32_bf16 v[10:13], v[192:195], v[216:219], v[10:13]
	v_mfma_f32_16x16x32_bf16 v[6:9], v[176:179], v[220:223], v[6:9]
	v_mfma_f32_16x16x32_bf16 v[6:9], v[184:187], v[224:227], v[6:9]
	v_mfma_f32_16x16x32_bf16 v[2:5], v[188:191], v[220:223], v[2:5]
	v_mfma_f32_16x16x32_bf16 v[2:5], v[192:195], v[224:227], v[2:5]
	s_setprio 0
	s_barrier
	s_add_i32 s45, 0, 0x18000
	v_add_u32_e32 v149, s45, v141
	s_add_i32 s46, 0, 0x1c000
	ds_read_b128 v[160:163], v149
	ds_read_b128 v[164:167], v149 offset:1024
	ds_read_b128 v[168:171], v149 offset:2048
	ds_read_b128 v[172:175], v149 offset:3072
	v_add_u32_e32 v149, s46, v141
	ds_read_b128 v[176:179], v149
	ds_read_b128 v[184:187], v149 offset:1024
	ds_read_b128 v[188:191], v149 offset:2048
	ds_read_b128 v[192:195], v149 offset:3072
	s_add_u32 s24, s24, 0x100000
	s_addc_u32 s25, s25, 0
	s_mov_b32 m0, s29
	v_lshl_add_u64 v[234:235], s[24:25], 0, v[130:131]
	ds_read_b128 v[196:199], v147 offset:32768
	ds_read_b128 v[200:203], v147 offset:33792
	ds_read_b128 v[204:207], v147 offset:34816
	ds_read_b128 v[208:211], v147 offset:35840
	ds_read_b128 v[212:215], v147 offset:36864
	ds_read_b128 v[216:219], v147 offset:37888
	ds_read_b128 v[220:223], v147 offset:38912
	ds_read_b128 v[224:227], v147 offset:39936
	global_load_lds_dwordx4 v[234:235], off
	v_lshl_add_u64 v[234:235], s[24:25], 0, v[134:135]
	s_mov_b32 m0, s30
	s_nop 0
	global_load_lds_dwordx4 v[234:235], off
	s_waitcnt vmcnt(8)
	s_waitcnt lgkmcnt(0)
	s_barrier
	s_setprio 1
	s_waitcnt lgkmcnt(0)
	v_mfma_f32_16x16x32_bf16 v[126:129], v[160:163], v[196:199], v[126:129]
	v_mfma_f32_16x16x32_bf16 v[126:129], v[164:167], v[200:203], v[126:129]
	v_mfma_f32_16x16x32_bf16 v[122:125], v[168:171], v[196:199], v[122:125]
	v_mfma_f32_16x16x32_bf16 v[122:125], v[172:175], v[200:203], v[122:125]
	v_mfma_f32_16x16x32_bf16 v[118:121], v[160:163], v[204:207], v[118:121]
	v_mfma_f32_16x16x32_bf16 v[118:121], v[164:167], v[208:211], v[118:121]
	v_mfma_f32_16x16x32_bf16 v[110:113], v[168:171], v[204:207], v[110:113]
	v_mfma_f32_16x16x32_bf16 v[110:113], v[172:175], v[208:211], v[110:113]
	v_mfma_f32_16x16x32_bf16 v[102:105], v[160:163], v[212:215], v[102:105]
	v_mfma_f32_16x16x32_bf16 v[102:105], v[164:167], v[216:219], v[102:105]
	v_mfma_f32_16x16x32_bf16 v[94:97], v[168:171], v[212:215], v[94:97]
	v_mfma_f32_16x16x32_bf16 v[94:97], v[172:175], v[216:219], v[94:97]
	v_mfma_f32_16x16x32_bf16 v[86:89], v[160:163], v[220:223], v[86:89]
	v_mfma_f32_16x16x32_bf16 v[86:89], v[164:167], v[224:227], v[86:89]
	v_mfma_f32_16x16x32_bf16 v[78:81], v[168:171], v[220:223], v[78:81]
	v_mfma_f32_16x16x32_bf16 v[78:81], v[172:175], v[224:227], v[78:81]
	s_setprio 0
	s_setprio 1
	v_mfma_f32_16x16x32_bf16 v[114:117], v[176:179], v[196:199], v[114:117]
	v_mfma_f32_16x16x32_bf16 v[114:117], v[184:187], v[200:203], v[114:117]
	v_mfma_f32_16x16x32_bf16 v[106:109], v[188:191], v[196:199], v[106:109]
	v_mfma_f32_16x16x32_bf16 v[106:109], v[192:195], v[200:203], v[106:109]
	v_mfma_f32_16x16x32_bf16 v[98:101], v[176:179], v[204:207], v[98:101]
	v_mfma_f32_16x16x32_bf16 v[98:101], v[184:187], v[208:211], v[98:101]
	v_mfma_f32_16x16x32_bf16 v[90:93], v[188:191], v[204:207], v[90:93]
	v_mfma_f32_16x16x32_bf16 v[90:93], v[192:195], v[208:211], v[90:93]
	v_mfma_f32_16x16x32_bf16 v[82:85], v[176:179], v[212:215], v[82:85]
	v_mfma_f32_16x16x32_bf16 v[82:85], v[184:187], v[216:219], v[82:85]
	v_mfma_f32_16x16x32_bf16 v[74:77], v[188:191], v[212:215], v[74:77]
	v_mfma_f32_16x16x32_bf16 v[74:77], v[192:195], v[216:219], v[74:77]
	v_mfma_f32_16x16x32_bf16 v[70:73], v[176:179], v[220:223], v[70:73]
	v_mfma_f32_16x16x32_bf16 v[70:73], v[184:187], v[224:227], v[70:73]
	v_mfma_f32_16x16x32_bf16 v[66:69], v[188:191], v[220:223], v[66:69]
	v_mfma_f32_16x16x32_bf16 v[66:69], v[192:195], v[224:227], v[66:69]
	s_setprio 0
	s_barrier
; #define PG8_STAGE(bufoff, gbase, voff) do { _Pragma("unroll") for (int _i = 0; _i < 2; ++_i) \
;         __builtin_amdgcn_global_load_lds((const unsigned*)((const char*)(gbase) + (voff)[_i]), (LAS unsigned*)(lds + (bufoff) + ldsw + _i * 8192), 16, 0, 0); } while (0)
; #define PG8_LDA(dst, b, h) do { _Pragma("unroll") for (int m = 0; m < 4; ++m) _Pragma("unroll") for (int k = 0; k < 2; ++k) dst[m][k] = *(const LAS bf16x8*)(lds + PG8_SA(b, h) + aoff + m * 2048 + k * 1024); } while (0)
; #define PG8_WAIT_V(n) asm volatile("s_waitcnt vmcnt(" #n ")" ::: "memory")
; #define PG8_WAIT_L(n) asm volatile("s_waitcnt lgkmcnt(" #n ")" ::: "memory")
; #define PG8_BAR __builtin_amdgcn_s_barrier()
; #define PG8_SCHED __builtin_amdgcn_sched_barrier(0)
; template <class Epi, class Sched, class Ptrs, bool ALIGN_EPI, bool I8 = false>
; __device__ __forceinline__ void gemm_phase(LAS unsigned char* lds, const Ptrs& P, const Sched& S, const Epi& E) {
;     ...
;             PG8_LDA(At, 1, 1); PG8_STAGE(PG8_SB(1, 0), b3, voffB); PG8_STAGE(PG8_SB(1, 1), b3 + hstepB, voffB); PG8_STAGE(PG8_SA(1, 0), a3, voffA);
;             PG8_WAIT_V(8); PG8_WAIT_L(0); PG8_BAR; PG8_MMA(1, 0, At, B0); PG8_MMA(1, 1, At, B1); PG8_BAR; PG8_SCHED;
;         }
	s_add_i32 s24, s45, s26
	v_lshl_add_u64 v[180:181], v[180:181], 0, s[10:11]
	s_mov_b32 m0, s24
	ds_read_b128 v[196:199], v147 offset:49152
	ds_read_b128 v[200:203], v147 offset:50176
	ds_read_b128 v[204:207], v147 offset:51200
	ds_read_b128 v[208:211], v147 offset:52224
	ds_read_b128 v[212:215], v147 offset:53248
	ds_read_b128 v[216:219], v147 offset:54272
	ds_read_b128 v[220:223], v147 offset:55296
	ds_read_b128 v[224:227], v147 offset:56320
	global_load_lds_dwordx4 v[180:181], off
	s_add_i32 m0, s24, 0x2000
	s_add_u32 s22, s22, 0x200080
	v_lshl_add_u64 v[180:181], v[228:229], 0, s[10:11]
	s_addc_u32 s23, s23, 0
	s_add_i32 s24, s46, s26
	global_load_lds_dwordx4 v[180:181], off
	v_lshl_add_u64 v[180:181], s[22:23], 0, v[132:133]
	s_mov_b32 m0, s24
	s_nop 0
	global_load_lds_dwordx4 v[180:181], off
	v_lshl_add_u64 v[180:181], s[22:23], 0, v[136:137]
	s_add_i32 m0, s24, 0x2000
	s_nop 0
	global_load_lds_dwordx4 v[180:181], off
	v_lshl_add_u64 v[180:181], v[230:231], 0, s[10:11]
	s_mov_b32 m0, s31
	s_nop 0
	global_load_lds_dwordx4 v[180:181], off
	v_lshl_add_u64 v[180:181], v[232:233], 0, s[10:11]
	s_mov_b32 m0, s33
	s_nop 0
	global_load_lds_dwordx4 v[180:181], off
	s_waitcnt vmcnt(8)
	s_waitcnt lgkmcnt(0)
	s_barrier
	s_setprio 1
	s_waitcnt lgkmcnt(0)
	v_mfma_f32_16x16x32_bf16 v[62:65], v[160:163], v[196:199], v[62:65]
	v_mfma_f32_16x16x32_bf16 v[62:65], v[164:167], v[200:203], v[62:65]
	v_mfma_f32_16x16x32_bf16 v[58:61], v[168:171], v[196:199], v[58:61]
	v_mfma_f32_16x16x32_bf16 v[58:61], v[172:175], v[200:203], v[58:61]
	v_mfma_f32_16x16x32_bf16 v[54:57], v[160:163], v[204:207], v[54:57]
	v_mfma_f32_16x16x32_bf16 v[54:57], v[164:167], v[208:211], v[54:57]
	v_mfma_f32_16x16x32_bf16 v[46:49], v[168:171], v[204:207], v[46:49]
	v_mfma_f32_16x16x32_bf16 v[46:49], v[172:175], v[208:211], v[46:49]
	v_mfma_f32_16x16x32_bf16 v[38:41], v[160:163], v[212:215], v[38:41]
	v_mfma_f32_16x16x32_bf16 v[38:41], v[164:167], v[216:219], v[38:41]
	v_mfma_f32_16x16x32_bf16 v[30:33], v[168:171], v[212:215], v[30:33]
	v_mfma_f32_16x16x32_bf16 v[30:33], v[172:175], v[216:219], v[30:33]
	v_mfma_f32_16x16x32_bf16 v[22:25], v[160:163], v[220:223], v[22:25]
	v_mfma_f32_16x16x32_bf16 v[22:25], v[164:167], v[224:227], v[22:25]
	v_mfma_f32_16x16x32_bf16 v[14:17], v[168:171], v[220:223], v[14:17]
	v_mfma_f32_16x16x32_bf16 v[14:17], v[172:175], v[224:227], v[14:17]
	s_setprio 0
	s_setprio 1
	v_mfma_f32_16x16x32_bf16 v[50:53], v[176:179], v[196:199], v[50:53]
	v_mfma_f32_16x16x32_bf16 v[50:53], v[184:187], v[200:203], v[50:53]
	v_mfma_f32_16x16x32_bf16 v[42:45], v[188:191], v[196:199], v[42:45]
	v_mfma_f32_16x16x32_bf16 v[42:45], v[192:195], v[200:203], v[42:45]
	v_mfma_f32_16x16x32_bf16 v[34:37], v[176:179], v[204:207], v[34:37]
	v_mfma_f32_16x16x32_bf16 v[34:37], v[184:187], v[208:211], v[34:37]
	v_mfma_f32_16x16x32_bf16 v[26:29], v[188:191], v[204:207], v[26:29]
	v_mfma_f32_16x16x32_bf16 v[26:29], v[192:195], v[208:211], v[26:29]
	v_mfma_f32_16x16x32_bf16 v[18:21], v[176:179], v[212:215], v[18:21]
	v_mfma_f32_16x16x32_bf16 v[18:21], v[184:187], v[216:219], v[18:21]
	v_mfma_f32_16x16x32_bf16 v[10:13], v[188:191], v[212:215], v[10:13]
	v_mfma_f32_16x16x32_bf16 v[10:13], v[192:195], v[216:219], v[10:13]
	v_mfma_f32_16x16x32_bf16 v[6:9], v[176:179], v[220:223], v[6:9]
	v_mfma_f32_16x16x32_bf16 v[6:9], v[184:187], v[224:227], v[6:9]
	v_mfma_f32_16x16x32_bf16 v[2:5], v[188:191], v[220:223], v[2:5]
	v_mfma_f32_16x16x32_bf16 v[2:5], v[192:195], v[224:227], v[2:5]
	s_setprio 0
	s_barrier
	s_add_i32 s44, s44, 2
	s_add_u32 s20, s20, 0x100
	s_addc_u32 s21, s21, 0
	s_add_u32 s0, s0, 0x100
	s_addc_u32 s43, s43, 0
	s_cmp_gt_u32 s44, 13
	s_cbranch_scc0 .LBB0_742
	s_and_b64 vcc, exec, s[12:13]
	s_cbranch_vccnz .LBB0_747
	s_cmpk_gt_i32 s42, 0xff
	s_mov_b64 s[20:21], -1
	s_cbranch_scc1 .LBB0_748

; #define PG8_STAGE(bufoff, gbase, voff) do { _Pragma("unroll") for (int _i = 0; _i < 2; ++_i) \
;         __builtin_amdgcn_global_load_lds((const unsigned*)((const char*)(gbase) + (voff)[_i]), (LAS unsigned*)(lds + (bufoff) + ldsw + _i * 8192), 16, 0, 0); } while (0)
; #define PG8_LDA(dst, b, h) do { _Pragma("unroll") for (int m = 0; m < 4; ++m) _Pragma("unroll") for (int k = 0; k < 2; ++k) dst[m][k] = *(const LAS bf16x8*)(lds + PG8_SA(b, h) + aoff + m * 2048 + k * 1024); } while (0)
; #define PG8_LDB(dst, b, h) do { _Pragma("unroll") for (int n = 0; n < 2; ++n) _Pragma("unroll") for (int k = 0; k < 2; ++k) dst[n][k] = *(const LAS bf16x8*)(lds + PG8_SB(b, h) + boff + n * 2048 + k * 1024); } while (0)
; #define PG8_WAIT_V(n) asm volatile("s_waitcnt vmcnt(" #n ")" ::: "memory")
; #define PG8_WAIT_L(n) asm volatile("s_waitcnt lgkmcnt(" #n ")" ::: "memory")
; #define PG8_BAR __builtin_amdgcn_s_barrier()
; #define PG8_SCHED __builtin_amdgcn_sched_barrier(0)
; template <class Epi, class Sched, class Ptrs, bool ALIGN_EPI, bool I8 = false>
; __device__ __forceinline__ void gemm_phase(LAS unsigned char* lds, const Ptrs& P, const Sched& S, const Epi& E) {
;     ...
;             PG8_LDB(B0, 0, 0); PG8_LDB(B1, 0, 1); PG8_SCHED; PG8_LDA(At, 0, 0); PG8_STAGE(PG8_SA(1, 1), a1 + hstepA, voffA);
;             PG8_WAIT_V(8); PG8_WAIT_L(0); PG8_BAR; PG8_MMA(0, 0, At, B0); PG8_MMA(0, 1, At, B1); PG8_BAR; PG8_SCHED;
.LBB0_1096:
	ds_read_b128 v[130:133], v192
	ds_read_b128 v[134:137], v192 offset:1024
	ds_read_b128 v[138:141], v192 offset:2048
	ds_read_b128 v[142:145], v192 offset:3072
	ds_read_b128 v[146:149], v193
	ds_read_b128 v[150:153], v193 offset:1024
	ds_read_b128 v[170:173], v193 offset:2048
	ds_read_b128 v[174:177], v193 offset:3072
	s_add_u32 s30, s28, 0xfff00080
	s_addc_u32 s31, s29, -1
	s_cmp_eq_u32 s50, 60
	s_cselect_b32 s35, s21, s31
	s_cselect_b32 s34, s27, s30
	s_cselect_b32 s31, s19, s49
	s_cselect_b32 s30, s47, s48
	v_lshl_add_u64 v[188:189], s[28:29], 0, v[162:163]
	s_add_i32 m0, s33, 0xc000
	ds_read_b128 v[178:181], v194
	ds_read_b128 v[184:187], v194 offset:1024
	ds_read_b128 v[196:199], v194 offset:2048
	ds_read_b128 v[200:203], v194 offset:3072
	ds_read_b128 v[204:207], v194 offset:4096
	ds_read_b128 v[208:211], v194 offset:5120
	ds_read_b128 v[212:215], v194 offset:6144
	ds_read_b128 v[216:219], v194 offset:7168
	global_load_lds_dwordx4 v[188:189], off
	v_lshl_add_u64 v[188:189], s[28:29], 0, v[164:165]
	s_add_i32 m0, s33, 0xe000
	s_nop 0
	global_load_lds_dwordx4 v[188:189], off
	s_waitcnt vmcnt(8)
	s_waitcnt lgkmcnt(0)
	s_barrier
	s_setprio 1
	s_waitcnt lgkmcnt(0)
	v_mfma_f32_16x16x32_bf16 v[126:129], v[130:133], v[178:181], v[126:129]
	v_mfma_f32_16x16x32_bf16 v[126:129], v[134:137], v[184:187], v[126:129]
	v_mfma_f32_16x16x32_bf16 v[122:125], v[138:141], v[178:181], v[122:125]
	v_mfma_f32_16x16x32_bf16 v[122:125], v[142:145], v[184:187], v[122:125]
	v_mfma_f32_16x16x32_bf16 v[110:113], v[130:133], v[196:199], v[110:113]
	v_mfma_f32_16x16x32_bf16 v[110:113], v[134:137], v[200:203], v[110:113]
	v_mfma_f32_16x16x32_bf16 v[106:109], v[138:141], v[196:199], v[106:109]
	v_mfma_f32_16x16x32_bf16 v[106:109], v[142:145], v[200:203], v[106:109]
	v_mfma_f32_16x16x32_bf16 v[94:97], v[130:133], v[204:207], v[94:97]
	v_mfma_f32_16x16x32_bf16 v[94:97], v[134:137], v[208:211], v[94:97]
	v_mfma_f32_16x16x32_bf16 v[90:93], v[138:141], v[204:207], v[90:93]
	v_mfma_f32_16x16x32_bf16 v[90:93], v[142:145], v[208:211], v[90:93]
	v_mfma_f32_16x16x32_bf16 v[78:81], v[130:133], v[212:215], v[78:81]
	v_mfma_f32_16x16x32_bf16 v[78:81], v[134:137], v[216:219], v[78:81]
	v_mfma_f32_16x16x32_bf16 v[74:77], v[138:141], v[212:215], v[74:77]
	v_mfma_f32_16x16x32_bf16 v[74:77], v[142:145], v[216:219], v[74:77]
	s_setprio 0
	s_setprio 1
	v_mfma_f32_16x16x32_bf16 v[118:121], v[146:149], v[178:181], v[118:121]
	v_mfma_f32_16x16x32_bf16 v[118:121], v[150:153], v[184:187], v[118:121]
	v_mfma_f32_16x16x32_bf16 v[114:117], v[170:173], v[178:181], v[114:117]
	v_mfma_f32_16x16x32_bf16 v[114:117], v[174:177], v[184:187], v[114:117]
	v_mfma_f32_16x16x32_bf16 v[102:105], v[146:149], v[196:199], v[102:105]
	v_mfma_f32_16x16x32_bf16 v[102:105], v[150:153], v[200:203], v[102:105]
	v_mfma_f32_16x16x32_bf16 v[98:101], v[170:173], v[196:199], v[98:101]
	v_mfma_f32_16x16x32_bf16 v[98:101], v[174:177], v[200:203], v[98:101]
	v_mfma_f32_16x16x32_bf16 v[86:89], v[146:149], v[204:207], v[86:89]
	v_mfma_f32_16x16x32_bf16 v[86:89], v[150:153], v[208:211], v[86:89]
	v_mfma_f32_16x16x32_bf16 v[82:85], v[170:173], v[204:207], v[82:85]
	v_mfma_f32_16x16x32_bf16 v[82:85], v[174:177], v[208:211], v[82:85]
	v_mfma_f32_16x16x32_bf16 v[70:73], v[146:149], v[212:215], v[70:73]
	v_mfma_f32_16x16x32_bf16 v[70:73], v[150:153], v[216:219], v[70:73]
	v_mfma_f32_16x16x32_bf16 v[66:69], v[170:173], v[212:215], v[66:69]
	v_mfma_f32_16x16x32_bf16 v[66:69], v[174:177], v[216:219], v[66:69]
	s_setprio 0
	s_barrier
	s_add_i32 s51, s44, s3
	v_lshl_add_u64 v[188:189], s[30:31], 0, v[156:157]
	s_mov_b32 m0, s51
	ds_read_b128 v[178:181], v194 offset:16384
	ds_read_b128 v[184:187], v194 offset:17408
	ds_read_b128 v[196:199], v194 offset:18432
	ds_read_b128 v[200:203], v194 offset:19456
	ds_read_b128 v[204:207], v194 offset:20480
	ds_read_b128 v[208:211], v194 offset:21504
	ds_read_b128 v[212:215], v194 offset:22528
	ds_read_b128 v[216:219], v194 offset:23552
	global_load_lds_dwordx4 v[188:189], off
	s_add_i32 m0, s51, 0x2000
	s_add_u32 s52, s30, 0x100000
	v_lshl_add_u64 v[220:221], s[30:31], 0, v[160:161]
	s_addc_u32 s53, s31, 0
	s_add_i32 s51, s45, s3
	global_load_lds_dwordx4 v[220:221], off
	v_lshl_add_u64 v[222:223], s[52:53], 0, v[156:157]
	s_mov_b32 m0, s51
	v_lshl_add_u64 v[224:225], s[34:35], 0, v[158:159]
	global_load_lds_dwordx4 v[222:223], off
	v_lshl_add_u64 v[222:223], s[52:53], 0, v[160:161]
	s_add_i32 m0, s51, 0x2000
	s_nop 0
	global_load_lds_dwordx4 v[222:223], off
	v_lshl_add_u64 v[222:223], s[34:35], 0, v[154:155]
	s_mov_b32 m0, s33
	s_nop 0
	global_load_lds_dwordx4 v[222:223], off
	s_mov_b32 m0, s36
	s_nop 0
	global_load_lds_dwordx4 v[224:225], off
	s_waitcnt vmcnt(8)
	s_waitcnt lgkmcnt(0)
	s_barrier
; #define PG8_STAGE(bufoff, gbase, voff) do { _Pragma("unroll") for (int _i = 0; _i < 2; ++_i) \
;         __builtin_amdgcn_global_load_lds((const unsigned*)((const char*)(gbase) + (voff)[_i]), (LAS unsigned*)(lds + (bufoff) + ldsw + _i * 8192), 16, 0, 0); } while (0)
; #define PG8_LDA(dst, b, h) do { _Pragma("unroll") for (int m = 0; m < 4; ++m) _Pragma("unroll") for (int k = 0; k < 2; ++k) dst[m][k] = *(const LAS bf16x8*)(lds + PG8_SA(b, h) + aoff + m * 2048 + k * 1024); } while (0)
; #define PG8_LDB(dst, b, h) do { _Pragma("unroll") for (int n = 0; n < 2; ++n) _Pragma("unroll") for (int k = 0; k < 2; ++k) dst[n][k] = *(const LAS bf16x8*)(lds + PG8_SB(b, h) + boff + n * 2048 + k * 1024); } while (0)
; #define PG8_WAIT_V(n) asm volatile("s_waitcnt vmcnt(" #n ")" ::: "memory")
; #define PG8_WAIT_L(n) asm volatile("s_waitcnt lgkmcnt(" #n ")" ::: "memory")
; #define PG8_BAR __builtin_amdgcn_s_barrier()
; #define PG8_SCHED __builtin_amdgcn_sched_barrier(0)
; template <class Epi, class Sched, class Ptrs, bool ALIGN_EPI, bool I8 = false>
; __device__ __forceinline__ void gemm_phase(LAS unsigned char* lds, const Ptrs& P, const Sched& S, const Epi& E) {
;     ...
;             PG8_LDA(At, 0, 1); PG8_STAGE(PG8_SB(0, 0), b2, voffB); PG8_STAGE(PG8_SB(0, 1), b2 + hstepB, voffB); PG8_STAGE(PG8_SA(0, 0), a2, voffA);
;             PG8_WAIT_V(8); PG8_WAIT_L(0); PG8_BAR; PG8_MMA(1, 0, At, B0); PG8_MMA(1, 1, At, B1); PG8_BAR; PG8_SCHED;
;             PG8_LDB(B0, 1, 0); PG8_LDB(B1, 1, 1); PG8_SCHED; PG8_LDA(At, 1, 0); PG8_STAGE(PG8_SA(0, 1), a2 + hstepA, voffA);
;             PG8_WAIT_V(8); PG8_WAIT_L(0); PG8_BAR; PG8_MMA(0, 0, At, B0); PG8_MMA(0, 1, At, B1); PG8_BAR; PG8_SCHED;
	s_setprio 1
	s_waitcnt lgkmcnt(0)
	v_mfma_f32_16x16x32_bf16 v[62:65], v[130:133], v[178:181], v[62:65]
	v_mfma_f32_16x16x32_bf16 v[62:65], v[134:137], v[184:187], v[62:65]
	v_mfma_f32_16x16x32_bf16 v[58:61], v[138:141], v[178:181], v[58:61]
	v_mfma_f32_16x16x32_bf16 v[58:61], v[142:145], v[184:187], v[58:61]
	v_mfma_f32_16x16x32_bf16 v[46:49], v[130:133], v[196:199], v[46:49]
	v_mfma_f32_16x16x32_bf16 v[46:49], v[134:137], v[200:203], v[46:49]
	v_mfma_f32_16x16x32_bf16 v[42:45], v[138:141], v[196:199], v[42:45]
	v_mfma_f32_16x16x32_bf16 v[42:45], v[142:145], v[200:203], v[42:45]
	v_mfma_f32_16x16x32_bf16 v[30:33], v[130:133], v[204:207], v[30:33]
	v_mfma_f32_16x16x32_bf16 v[30:33], v[134:137], v[208:211], v[30:33]
	v_mfma_f32_16x16x32_bf16 v[26:29], v[138:141], v[204:207], v[26:29]
	v_mfma_f32_16x16x32_bf16 v[26:29], v[142:145], v[208:211], v[26:29]
	v_mfma_f32_16x16x32_bf16 v[14:17], v[130:133], v[212:215], v[14:17]
	v_mfma_f32_16x16x32_bf16 v[14:17], v[134:137], v[216:219], v[14:17]
	v_mfma_f32_16x16x32_bf16 v[10:13], v[138:141], v[212:215], v[10:13]
	v_mfma_f32_16x16x32_bf16 v[10:13], v[142:145], v[216:219], v[10:13]
	s_setprio 0
	s_setprio 1
	v_mfma_f32_16x16x32_bf16 v[54:57], v[146:149], v[178:181], v[54:57]
	v_mfma_f32_16x16x32_bf16 v[54:57], v[150:153], v[184:187], v[54:57]
	v_mfma_f32_16x16x32_bf16 v[50:53], v[170:173], v[178:181], v[50:53]
	v_mfma_f32_16x16x32_bf16 v[50:53], v[174:177], v[184:187], v[50:53]
	v_mfma_f32_16x16x32_bf16 v[38:41], v[146:149], v[196:199], v[38:41]
	v_mfma_f32_16x16x32_bf16 v[38:41], v[150:153], v[200:203], v[38:41]
	v_mfma_f32_16x16x32_bf16 v[34:37], v[170:173], v[196:199], v[34:37]
	v_mfma_f32_16x16x32_bf16 v[34:37], v[174:177], v[200:203], v[34:37]
	v_mfma_f32_16x16x32_bf16 v[22:25], v[146:149], v[204:207], v[22:25]
	v_mfma_f32_16x16x32_bf16 v[22:25], v[150:153], v[208:211], v[22:25]
	v_mfma_f32_16x16x32_bf16 v[18:21], v[170:173], v[204:207], v[18:21]
	v_mfma_f32_16x16x32_bf16 v[18:21], v[174:177], v[208:211], v[18:21]
	v_mfma_f32_16x16x32_bf16 v[6:9], v[146:149], v[212:215], v[6:9]
	v_mfma_f32_16x16x32_bf16 v[6:9], v[150:153], v[216:219], v[6:9]
	v_mfma_f32_16x16x32_bf16 v[2:5], v[170:173], v[212:215], v[2:5]
	v_mfma_f32_16x16x32_bf16 v[2:5], v[174:177], v[216:219], v[2:5]
	s_setprio 0
	s_barrier
	s_add_i32 s51, 0, 0x18000
	s_add_i32 s52, 0, 0x1c000
	v_add_u32_e32 v142, s51, v190
	v_add_u32_e32 v174, s52, v190
	ds_read_b128 v[130:133], v142
	ds_read_b128 v[134:137], v142 offset:1024
	ds_read_b128 v[138:141], v142 offset:2048
	ds_read_b128 v[142:145], v142 offset:3072
	ds_read_b128 v[146:149], v174
	ds_read_b128 v[150:153], v174 offset:1024
	ds_read_b128 v[170:173], v174 offset:2048
	ds_read_b128 v[174:177], v174 offset:3072
	s_add_u32 s34, s34, 0x100000
	s_addc_u32 s35, s35, 0
	s_mov_b32 m0, s37
	v_lshl_add_u64 v[226:227], s[34:35], 0, v[154:155]
	ds_read_b128 v[178:181], v194 offset:32768
	ds_read_b128 v[184:187], v194 offset:33792
	ds_read_b128 v[196:199], v194 offset:34816
	ds_read_b128 v[200:203], v194 offset:35840
	ds_read_b128 v[204:207], v194 offset:36864
	ds_read_b128 v[208:211], v194 offset:37888
	ds_read_b128 v[212:215], v194 offset:38912
	ds_read_b128 v[216:219], v194 offset:39936
	global_load_lds_dwordx4 v[226:227], off
	v_lshl_add_u64 v[226:227], s[34:35], 0, v[158:159]
	s_mov_b32 m0, s38
	s_nop 0
	global_load_lds_dwordx4 v[226:227], off
	s_waitcnt vmcnt(8)
	s_waitcnt lgkmcnt(0)
	s_barrier
	s_setprio 1
	s_waitcnt lgkmcnt(0)
	v_mfma_f32_16x16x32_bf16 v[126:129], v[130:133], v[178:181], v[126:129]
	v_mfma_f32_16x16x32_bf16 v[126:129], v[134:137], v[184:187], v[126:129]
	v_mfma_f32_16x16x32_bf16 v[122:125], v[138:141], v[178:181], v[122:125]
	v_mfma_f32_16x16x32_bf16 v[122:125], v[142:145], v[184:187], v[122:125]
	v_mfma_f32_16x16x32_bf16 v[110:113], v[130:133], v[196:199], v[110:113]
	v_mfma_f32_16x16x32_bf16 v[110:113], v[134:137], v[200:203], v[110:113]
	v_mfma_f32_16x16x32_bf16 v[106:109], v[138:141], v[196:199], v[106:109]
	v_mfma_f32_16x16x32_bf16 v[106:109], v[142:145], v[200:203], v[106:109]
	v_mfma_f32_16x16x32_bf16 v[94:97], v[130:133], v[204:207], v[94:97]
	v_mfma_f32_16x16x32_bf16 v[94:97], v[134:137], v[208:211], v[94:97]
	v_mfma_f32_16x16x32_bf16 v[90:93], v[138:141], v[204:207], v[90:93]
	v_mfma_f32_16x16x32_bf16 v[90:93], v[142:145], v[208:211], v[90:93]
	v_mfma_f32_16x16x32_bf16 v[78:81], v[130:133], v[212:215], v[78:81]
	v_mfma_f32_16x16x32_bf16 v[78:81], v[134:137], v[216:219], v[78:81]
	v_mfma_f32_16x16x32_bf16 v[74:77], v[138:141], v[212:215], v[74:77]
	v_mfma_f32_16x16x32_bf16 v[74:77], v[142:145], v[216:219], v[74:77]
	s_setprio 0
	s_setprio 1
	v_mfma_f32_16x16x32_bf16 v[118:121], v[146:149], v[178:181], v[118:121]
	v_mfma_f32_16x16x32_bf16 v[118:121], v[150:153], v[184:187], v[118:121]
	v_mfma_f32_16x16x32_bf16 v[114:117], v[170:173], v[178:181], v[114:117]
	v_mfma_f32_16x16x32_bf16 v[114:117], v[174:177], v[184:187], v[114:117]
	v_mfma_f32_16x16x32_bf16 v[102:105], v[146:149], v[196:199], v[102:105]
	v_mfma_f32_16x16x32_bf16 v[102:105], v[150:153], v[200:203], v[102:105]
	v_mfma_f32_16x16x32_bf16 v[98:101], v[170:173], v[196:199], v[98:101]
	v_mfma_f32_16x16x32_bf16 v[98:101], v[174:177], v[200:203], v[98:101]
	v_mfma_f32_16x16x32_bf16 v[86:89], v[146:149], v[204:207], v[86:89]
	v_mfma_f32_16x16x32_bf16 v[86:89], v[150:153], v[208:211], v[86:89]
	v_mfma_f32_16x16x32_bf16 v[82:85], v[170:173], v[204:207], v[82:85]
	v_mfma_f32_16x16x32_bf16 v[82:85], v[174:177], v[208:211], v[82:85]
	v_mfma_f32_16x16x32_bf16 v[70:73], v[146:149], v[212:215], v[70:73]
	v_mfma_f32_16x16x32_bf16 v[70:73], v[150:153], v[216:219], v[70:73]
	v_mfma_f32_16x16x32_bf16 v[66:69], v[170:173], v[212:215], v[66:69]
	v_mfma_f32_16x16x32_bf16 v[66:69], v[174:177], v[216:219], v[66:69]
	s_setprio 0
	s_barrier
; #define PG8_STAGE(bufoff, gbase, voff) do { _Pragma("unroll") for (int _i = 0; _i < 2; ++_i) \
;         __builtin_amdgcn_global_load_lds((const unsigned*)((const char*)(gbase) + (voff)[_i]), (LAS unsigned*)(lds + (bufoff) + ldsw + _i * 8192), 16, 0, 0); } while (0)
; #define PG8_LDA(dst, b, h) do { _Pragma("unroll") for (int m = 0; m < 4; ++m) _Pragma("unroll") for (int k = 0; k < 2; ++k) dst[m][k] = *(const LAS bf16x8*)(lds + PG8_SA(b, h) + aoff + m * 2048 + k * 1024); } while (0)
; #define PG8_WAIT_V(n) asm volatile("s_waitcnt vmcnt(" #n ")" ::: "memory")
; #define PG8_WAIT_L(n) asm volatile("s_waitcnt lgkmcnt(" #n ")" ::: "memory")
; #define PG8_BAR __builtin_amdgcn_s_barrier()
; #define PG8_SCHED __builtin_amdgcn_sched_barrier(0)
; template <class Epi, class Sched, class Ptrs, bool ALIGN_EPI, bool I8 = false>
; __device__ __forceinline__ void gemm_phase(LAS unsigned char* lds, const Ptrs& P, const Sched& S, const Epi& E) {
;     ...
;             PG8_LDA(At, 1, 1); PG8_STAGE(PG8_SB(1, 0), b3, voffB); PG8_STAGE(PG8_SB(1, 1), b3 + hstepB, voffB); PG8_STAGE(PG8_SA(1, 0), a3, voffA);
;             PG8_WAIT_V(8); PG8_WAIT_L(0); PG8_BAR; PG8_MMA(1, 0, At, B0); PG8_MMA(1, 1, At, B1); PG8_BAR; PG8_SCHED;
;         }
	s_add_i32 s34, s51, s3
	v_lshl_add_u64 v[188:189], v[188:189], 0, s[14:15]
	s_mov_b32 m0, s34
	ds_read_b128 v[178:181], v194 offset:49152
	ds_read_b128 v[184:187], v194 offset:50176
	ds_read_b128 v[196:199], v194 offset:51200
	ds_read_b128 v[200:203], v194 offset:52224
	ds_read_b128 v[204:207], v194 offset:53248
	ds_read_b128 v[208:211], v194 offset:54272
	ds_read_b128 v[212:215], v194 offset:55296
	ds_read_b128 v[216:219], v194 offset:56320
	global_load_lds_dwordx4 v[188:189], off
	s_add_i32 m0, s34, 0x2000
	s_add_u32 s30, s30, 0x100080
	v_lshl_add_u64 v[188:189], v[220:221], 0, s[14:15]
	s_addc_u32 s31, s31, 0
	s_add_i32 s34, s52, s3
	global_load_lds_dwordx4 v[188:189], off
	v_lshl_add_u64 v[188:189], s[30:31], 0, v[156:157]
	s_mov_b32 m0, s34
	s_nop 0
	global_load_lds_dwordx4 v[188:189], off
	v_lshl_add_u64 v[188:189], s[30:31], 0, v[160:161]
	s_add_i32 m0, s34, 0x2000
	s_nop 0
	global_load_lds_dwordx4 v[188:189], off
	v_lshl_add_u64 v[188:189], v[222:223], 0, s[14:15]
	s_mov_b32 m0, s40
	s_nop 0
	global_load_lds_dwordx4 v[188:189], off
	v_lshl_add_u64 v[188:189], v[224:225], 0, s[14:15]
	s_mov_b32 m0, s41
	s_nop 0
	global_load_lds_dwordx4 v[188:189], off
	s_waitcnt vmcnt(8)
	s_waitcnt lgkmcnt(0)
	s_barrier
	s_setprio 1
	s_waitcnt lgkmcnt(0)
	v_mfma_f32_16x16x32_bf16 v[62:65], v[130:133], v[178:181], v[62:65]
	v_mfma_f32_16x16x32_bf16 v[62:65], v[134:137], v[184:187], v[62:65]
	v_mfma_f32_16x16x32_bf16 v[58:61], v[138:141], v[178:181], v[58:61]
	v_mfma_f32_16x16x32_bf16 v[58:61], v[142:145], v[184:187], v[58:61]
	v_mfma_f32_16x16x32_bf16 v[46:49], v[130:133], v[196:199], v[46:49]
	v_mfma_f32_16x16x32_bf16 v[46:49], v[134:137], v[200:203], v[46:49]
	v_mfma_f32_16x16x32_bf16 v[42:45], v[138:141], v[196:199], v[42:45]
	v_mfma_f32_16x16x32_bf16 v[42:45], v[142:145], v[200:203], v[42:45]
	v_mfma_f32_16x16x32_bf16 v[30:33], v[130:133], v[204:207], v[30:33]
	v_mfma_f32_16x16x32_bf16 v[30:33], v[134:137], v[208:211], v[30:33]
	v_mfma_f32_16x16x32_bf16 v[26:29], v[138:141], v[204:207], v[26:29]
	v_mfma_f32_16x16x32_bf16 v[26:29], v[142:145], v[208:211], v[26:29]
	v_mfma_f32_16x16x32_bf16 v[14:17], v[130:133], v[212:215], v[14:17]
	v_mfma_f32_16x16x32_bf16 v[14:17], v[134:137], v[216:219], v[14:17]
	v_mfma_f32_16x16x32_bf16 v[10:13], v[138:141], v[212:215], v[10:13]
	v_mfma_f32_16x16x32_bf16 v[10:13], v[142:145], v[216:219], v[10:13]
	s_setprio 0
	s_setprio 1
	v_mfma_f32_16x16x32_bf16 v[54:57], v[146:149], v[178:181], v[54:57]
	v_mfma_f32_16x16x32_bf16 v[54:57], v[150:153], v[184:187], v[54:57]
	v_mfma_f32_16x16x32_bf16 v[50:53], v[170:173], v[178:181], v[50:53]
	v_mfma_f32_16x16x32_bf16 v[50:53], v[174:177], v[184:187], v[50:53]
	v_mfma_f32_16x16x32_bf16 v[38:41], v[146:149], v[196:199], v[38:41]
	v_mfma_f32_16x16x32_bf16 v[38:41], v[150:153], v[200:203], v[38:41]
	v_mfma_f32_16x16x32_bf16 v[34:37], v[170:173], v[196:199], v[34:37]
	v_mfma_f32_16x16x32_bf16 v[34:37], v[174:177], v[200:203], v[34:37]
	v_mfma_f32_16x16x32_bf16 v[22:25], v[146:149], v[204:207], v[22:25]
	v_mfma_f32_16x16x32_bf16 v[22:25], v[150:153], v[208:211], v[22:25]
	v_mfma_f32_16x16x32_bf16 v[18:21], v[170:173], v[204:207], v[18:21]
	v_mfma_f32_16x16x32_bf16 v[18:21], v[174:177], v[208:211], v[18:21]
	v_mfma_f32_16x16x32_bf16 v[6:9], v[146:149], v[212:215], v[6:9]
	v_mfma_f32_16x16x32_bf16 v[6:9], v[150:153], v[216:219], v[6:9]
	v_mfma_f32_16x16x32_bf16 v[2:5], v[170:173], v[212:215], v[2:5]
	v_mfma_f32_16x16x32_bf16 v[2:5], v[174:177], v[216:219], v[2:5]
	s_setprio 0
	s_barrier
	s_add_i32 s50, s50, 2
	s_add_u32 s28, s28, 0x100
	s_addc_u32 s29, s29, 0
	s_add_u32 s48, s48, 0x100
	s_addc_u32 s49, s49, 0
	s_cmp_gt_u32 s50, 61
	s_cbranch_scc0 .LBB0_1096
	s_and_b64 vcc, exec, s[16:17]
	s_cbranch_vccz .LBB0_1099
	s_barrier

; #define PG8_STAGE(bufoff, gbase, voff) do { _Pragma("unroll") for (int _i = 0; _i < 2; ++_i) \
;         __builtin_amdgcn_global_load_lds((const unsigned*)((const char*)(gbase) + (voff)[_i]), (LAS unsigned*)(lds + (bufoff) + ldsw + _i * 8192), 16, 0, 0); } while (0)
; #define PG8_LDA(dst, b, h) do { _Pragma("unroll") for (int m = 0; m < 4; ++m) _Pragma("unroll") for (int k = 0; k < 2; ++k) dst[m][k] = *(const LAS bf16x8*)(lds + PG8_SA(b, h) + aoff + m * 2048 + k * 1024); } while (0)
; #define PG8_LDB(dst, b, h) do { _Pragma("unroll") for (int n = 0; n < 2; ++n) _Pragma("unroll") for (int k = 0; k < 2; ++k) dst[n][k] = *(const LAS bf16x8*)(lds + PG8_SB(b, h) + boff + n * 2048 + k * 1024); } while (0)
; #define PG8_WAIT_V(n) asm volatile("s_waitcnt vmcnt(" #n ")" ::: "memory")
; #define PG8_WAIT_L(n) asm volatile("s_waitcnt lgkmcnt(" #n ")" ::: "memory")
; #define PG8_BAR __builtin_amdgcn_s_barrier()
; #define PG8_SCHED __builtin_amdgcn_sched_barrier(0)
; template <class Epi, class Sched, class Ptrs, bool ALIGN_EPI, bool I8 = false>
; __device__ __forceinline__ void gemm_phase(LAS unsigned char* lds, const Ptrs& P, const Sched& S, const Epi& E) {
;     ...
;             PG8_LDB(B0, 0, 0); PG8_LDB(B1, 0, 1); PG8_SCHED; PG8_LDA(At, 0, 0); PG8_STAGE(PG8_SA(1, 1), a1 + hstepA, voffA);
;             PG8_WAIT_V(8); PG8_WAIT_L(0); PG8_BAR; PG8_MMA(0, 0, At, B0); PG8_MMA(0, 1, At, B1); PG8_BAR; PG8_SCHED;
;             PG8_LDA(At, 0, 1); PG8_STAGE(PG8_SB(0, 0), b2, voffB); PG8_STAGE(PG8_SB(0, 1), b2 + hstepB, voffB); PG8_STAGE(PG8_SA(0, 0), a2, voffA);
;             PG8_WAIT_V(8); PG8_WAIT_L(0); PG8_BAR; PG8_MMA(1, 0, At, B0); PG8_MMA(1, 1, At, B1); PG8_BAR; PG8_SCHED;
.LBB0_1191:
	v_add_u32_e32 v164, s41, v150
	v_add_u32_e32 v180, s42, v150
	s_add_u32 s26, s14, s8
	ds_read_b128 v[152:155], v164
	ds_read_b128 v[156:159], v164 offset:1024
	ds_read_b128 v[160:163], v164 offset:2048
	ds_read_b128 v[164:167], v164 offset:3072
	ds_read_b128 v[168:171], v180
	ds_read_b128 v[172:175], v180 offset:1024
	ds_read_b128 v[176:179], v180 offset:2048
	ds_read_b128 v[184:187], v180 offset:3072
	s_addc_u32 s27, s15, s9
	s_add_u32 s26, s26, 0x100
	s_addc_u32 s27, s27, 0
	s_add_u32 s47, s44, s8
	s_addc_u32 s48, s45, s9
	s_cmpk_eq_i32 s8, 0x1f00
	s_cselect_b32 s29, s19, s27
	s_cselect_b32 s28, s21, s26
	s_cselect_b32 s27, s23, s48
	s_cselect_b32 s26, s22, s47
	v_lshl_add_u64 v[180:181], v[146:147], 0, s[8:9]
	s_add_i32 m0, s34, 0xc000
	ds_read_b128 v[188:191], v151
	ds_read_b128 v[192:195], v151 offset:1024
	ds_read_b128 v[198:201], v151 offset:2048
	ds_read_b128 v[202:205], v151 offset:3072
	ds_read_b128 v[206:209], v151 offset:4096
	ds_read_b128 v[210:213], v151 offset:5120
	ds_read_b128 v[214:217], v151 offset:6144
	ds_read_b128 v[218:221], v151 offset:7168
	global_load_lds_dwordx4 v[180:181], off
	v_lshl_add_u64 v[180:181], v[148:149], 0, s[8:9]
	s_add_i32 m0, s34, 0xe000
	s_nop 0
	global_load_lds_dwordx4 v[180:181], off
	s_waitcnt vmcnt(8)
	s_waitcnt lgkmcnt(0)
	s_barrier
	s_setprio 1
	s_waitcnt lgkmcnt(0)
	v_mfma_f32_16x16x32_bf16 v[126:129], v[152:155], v[188:191], v[126:129]
	v_mfma_f32_16x16x32_bf16 v[126:129], v[156:159], v[192:195], v[126:129]
	v_mfma_f32_16x16x32_bf16 v[122:125], v[160:163], v[188:191], v[122:125]
	v_mfma_f32_16x16x32_bf16 v[122:125], v[164:167], v[192:195], v[122:125]
	v_mfma_f32_16x16x32_bf16 v[118:121], v[152:155], v[198:201], v[118:121]
	v_mfma_f32_16x16x32_bf16 v[118:121], v[156:159], v[202:205], v[118:121]
	v_mfma_f32_16x16x32_bf16 v[110:113], v[160:163], v[198:201], v[110:113]
	v_mfma_f32_16x16x32_bf16 v[110:113], v[164:167], v[202:205], v[110:113]
	v_mfma_f32_16x16x32_bf16 v[102:105], v[152:155], v[206:209], v[102:105]
	v_mfma_f32_16x16x32_bf16 v[102:105], v[156:159], v[210:213], v[102:105]
	v_mfma_f32_16x16x32_bf16 v[94:97], v[160:163], v[206:209], v[94:97]
	v_mfma_f32_16x16x32_bf16 v[94:97], v[164:167], v[210:213], v[94:97]
	v_mfma_f32_16x16x32_bf16 v[86:89], v[152:155], v[214:217], v[86:89]
	v_mfma_f32_16x16x32_bf16 v[86:89], v[156:159], v[218:221], v[86:89]
	v_mfma_f32_16x16x32_bf16 v[78:81], v[160:163], v[214:217], v[78:81]
	v_mfma_f32_16x16x32_bf16 v[78:81], v[164:167], v[218:221], v[78:81]
	s_setprio 0
	s_setprio 1
	v_mfma_f32_16x16x32_bf16 v[114:117], v[168:171], v[188:191], v[114:117]
	v_mfma_f32_16x16x32_bf16 v[114:117], v[172:175], v[192:195], v[114:117]
	v_mfma_f32_16x16x32_bf16 v[106:109], v[176:179], v[188:191], v[106:109]
	v_mfma_f32_16x16x32_bf16 v[106:109], v[184:187], v[192:195], v[106:109]
	v_mfma_f32_16x16x32_bf16 v[98:101], v[168:171], v[198:201], v[98:101]
	v_mfma_f32_16x16x32_bf16 v[98:101], v[172:175], v[202:205], v[98:101]
	v_mfma_f32_16x16x32_bf16 v[90:93], v[176:179], v[198:201], v[90:93]
	v_mfma_f32_16x16x32_bf16 v[90:93], v[184:187], v[202:205], v[90:93]
	v_mfma_f32_16x16x32_bf16 v[82:85], v[168:171], v[206:209], v[82:85]
	v_mfma_f32_16x16x32_bf16 v[82:85], v[172:175], v[210:213], v[82:85]
	v_mfma_f32_16x16x32_bf16 v[74:77], v[176:179], v[206:209], v[74:77]
	v_mfma_f32_16x16x32_bf16 v[74:77], v[184:187], v[210:213], v[74:77]
	v_mfma_f32_16x16x32_bf16 v[70:73], v[168:171], v[214:217], v[70:73]
	v_mfma_f32_16x16x32_bf16 v[70:73], v[172:175], v[218:221], v[70:73]
	v_mfma_f32_16x16x32_bf16 v[66:69], v[176:179], v[214:217], v[66:69]
	v_mfma_f32_16x16x32_bf16 v[66:69], v[184:187], v[218:221], v[66:69]
	s_setprio 0
	s_barrier
	s_add_i32 s47, s41, s33
	v_lshl_add_u64 v[180:181], s[26:27], 0, v[132:133]
	s_mov_b32 m0, s47
	ds_read_b128 v[188:191], v151 offset:16384
	ds_read_b128 v[192:195], v151 offset:17408
	ds_read_b128 v[198:201], v151 offset:18432
	ds_read_b128 v[202:205], v151 offset:19456
	ds_read_b128 v[206:209], v151 offset:20480
	ds_read_b128 v[210:213], v151 offset:21504
	ds_read_b128 v[214:217], v151 offset:22528
	ds_read_b128 v[218:221], v151 offset:23552
	global_load_lds_dwordx4 v[180:181], off
	s_add_i32 m0, s47, 0x2000
	s_add_u32 s48, s26, 0x100000
	v_lshl_add_u64 v[222:223], s[26:27], 0, v[136:137]
	s_addc_u32 s49, s27, 0
	s_add_i32 s47, s42, s33
	global_load_lds_dwordx4 v[222:223], off
	v_lshl_add_u64 v[224:225], s[48:49], 0, v[132:133]
	s_mov_b32 m0, s47
	v_lshl_add_u64 v[226:227], s[28:29], 0, v[134:135]
	global_load_lds_dwordx4 v[224:225], off
	v_lshl_add_u64 v[224:225], s[48:49], 0, v[136:137]
	s_add_i32 m0, s47, 0x2000
	s_nop 0
	global_load_lds_dwordx4 v[224:225], off
	v_lshl_add_u64 v[224:225], s[28:29], 0, v[130:131]
	s_mov_b32 m0, s34
	s_nop 0
	global_load_lds_dwordx4 v[224:225], off
	s_mov_b32 m0, s35
	s_nop 0
	global_load_lds_dwordx4 v[226:227], off
	s_waitcnt vmcnt(8)
	s_waitcnt lgkmcnt(0)
	s_barrier
; #define PG8_STAGE(bufoff, gbase, voff) do { _Pragma("unroll") for (int _i = 0; _i < 2; ++_i) \
;         __builtin_amdgcn_global_load_lds((const unsigned*)((const char*)(gbase) + (voff)[_i]), (LAS unsigned*)(lds + (bufoff) + ldsw + _i * 8192), 16, 0, 0); } while (0)
; #define PG8_LDA(dst, b, h) do { _Pragma("unroll") for (int m = 0; m < 4; ++m) _Pragma("unroll") for (int k = 0; k < 2; ++k) dst[m][k] = *(const LAS bf16x8*)(lds + PG8_SA(b, h) + aoff + m * 2048 + k * 1024); } while (0)
; #define PG8_LDB(dst, b, h) do { _Pragma("unroll") for (int n = 0; n < 2; ++n) _Pragma("unroll") for (int k = 0; k < 2; ++k) dst[n][k] = *(const LAS bf16x8*)(lds + PG8_SB(b, h) + boff + n * 2048 + k * 1024); } while (0)
; #define PG8_WAIT_V(n) asm volatile("s_waitcnt vmcnt(" #n ")" ::: "memory")
; #define PG8_WAIT_L(n) asm volatile("s_waitcnt lgkmcnt(" #n ")" ::: "memory")
; #define PG8_BAR __builtin_amdgcn_s_barrier()
; #define PG8_SCHED __builtin_amdgcn_sched_barrier(0)
; template <class Epi, class Sched, class Ptrs, bool ALIGN_EPI, bool I8 = false>
; __device__ __forceinline__ void gemm_phase(LAS unsigned char* lds, const Ptrs& P, const Sched& S, const Epi& E) {
;     ...
;             PG8_LDB(B0, 0, 0); PG8_LDB(B1, 0, 1); PG8_SCHED; PG8_LDA(At, 0, 0); PG8_STAGE(PG8_SA(1, 1), a1 + hstepA, voffA);
;             PG8_WAIT_V(8); PG8_WAIT_L(0); PG8_BAR; PG8_MMA(0, 0, At, B0); PG8_MMA(0, 1, At, B1); PG8_BAR; PG8_SCHED;
;             PG8_LDA(At, 0, 1); PG8_STAGE(PG8_SB(0, 0), b2, voffB); PG8_STAGE(PG8_SB(0, 1), b2 + hstepB, voffB); PG8_STAGE(PG8_SA(0, 0), a2, voffA);
;             PG8_WAIT_V(8); PG8_WAIT_L(0); PG8_BAR; PG8_MMA(1, 0, At, B0); PG8_MMA(1, 1, At, B1); PG8_BAR; PG8_SCHED;
;             PG8_LDB(B0, 1, 0); PG8_LDB(B1, 1, 1); PG8_SCHED; PG8_LDA(At, 1, 0); PG8_STAGE(PG8_SA(0, 1), a2 + hstepA, voffA);
;             PG8_WAIT_V(8); PG8_WAIT_L(0); PG8_BAR; PG8_MMA(0, 0, At, B0); PG8_MMA(0, 1, At, B1); PG8_BAR; PG8_SCHED;
;             PG8_LDA(At, 1, 1); PG8_STAGE(PG8_SB(1, 0), b3, voffB); PG8_STAGE(PG8_SB(1, 1), b3 + hstepB, voffB); PG8_STAGE(PG8_SA(1, 0), a3, voffA);
;             PG8_WAIT_V(8); PG8_WAIT_L(0); PG8_BAR; PG8_MMA(1, 0, At, B0); PG8_MMA(1, 1, At, B1); PG8_BAR; PG8_SCHED;
	s_setprio 1
	s_waitcnt lgkmcnt(0)
	v_mfma_f32_16x16x32_bf16 v[62:65], v[152:155], v[188:191], v[62:65]
	v_mfma_f32_16x16x32_bf16 v[62:65], v[156:159], v[192:195], v[62:65]
	v_mfma_f32_16x16x32_bf16 v[58:61], v[160:163], v[188:191], v[58:61]
	v_mfma_f32_16x16x32_bf16 v[58:61], v[164:167], v[192:195], v[58:61]
	v_mfma_f32_16x16x32_bf16 v[54:57], v[152:155], v[198:201], v[54:57]
	v_mfma_f32_16x16x32_bf16 v[54:57], v[156:159], v[202:205], v[54:57]
	v_mfma_f32_16x16x32_bf16 v[46:49], v[160:163], v[198:201], v[46:49]
	v_mfma_f32_16x16x32_bf16 v[46:49], v[164:167], v[202:205], v[46:49]
	v_mfma_f32_16x16x32_bf16 v[38:41], v[152:155], v[206:209], v[38:41]
	v_mfma_f32_16x16x32_bf16 v[38:41], v[156:159], v[210:213], v[38:41]
	v_mfma_f32_16x16x32_bf16 v[30:33], v[160:163], v[206:209], v[30:33]
	v_mfma_f32_16x16x32_bf16 v[30:33], v[164:167], v[210:213], v[30:33]
	v_mfma_f32_16x16x32_bf16 v[22:25], v[152:155], v[214:217], v[22:25]
	v_mfma_f32_16x16x32_bf16 v[22:25], v[156:159], v[218:221], v[22:25]
	v_mfma_f32_16x16x32_bf16 v[14:17], v[160:163], v[214:217], v[14:17]
	v_mfma_f32_16x16x32_bf16 v[14:17], v[164:167], v[218:221], v[14:17]
	s_setprio 0
	s_setprio 1
	v_mfma_f32_16x16x32_bf16 v[50:53], v[168:171], v[188:191], v[50:53]
	v_mfma_f32_16x16x32_bf16 v[50:53], v[172:175], v[192:195], v[50:53]
	v_mfma_f32_16x16x32_bf16 v[42:45], v[176:179], v[188:191], v[42:45]
	v_mfma_f32_16x16x32_bf16 v[42:45], v[184:187], v[192:195], v[42:45]
	v_mfma_f32_16x16x32_bf16 v[34:37], v[168:171], v[198:201], v[34:37]
	v_mfma_f32_16x16x32_bf16 v[34:37], v[172:175], v[202:205], v[34:37]
	v_mfma_f32_16x16x32_bf16 v[26:29], v[176:179], v[198:201], v[26:29]
	v_mfma_f32_16x16x32_bf16 v[26:29], v[184:187], v[202:205], v[26:29]
	v_mfma_f32_16x16x32_bf16 v[18:21], v[168:171], v[206:209], v[18:21]
	v_mfma_f32_16x16x32_bf16 v[18:21], v[172:175], v[210:213], v[18:21]
	v_mfma_f32_16x16x32_bf16 v[10:13], v[176:179], v[206:209], v[10:13]
	v_mfma_f32_16x16x32_bf16 v[10:13], v[184:187], v[210:213], v[10:13]
	v_mfma_f32_16x16x32_bf16 v[6:9], v[168:171], v[214:217], v[6:9]
	v_mfma_f32_16x16x32_bf16 v[6:9], v[172:175], v[218:221], v[6:9]
	v_mfma_f32_16x16x32_bf16 v[2:5], v[176:179], v[214:217], v[2:5]
	v_mfma_f32_16x16x32_bf16 v[2:5], v[184:187], v[218:221], v[2:5]
	s_setprio 0
	s_barrier
	s_add_i32 s47, 0, 0x18000
	s_add_i32 s48, 0, 0x1c000
	v_add_u32_e32 v164, s47, v150
	v_add_u32_e32 v184, s48, v150
	ds_read_b128 v[152:155], v164
	ds_read_b128 v[156:159], v164 offset:1024
	ds_read_b128 v[160:163], v164 offset:2048
	ds_read_b128 v[164:167], v164 offset:3072
	ds_read_b128 v[168:171], v184
	ds_read_b128 v[172:175], v184 offset:1024
	ds_read_b128 v[176:179], v184 offset:2048
	ds_read_b128 v[184:187], v184 offset:3072
	s_add_u32 s28, s28, 0x100000
	s_addc_u32 s29, s29, 0
	s_mov_b32 m0, s36
	v_lshl_add_u64 v[228:229], s[28:29], 0, v[130:131]
	ds_read_b128 v[188:191], v151 offset:32768
	ds_read_b128 v[192:195], v151 offset:33792
	ds_read_b128 v[198:201], v151 offset:34816
	ds_read_b128 v[202:205], v151 offset:35840
	ds_read_b128 v[206:209], v151 offset:36864
	ds_read_b128 v[210:213], v151 offset:37888
	ds_read_b128 v[214:217], v151 offset:38912
	ds_read_b128 v[218:221], v151 offset:39936
	global_load_lds_dwordx4 v[228:229], off
	v_lshl_add_u64 v[228:229], s[28:29], 0, v[134:135]
	s_mov_b32 m0, s37
	s_nop 0
	global_load_lds_dwordx4 v[228:229], off
	s_waitcnt vmcnt(8)
	s_waitcnt lgkmcnt(0)
	s_barrier
	s_setprio 1
	s_waitcnt lgkmcnt(0)
	v_mfma_f32_16x16x32_bf16 v[126:129], v[152:155], v[188:191], v[126:129]
	v_mfma_f32_16x16x32_bf16 v[126:129], v[156:159], v[192:195], v[126:129]
	v_mfma_f32_16x16x32_bf16 v[122:125], v[160:163], v[188:191], v[122:125]
	v_mfma_f32_16x16x32_bf16 v[122:125], v[164:167], v[192:195], v[122:125]
	v_mfma_f32_16x16x32_bf16 v[118:121], v[152:155], v[198:201], v[118:121]
	v_mfma_f32_16x16x32_bf16 v[118:121], v[156:159], v[202:205], v[118:121]
	v_mfma_f32_16x16x32_bf16 v[110:113], v[160:163], v[198:201], v[110:113]
	v_mfma_f32_16x16x32_bf16 v[110:113], v[164:167], v[202:205], v[110:113]
	v_mfma_f32_16x16x32_bf16 v[102:105], v[152:155], v[206:209], v[102:105]
	v_mfma_f32_16x16x32_bf16 v[102:105], v[156:159], v[210:213], v[102:105]
	v_mfma_f32_16x16x32_bf16 v[94:97], v[160:163], v[206:209], v[94:97]
	v_mfma_f32_16x16x32_bf16 v[94:97], v[164:167], v[210:213], v[94:97]
	v_mfma_f32_16x16x32_bf16 v[86:89], v[152:155], v[214:217], v[86:89]
	v_mfma_f32_16x16x32_bf16 v[86:89], v[156:159], v[218:221], v[86:89]
	v_mfma_f32_16x16x32_bf16 v[78:81], v[160:163], v[214:217], v[78:81]
	v_mfma_f32_16x16x32_bf16 v[78:81], v[164:167], v[218:221], v[78:81]
	s_setprio 0
	s_setprio 1
	v_mfma_f32_16x16x32_bf16 v[114:117], v[168:171], v[188:191], v[114:117]
	v_mfma_f32_16x16x32_bf16 v[114:117], v[172:175], v[192:195], v[114:117]
	v_mfma_f32_16x16x32_bf16 v[106:109], v[176:179], v[188:191], v[106:109]
	v_mfma_f32_16x16x32_bf16 v[106:109], v[184:187], v[192:195], v[106:109]
	v_mfma_f32_16x16x32_bf16 v[98:101], v[168:171], v[198:201], v[98:101]
	v_mfma_f32_16x16x32_bf16 v[98:101], v[172:175], v[202:205], v[98:101]
	v_mfma_f32_16x16x32_bf16 v[90:93], v[176:179], v[198:201], v[90:93]
	v_mfma_f32_16x16x32_bf16 v[90:93], v[184:187], v[202:205], v[90:93]
	v_mfma_f32_16x16x32_bf16 v[82:85], v[168:171], v[206:209], v[82:85]
	v_mfma_f32_16x16x32_bf16 v[82:85], v[172:175], v[210:213], v[82:85]
	v_mfma_f32_16x16x32_bf16 v[74:77], v[176:179], v[206:209], v[74:77]
	v_mfma_f32_16x16x32_bf16 v[74:77], v[184:187], v[210:213], v[74:77]
	v_mfma_f32_16x16x32_bf16 v[70:73], v[168:171], v[214:217], v[70:73]
	v_mfma_f32_16x16x32_bf16 v[70:73], v[172:175], v[218:221], v[70:73]
	v_mfma_f32_16x16x32_bf16 v[66:69], v[176:179], v[214:217], v[66:69]
	v_mfma_f32_16x16x32_bf16 v[66:69], v[184:187], v[218:221], v[66:69]
	s_setprio 0
	s_barrier
; #define PG8_STAGE(bufoff, gbase, voff) do { _Pragma("unroll") for (int _i = 0; _i < 2; ++_i) \
;         __builtin_amdgcn_global_load_lds((const unsigned*)((const char*)(gbase) + (voff)[_i]), (LAS unsigned*)(lds + (bufoff) + ldsw + _i * 8192), 16, 0, 0); } while (0)
; #define PG8_LDA(dst, b, h) do { _Pragma("unroll") for (int m = 0; m < 4; ++m) _Pragma("unroll") for (int k = 0; k < 2; ++k) dst[m][k] = *(const LAS bf16x8*)(lds + PG8_SA(b, h) + aoff + m * 2048 + k * 1024); } while (0)
; #define PG8_LDB(dst, b, h) do { _Pragma("unroll") for (int n = 0; n < 2; ++n) _Pragma("unroll") for (int k = 0; k < 2; ++k) dst[n][k] = *(const LAS bf16x8*)(lds + PG8_SB(b, h) + boff + n * 2048 + k * 1024); } while (0)
; #define PG8_WAIT_V(n) asm volatile("s_waitcnt vmcnt(" #n ")" ::: "memory")
; #define PG8_WAIT_L(n) asm volatile("s_waitcnt lgkmcnt(" #n ")" ::: "memory")
; #define PG8_BAR __builtin_amdgcn_s_barrier()
; #define PG8_SCHED __builtin_amdgcn_sched_barrier(0)
; template <class Epi, class Sched, class Ptrs, bool ALIGN_EPI, bool I8 = false>
; __device__ __forceinline__ void gemm_phase(LAS unsigned char* lds, const Ptrs& P, const Sched& S, const Epi& E) {
;     ...
;             PG8_LDB(B0, 1, 0); PG8_LDB(B1, 1, 1); PG8_SCHED; PG8_LDA(At, 1, 0); PG8_STAGE(PG8_SA(0, 1), a2 + hstepA, voffA);
;             PG8_WAIT_V(8); PG8_WAIT_L(0); PG8_BAR; PG8_MMA(0, 0, At, B0); PG8_MMA(0, 1, At, B1); PG8_BAR; PG8_SCHED;
;             PG8_LDA(At, 1, 1); PG8_STAGE(PG8_SB(1, 0), b3, voffB); PG8_STAGE(PG8_SB(1, 1), b3 + hstepB, voffB); PG8_STAGE(PG8_SA(1, 0), a3, voffA);
;             PG8_WAIT_V(8); PG8_WAIT_L(0); PG8_BAR; PG8_MMA(1, 0, At, B0); PG8_MMA(1, 1, At, B1); PG8_BAR; PG8_SCHED;
;     ...
;         for (int a = 0; a < 2; ++a)
; #pragma unroll
;             for (int b = 0; b < 2; ++b)
; #pragma unroll
;                 for (int m = 0; m < 4; ++m)
; #pragma unroll
;                     for (int n = 0; n < 2; ++n) acc[a][b][m][n] = acc_t{};
;         cur = nxt; cA = nA; cB = nB; ++ui;
	s_add_i32 s28, s47, s33
	v_lshl_add_u64 v[180:181], v[180:181], 0, s[16:17]
	s_mov_b32 m0, s28
	ds_read_b128 v[188:191], v151 offset:49152
	ds_read_b128 v[192:195], v151 offset:50176
	ds_read_b128 v[198:201], v151 offset:51200
	ds_read_b128 v[202:205], v151 offset:52224
	ds_read_b128 v[206:209], v151 offset:53248
	ds_read_b128 v[210:213], v151 offset:54272
	ds_read_b128 v[214:217], v151 offset:55296
	ds_read_b128 v[218:221], v151 offset:56320
	global_load_lds_dwordx4 v[180:181], off
	s_add_i32 m0, s28, 0x2000
	s_add_u32 s26, s26, 0x100080
	v_lshl_add_u64 v[180:181], v[222:223], 0, s[16:17]
	s_addc_u32 s27, s27, 0
	s_add_i32 s28, s48, s33
	global_load_lds_dwordx4 v[180:181], off
	v_lshl_add_u64 v[180:181], s[26:27], 0, v[132:133]
	s_mov_b32 m0, s28
	s_nop 0
	global_load_lds_dwordx4 v[180:181], off
	v_lshl_add_u64 v[180:181], s[26:27], 0, v[136:137]
	s_add_i32 m0, s28, 0x2000
	s_nop 0
	global_load_lds_dwordx4 v[180:181], off
	v_lshl_add_u64 v[180:181], v[224:225], 0, s[16:17]
	s_mov_b32 m0, s39
	s_nop 0
	global_load_lds_dwordx4 v[180:181], off
	v_lshl_add_u64 v[180:181], v[226:227], 0, s[16:17]
	s_mov_b32 m0, s40
	s_nop 0
	global_load_lds_dwordx4 v[180:181], off
	s_waitcnt vmcnt(8)
	s_waitcnt lgkmcnt(0)
	s_barrier
	s_setprio 1
	s_waitcnt lgkmcnt(0)
	v_mfma_f32_16x16x32_bf16 v[62:65], v[152:155], v[188:191], v[62:65]
	v_mfma_f32_16x16x32_bf16 v[62:65], v[156:159], v[192:195], v[62:65]
	v_mfma_f32_16x16x32_bf16 v[58:61], v[160:163], v[188:191], v[58:61]
	v_mfma_f32_16x16x32_bf16 v[58:61], v[164:167], v[192:195], v[58:61]
	v_mfma_f32_16x16x32_bf16 v[54:57], v[152:155], v[198:201], v[54:57]
	v_mfma_f32_16x16x32_bf16 v[54:57], v[156:159], v[202:205], v[54:57]
	v_mfma_f32_16x16x32_bf16 v[46:49], v[160:163], v[198:201], v[46:49]
	v_mfma_f32_16x16x32_bf16 v[46:49], v[164:167], v[202:205], v[46:49]
	v_mfma_f32_16x16x32_bf16 v[38:41], v[152:155], v[206:209], v[38:41]
	v_mfma_f32_16x16x32_bf16 v[38:41], v[156:159], v[210:213], v[38:41]
	v_mfma_f32_16x16x32_bf16 v[30:33], v[160:163], v[206:209], v[30:33]
	v_mfma_f32_16x16x32_bf16 v[30:33], v[164:167], v[210:213], v[30:33]
	v_mfma_f32_16x16x32_bf16 v[22:25], v[152:155], v[214:217], v[22:25]
	v_mfma_f32_16x16x32_bf16 v[22:25], v[156:159], v[218:221], v[22:25]
	v_mfma_f32_16x16x32_bf16 v[14:17], v[160:163], v[214:217], v[14:17]
	v_mfma_f32_16x16x32_bf16 v[14:17], v[164:167], v[218:221], v[14:17]
	s_setprio 0
	s_setprio 1
	v_mfma_f32_16x16x32_bf16 v[50:53], v[168:171], v[188:191], v[50:53]
	v_mfma_f32_16x16x32_bf16 v[50:53], v[172:175], v[192:195], v[50:53]
	v_mfma_f32_16x16x32_bf16 v[42:45], v[176:179], v[188:191], v[42:45]
	v_mfma_f32_16x16x32_bf16 v[42:45], v[184:187], v[192:195], v[42:45]
	v_mfma_f32_16x16x32_bf16 v[34:37], v[168:171], v[198:201], v[34:37]
	v_mfma_f32_16x16x32_bf16 v[34:37], v[172:175], v[202:205], v[34:37]
	v_mfma_f32_16x16x32_bf16 v[26:29], v[176:179], v[198:201], v[26:29]
	v_mfma_f32_16x16x32_bf16 v[26:29], v[184:187], v[202:205], v[26:29]
	v_mfma_f32_16x16x32_bf16 v[18:21], v[168:171], v[206:209], v[18:21]
	v_mfma_f32_16x16x32_bf16 v[18:21], v[172:175], v[210:213], v[18:21]
	v_mfma_f32_16x16x32_bf16 v[10:13], v[176:179], v[206:209], v[10:13]
	v_mfma_f32_16x16x32_bf16 v[10:13], v[184:187], v[210:213], v[10:13]
	v_mfma_f32_16x16x32_bf16 v[6:9], v[168:171], v[214:217], v[6:9]
	v_mfma_f32_16x16x32_bf16 v[6:9], v[172:175], v[218:221], v[6:9]
	v_mfma_f32_16x16x32_bf16 v[2:5], v[176:179], v[214:217], v[2:5]
	v_mfma_f32_16x16x32_bf16 v[2:5], v[184:187], v[218:221], v[2:5]
	s_setprio 0
	s_barrier
	s_add_i32 s46, s46, 2
	s_add_u32 s8, s8, 0x100
	s_addc_u32 s9, s9, 0
	s_cmp_gt_u32 s46, 61
	s_cbranch_scc0 .LBB0_1191
	s_add_u32 s8, s44, 0xffffff00
	s_addc_u32 s9, s45, -1
	s_and_b64 vcc, exec, s[6:7]
	s_cbranch_vccnz .LBB0_1194
	v_mov_b32_e32 v2, 0
	s_mov_b32 s13, s18
	s_mov_b32 s12, s20
	s_mov_b64 s[14:15], s[24:25]
	s_mov_b32 s38, s43
	v_mov_b32_e32 v3, v2
	v_mov_b32_e32 v4, v2
	v_mov_b32_e32 v5, v2
	v_mov_b32_e32 v6, v2
	v_mov_b32_e32 v7, v2
	v_mov_b32_e32 v8, v2
	v_mov_b32_e32 v9, v2
	v_mov_b32_e32 v10, v2
	v_mov_b32_e32 v11, v2
	v_mov_b32_e32 v12, v2
	v_mov_b32_e32 v13, v2
	v_mov_b32_e32 v18, v2
	v_mov_b32_e32 v19, v2
	v_mov_b32_e32 v20, v2
	v_mov_b32_e32 v21, v2
	v_mov_b32_e32 v26, v2
	v_mov_b32_e32 v27, v2
	v_mov_b32_e32 v28, v2
	v_mov_b32_e32 v29, v2
	v_mov_b32_e32 v34, v2
	v_mov_b32_e32 v35, v2
	v_mov_b32_e32 v36, v2
	v_mov_b32_e32 v37, v2
	v_mov_b32_e32 v42, v2
	v_mov_b32_e32 v43, v2
	v_mov_b32_e32 v44, v2
	v_mov_b32_e32 v45, v2
	v_mov_b32_e32 v50, v2
	v_mov_b32_e32 v51, v2
	v_mov_b32_e32 v52, v2
	v_mov_b32_e32 v53, v2
	v_mov_b32_e32 v14, v2
	v_mov_b32_e32 v15, v2
	v_mov_b32_e32 v16, v2
	v_mov_b32_e32 v17, v2
	v_mov_b32_e32 v22, v2
	v_mov_b32_e32 v23, v2
	v_mov_b32_e32 v24, v2
	v_mov_b32_e32 v25, v2
	v_mov_b32_e32 v30, v2
	v_mov_b32_e32 v31, v2
	v_mov_b32_e32 v32, v2
	v_mov_b32_e32 v33, v2
	v_mov_b32_e32 v38, v2
	v_mov_b32_e32 v39, v2
	v_mov_b32_e32 v40, v2
	v_mov_b32_e32 v41, v2
	v_mov_b32_e32 v46, v2
	v_mov_b32_e32 v47, v2
	v_mov_b32_e32 v48, v2
	v_mov_b32_e32 v49, v2
	v_mov_b32_e32 v54, v2
	v_mov_b32_e32 v55, v2
	v_mov_b32_e32 v56, v2
	v_mov_b32_e32 v57, v2
	v_mov_b32_e32 v58, v2
	v_mov_b32_e32 v59, v2
	v_mov_b32_e32 v60, v2
	v_mov_b32_e32 v61, v2
	v_mov_b32_e32 v62, v2
	v_mov_b32_e32 v63, v2
	v_mov_b32_e32 v64, v2
	v_mov_b32_e32 v65, v2
	v_mov_b32_e32 v66, v2
	v_mov_b32_e32 v67, v2
	v_mov_b32_e32 v68, v2
	v_mov_b32_e32 v69, v2
	v_mov_b32_e32 v70, v2
	v_mov_b32_e32 v71, v2
	v_mov_b32_e32 v72, v2
	v_mov_b32_e32 v73, v2
	v_mov_b32_e32 v74, v2
	v_mov_b32_e32 v75, v2
	v_mov_b32_e32 v76, v2
	v_mov_b32_e32 v77, v2
	v_mov_b32_e32 v82, v2
	v_mov_b32_e32 v83, v2
	v_mov_b32_e32 v84, v2
	v_mov_b32_e32 v85, v2
	v_mov_b32_e32 v90, v2
	v_mov_b32_e32 v91, v2
	v_mov_b32_e32 v92, v2
	v_mov_b32_e32 v93, v2
	v_mov_b32_e32 v98, v2
	v_mov_b32_e32 v99, v2
	v_mov_b32_e32 v100, v2
	v_mov_b32_e32 v101, v2
	v_mov_b32_e32 v106, v2
	v_mov_b32_e32 v107, v2
	v_mov_b32_e32 v108, v2
	v_mov_b32_e32 v109, v2
	v_mov_b32_e32 v114, v2
	v_mov_b32_e32 v115, v2
	v_mov_b32_e32 v116, v2
	v_mov_b32_e32 v117, v2
	v_mov_b32_e32 v78, v2
	v_mov_b32_e32 v79, v2
	v_mov_b32_e32 v80, v2
	v_mov_b32_e32 v81, v2
	v_mov_b32_e32 v86, v2
	v_mov_b32_e32 v87, v2
	v_mov_b32_e32 v88, v2
	v_mov_b32_e32 v89, v2
	v_mov_b32_e32 v94, v2
	v_mov_b32_e32 v95, v2
	v_mov_b32_e32 v96, v2
	v_mov_b32_e32 v97, v2
	v_mov_b32_e32 v102, v2
	v_mov_b32_e32 v103, v2
	v_mov_b32_e32 v104, v2
	v_mov_b32_e32 v105, v2
	v_mov_b32_e32 v110, v2
	v_mov_b32_e32 v111, v2
	v_mov_b32_e32 v112, v2
	v_mov_b32_e32 v113, v2
	v_mov_b32_e32 v118, v2
	v_mov_b32_e32 v119, v2
	v_mov_b32_e32 v120, v2
	v_mov_b32_e32 v121, v2
	v_mov_b32_e32 v122, v2
	v_mov_b32_e32 v123, v2
	v_mov_b32_e32 v124, v2
	v_mov_b32_e32 v125, v2
	v_mov_b32_e32 v126, v2
	v_mov_b32_e32 v127, v2
	v_mov_b32_e32 v128, v2
	v_mov_b32_e32 v129, v2
	s_andn2_b64 vcc, exec, s[4:5]
	s_cbranch_vccnz .LBB0_1195
	s_branch .LBB0_1196

; #define PG8_STAGE(bufoff, gbase, voff) do { _Pragma("unroll") for (int _i = 0; _i < 2; ++_i) \
;         __builtin_amdgcn_global_load_lds((const unsigned*)((const char*)(gbase) + (voff)[_i]), (LAS unsigned*)(lds + (bufoff) + ldsw + _i * 8192), 16, 0, 0); } while (0)
; #define PG8_LDA(dst, b, h) do { _Pragma("unroll") for (int m = 0; m < 4; ++m) _Pragma("unroll") for (int k = 0; k < 2; ++k) dst[m][k] = *(const LAS bf16x8*)(lds + PG8_SA(b, h) + aoff + m * 2048 + k * 1024); } while (0)
; #define PG8_LDB(dst, b, h) do { _Pragma("unroll") for (int n = 0; n < 2; ++n) _Pragma("unroll") for (int k = 0; k < 2; ++k) dst[n][k] = *(const LAS bf16x8*)(lds + PG8_SB(b, h) + boff + n * 2048 + k * 1024); } while (0)
; #define PG8_WAIT_V(n) asm volatile("s_waitcnt vmcnt(" #n ")" ::: "memory")
; #define PG8_WAIT_L(n) asm volatile("s_waitcnt lgkmcnt(" #n ")" ::: "memory")
; #define PG8_BAR __builtin_amdgcn_s_barrier()
; #define PG8_SCHED __builtin_amdgcn_sched_barrier(0)
; template <class Epi, class Sched, class Ptrs, bool ALIGN_EPI, bool I8 = false>
; __device__ __forceinline__ void gemm_phase(LAS unsigned char* lds, const Ptrs& P, const Sched& S, const Epi& E) {
;     ...
;             PG8_LDB(B0, 0, 0); PG8_LDB(B1, 0, 1); PG8_SCHED; PG8_LDA(At, 0, 0); PG8_STAGE(PG8_SA(1, 1), a1 + hstepA, voffA);
;             PG8_WAIT_V(8); PG8_WAIT_L(0); PG8_BAR; PG8_MMA(0, 0, At, B0); PG8_MMA(0, 1, At, B1); PG8_BAR; PG8_SCHED;
;             PG8_LDA(At, 0, 1); PG8_STAGE(PG8_SB(0, 0), b2, voffB); PG8_STAGE(PG8_SB(0, 1), b2 + hstepB, voffB); PG8_STAGE(PG8_SA(0, 0), a2, voffA);
;             PG8_WAIT_V(8); PG8_WAIT_L(0); PG8_BAR; PG8_MMA(1, 0, At, B0); PG8_MMA(1, 1, At, B1); PG8_BAR; PG8_SCHED;
.LBB0_1309:
	ds_read_b128 v[130:133], v192
	ds_read_b128 v[134:137], v192 offset:1024
	ds_read_b128 v[138:141], v192 offset:2048
	ds_read_b128 v[142:145], v192 offset:3072
	ds_read_b128 v[146:149], v193
	ds_read_b128 v[150:153], v193 offset:1024
	ds_read_b128 v[170:173], v193 offset:2048
	ds_read_b128 v[174:177], v193 offset:3072
	s_add_u32 s30, s8, 0xfffc0080
	s_addc_u32 s31, s9, -1
	s_cmp_eq_u32 s48, 12
	s_cselect_b32 s35, s21, s31
	s_cselect_b32 s34, s23, s30
	s_cselect_b32 s31, s25, s47
	s_cselect_b32 s30, s24, s29
	v_lshl_add_u64 v[188:189], s[8:9], 0, v[162:163]
	s_add_i32 m0, s33, 0xc000
	ds_read_b128 v[178:181], v194
	ds_read_b128 v[184:187], v194 offset:1024
	ds_read_b128 v[196:199], v194 offset:2048
	ds_read_b128 v[200:203], v194 offset:3072
	ds_read_b128 v[204:207], v194 offset:4096
	ds_read_b128 v[208:211], v194 offset:5120
	ds_read_b128 v[212:215], v194 offset:6144
	ds_read_b128 v[216:219], v194 offset:7168
	global_load_lds_dwordx4 v[188:189], off
	v_lshl_add_u64 v[188:189], s[8:9], 0, v[164:165]
	s_add_i32 m0, s33, 0xe000
	s_nop 0
	global_load_lds_dwordx4 v[188:189], off
	s_waitcnt vmcnt(8)
	s_waitcnt lgkmcnt(0)
	s_barrier
	s_setprio 1
	s_waitcnt lgkmcnt(0)
	v_mfma_f32_16x16x32_bf16 v[126:129], v[130:133], v[178:181], v[126:129]
	v_mfma_f32_16x16x32_bf16 v[126:129], v[134:137], v[184:187], v[126:129]
	v_mfma_f32_16x16x32_bf16 v[122:125], v[138:141], v[178:181], v[122:125]
	v_mfma_f32_16x16x32_bf16 v[122:125], v[142:145], v[184:187], v[122:125]
	v_mfma_f32_16x16x32_bf16 v[110:113], v[130:133], v[196:199], v[110:113]
	v_mfma_f32_16x16x32_bf16 v[110:113], v[134:137], v[200:203], v[110:113]
	v_mfma_f32_16x16x32_bf16 v[106:109], v[138:141], v[196:199], v[106:109]
	v_mfma_f32_16x16x32_bf16 v[106:109], v[142:145], v[200:203], v[106:109]
	v_mfma_f32_16x16x32_bf16 v[94:97], v[130:133], v[204:207], v[94:97]
	v_mfma_f32_16x16x32_bf16 v[94:97], v[134:137], v[208:211], v[94:97]
	v_mfma_f32_16x16x32_bf16 v[90:93], v[138:141], v[204:207], v[90:93]
	v_mfma_f32_16x16x32_bf16 v[90:93], v[142:145], v[208:211], v[90:93]
	v_mfma_f32_16x16x32_bf16 v[78:81], v[130:133], v[212:215], v[78:81]
	v_mfma_f32_16x16x32_bf16 v[78:81], v[134:137], v[216:219], v[78:81]
	v_mfma_f32_16x16x32_bf16 v[74:77], v[138:141], v[212:215], v[74:77]
	v_mfma_f32_16x16x32_bf16 v[74:77], v[142:145], v[216:219], v[74:77]
	s_setprio 0
	s_setprio 1
	v_mfma_f32_16x16x32_bf16 v[118:121], v[146:149], v[178:181], v[118:121]
	v_mfma_f32_16x16x32_bf16 v[118:121], v[150:153], v[184:187], v[118:121]
	v_mfma_f32_16x16x32_bf16 v[114:117], v[170:173], v[178:181], v[114:117]
	v_mfma_f32_16x16x32_bf16 v[114:117], v[174:177], v[184:187], v[114:117]
	v_mfma_f32_16x16x32_bf16 v[102:105], v[146:149], v[196:199], v[102:105]
	v_mfma_f32_16x16x32_bf16 v[102:105], v[150:153], v[200:203], v[102:105]
	v_mfma_f32_16x16x32_bf16 v[98:101], v[170:173], v[196:199], v[98:101]
	v_mfma_f32_16x16x32_bf16 v[98:101], v[174:177], v[200:203], v[98:101]
	v_mfma_f32_16x16x32_bf16 v[86:89], v[146:149], v[204:207], v[86:89]
	v_mfma_f32_16x16x32_bf16 v[86:89], v[150:153], v[208:211], v[86:89]
	v_mfma_f32_16x16x32_bf16 v[82:85], v[170:173], v[204:207], v[82:85]
	v_mfma_f32_16x16x32_bf16 v[82:85], v[174:177], v[208:211], v[82:85]
	v_mfma_f32_16x16x32_bf16 v[70:73], v[146:149], v[212:215], v[70:73]
	v_mfma_f32_16x16x32_bf16 v[70:73], v[150:153], v[216:219], v[70:73]
	v_mfma_f32_16x16x32_bf16 v[66:69], v[170:173], v[212:215], v[66:69]
	v_mfma_f32_16x16x32_bf16 v[66:69], v[174:177], v[216:219], v[66:69]
	s_setprio 0
	s_barrier
	s_add_i32 s49, s44, s3
	v_lshl_add_u64 v[188:189], s[30:31], 0, v[156:157]
	s_mov_b32 m0, s49
	ds_read_b128 v[178:181], v194 offset:16384
	ds_read_b128 v[184:187], v194 offset:17408
	ds_read_b128 v[196:199], v194 offset:18432
	ds_read_b128 v[200:203], v194 offset:19456
	ds_read_b128 v[204:207], v194 offset:20480
	ds_read_b128 v[208:211], v194 offset:21504
	ds_read_b128 v[212:215], v194 offset:22528
	ds_read_b128 v[216:219], v194 offset:23552
	global_load_lds_dwordx4 v[188:189], off
	s_add_i32 m0, s49, 0x2000
	s_add_u32 s50, s30, 0x40000
	v_lshl_add_u64 v[220:221], s[30:31], 0, v[160:161]
	s_addc_u32 s51, s31, 0
	s_add_i32 s49, s45, s3
	global_load_lds_dwordx4 v[220:221], off
	v_lshl_add_u64 v[222:223], s[50:51], 0, v[156:157]
	s_mov_b32 m0, s49
	v_lshl_add_u64 v[224:225], s[34:35], 0, v[158:159]
	global_load_lds_dwordx4 v[222:223], off
	v_lshl_add_u64 v[222:223], s[50:51], 0, v[160:161]
	s_add_i32 m0, s49, 0x2000
	s_nop 0
	global_load_lds_dwordx4 v[222:223], off
	v_lshl_add_u64 v[222:223], s[34:35], 0, v[154:155]
	s_mov_b32 m0, s33
	s_nop 0
	global_load_lds_dwordx4 v[222:223], off
	s_mov_b32 m0, s36
	s_nop 0
	global_load_lds_dwordx4 v[224:225], off
	s_waitcnt vmcnt(8)
	s_waitcnt lgkmcnt(0)
	s_barrier
; #define PG8_STAGE(bufoff, gbase, voff) do { _Pragma("unroll") for (int _i = 0; _i < 2; ++_i) \
;         __builtin_amdgcn_global_load_lds((const unsigned*)((const char*)(gbase) + (voff)[_i]), (LAS unsigned*)(lds + (bufoff) + ldsw + _i * 8192), 16, 0, 0); } while (0)
; #define PG8_LDA(dst, b, h) do { _Pragma("unroll") for (int m = 0; m < 4; ++m) _Pragma("unroll") for (int k = 0; k < 2; ++k) dst[m][k] = *(const LAS bf16x8*)(lds + PG8_SA(b, h) + aoff + m * 2048 + k * 1024); } while (0)
; #define PG8_LDB(dst, b, h) do { _Pragma("unroll") for (int n = 0; n < 2; ++n) _Pragma("unroll") for (int k = 0; k < 2; ++k) dst[n][k] = *(const LAS bf16x8*)(lds + PG8_SB(b, h) + boff + n * 2048 + k * 1024); } while (0)
; #define PG8_WAIT_V(n) asm volatile("s_waitcnt vmcnt(" #n ")" ::: "memory")
; #define PG8_WAIT_L(n) asm volatile("s_waitcnt lgkmcnt(" #n ")" ::: "memory")
; #define PG8_BAR __builtin_amdgcn_s_barrier()
; #define PG8_SCHED __builtin_amdgcn_sched_barrier(0)
; template <class Epi, class Sched, class Ptrs, bool ALIGN_EPI, bool I8 = false>
; __device__ __forceinline__ void gemm_phase(LAS unsigned char* lds, const Ptrs& P, const Sched& S, const Epi& E) {
;     ...
;             PG8_LDA(At, 0, 1); PG8_STAGE(PG8_SB(0, 0), b2, voffB); PG8_STAGE(PG8_SB(0, 1), b2 + hstepB, voffB); PG8_STAGE(PG8_SA(0, 0), a2, voffA);
;             PG8_WAIT_V(8); PG8_WAIT_L(0); PG8_BAR; PG8_MMA(1, 0, At, B0); PG8_MMA(1, 1, At, B1); PG8_BAR; PG8_SCHED;
;             PG8_LDB(B0, 1, 0); PG8_LDB(B1, 1, 1); PG8_SCHED; PG8_LDA(At, 1, 0); PG8_STAGE(PG8_SA(0, 1), a2 + hstepA, voffA);
;             PG8_WAIT_V(8); PG8_WAIT_L(0); PG8_BAR; PG8_MMA(0, 0, At, B0); PG8_MMA(0, 1, At, B1); PG8_BAR; PG8_SCHED;
;             PG8_LDA(At, 1, 1); PG8_STAGE(PG8_SB(1, 0), b3, voffB); PG8_STAGE(PG8_SB(1, 1), b3 + hstepB, voffB); PG8_STAGE(PG8_SA(1, 0), a3, voffA);
	s_setprio 1
	s_waitcnt lgkmcnt(0)
	v_mfma_f32_16x16x32_bf16 v[62:65], v[130:133], v[178:181], v[62:65]
	v_mfma_f32_16x16x32_bf16 v[62:65], v[134:137], v[184:187], v[62:65]
	v_mfma_f32_16x16x32_bf16 v[58:61], v[138:141], v[178:181], v[58:61]
	v_mfma_f32_16x16x32_bf16 v[58:61], v[142:145], v[184:187], v[58:61]
	v_mfma_f32_16x16x32_bf16 v[46:49], v[130:133], v[196:199], v[46:49]
	v_mfma_f32_16x16x32_bf16 v[46:49], v[134:137], v[200:203], v[46:49]
	v_mfma_f32_16x16x32_bf16 v[42:45], v[138:141], v[196:199], v[42:45]
	v_mfma_f32_16x16x32_bf16 v[42:45], v[142:145], v[200:203], v[42:45]
	v_mfma_f32_16x16x32_bf16 v[30:33], v[130:133], v[204:207], v[30:33]
	v_mfma_f32_16x16x32_bf16 v[30:33], v[134:137], v[208:211], v[30:33]
	v_mfma_f32_16x16x32_bf16 v[26:29], v[138:141], v[204:207], v[26:29]
	v_mfma_f32_16x16x32_bf16 v[26:29], v[142:145], v[208:211], v[26:29]
	v_mfma_f32_16x16x32_bf16 v[14:17], v[130:133], v[212:215], v[14:17]
	v_mfma_f32_16x16x32_bf16 v[14:17], v[134:137], v[216:219], v[14:17]
	v_mfma_f32_16x16x32_bf16 v[10:13], v[138:141], v[212:215], v[10:13]
	v_mfma_f32_16x16x32_bf16 v[10:13], v[142:145], v[216:219], v[10:13]
	s_setprio 0
	s_setprio 1
	v_mfma_f32_16x16x32_bf16 v[54:57], v[146:149], v[178:181], v[54:57]
	v_mfma_f32_16x16x32_bf16 v[54:57], v[150:153], v[184:187], v[54:57]
	v_mfma_f32_16x16x32_bf16 v[50:53], v[170:173], v[178:181], v[50:53]
	v_mfma_f32_16x16x32_bf16 v[50:53], v[174:177], v[184:187], v[50:53]
	v_mfma_f32_16x16x32_bf16 v[38:41], v[146:149], v[196:199], v[38:41]
	v_mfma_f32_16x16x32_bf16 v[38:41], v[150:153], v[200:203], v[38:41]
	v_mfma_f32_16x16x32_bf16 v[34:37], v[170:173], v[196:199], v[34:37]
	v_mfma_f32_16x16x32_bf16 v[34:37], v[174:177], v[200:203], v[34:37]
	v_mfma_f32_16x16x32_bf16 v[22:25], v[146:149], v[204:207], v[22:25]
	v_mfma_f32_16x16x32_bf16 v[22:25], v[150:153], v[208:211], v[22:25]
	v_mfma_f32_16x16x32_bf16 v[18:21], v[170:173], v[204:207], v[18:21]
	v_mfma_f32_16x16x32_bf16 v[18:21], v[174:177], v[208:211], v[18:21]
	v_mfma_f32_16x16x32_bf16 v[6:9], v[146:149], v[212:215], v[6:9]
	v_mfma_f32_16x16x32_bf16 v[6:9], v[150:153], v[216:219], v[6:9]
	v_mfma_f32_16x16x32_bf16 v[2:5], v[170:173], v[212:215], v[2:5]
	v_mfma_f32_16x16x32_bf16 v[2:5], v[174:177], v[216:219], v[2:5]
	s_setprio 0
	s_barrier
	s_add_i32 s49, 0, 0x18000
	s_add_i32 s50, 0, 0x1c000
	v_add_u32_e32 v142, s49, v190
	v_add_u32_e32 v174, s50, v190
	ds_read_b128 v[130:133], v142
	ds_read_b128 v[134:137], v142 offset:1024
	ds_read_b128 v[138:141], v142 offset:2048
	ds_read_b128 v[142:145], v142 offset:3072
	ds_read_b128 v[146:149], v174
	ds_read_b128 v[150:153], v174 offset:1024
	ds_read_b128 v[170:173], v174 offset:2048
	ds_read_b128 v[174:177], v174 offset:3072
	s_add_u32 s34, s34, 0x40000
	s_addc_u32 s35, s35, 0
	s_mov_b32 m0, s37
	v_lshl_add_u64 v[226:227], s[34:35], 0, v[154:155]
	ds_read_b128 v[178:181], v194 offset:32768
	ds_read_b128 v[184:187], v194 offset:33792
	ds_read_b128 v[196:199], v194 offset:34816
	ds_read_b128 v[200:203], v194 offset:35840
	ds_read_b128 v[204:207], v194 offset:36864
	ds_read_b128 v[208:211], v194 offset:37888
	ds_read_b128 v[212:215], v194 offset:38912
	ds_read_b128 v[216:219], v194 offset:39936
	global_load_lds_dwordx4 v[226:227], off
	v_lshl_add_u64 v[226:227], s[34:35], 0, v[158:159]
	s_mov_b32 m0, s38
	s_nop 0
	global_load_lds_dwordx4 v[226:227], off
	s_waitcnt vmcnt(8)
	s_waitcnt lgkmcnt(0)
	s_barrier
	s_setprio 1
	s_waitcnt lgkmcnt(0)
	v_mfma_f32_16x16x32_bf16 v[126:129], v[130:133], v[178:181], v[126:129]
	v_mfma_f32_16x16x32_bf16 v[126:129], v[134:137], v[184:187], v[126:129]
	v_mfma_f32_16x16x32_bf16 v[122:125], v[138:141], v[178:181], v[122:125]
	v_mfma_f32_16x16x32_bf16 v[122:125], v[142:145], v[184:187], v[122:125]
	v_mfma_f32_16x16x32_bf16 v[110:113], v[130:133], v[196:199], v[110:113]
	v_mfma_f32_16x16x32_bf16 v[110:113], v[134:137], v[200:203], v[110:113]
	v_mfma_f32_16x16x32_bf16 v[106:109], v[138:141], v[196:199], v[106:109]
	v_mfma_f32_16x16x32_bf16 v[106:109], v[142:145], v[200:203], v[106:109]
	v_mfma_f32_16x16x32_bf16 v[94:97], v[130:133], v[204:207], v[94:97]
	v_mfma_f32_16x16x32_bf16 v[94:97], v[134:137], v[208:211], v[94:97]
	v_mfma_f32_16x16x32_bf16 v[90:93], v[138:141], v[204:207], v[90:93]
	v_mfma_f32_16x16x32_bf16 v[90:93], v[142:145], v[208:211], v[90:93]
	v_mfma_f32_16x16x32_bf16 v[78:81], v[130:133], v[212:215], v[78:81]
	v_mfma_f32_16x16x32_bf16 v[78:81], v[134:137], v[216:219], v[78:81]
	v_mfma_f32_16x16x32_bf16 v[74:77], v[138:141], v[212:215], v[74:77]
	v_mfma_f32_16x16x32_bf16 v[74:77], v[142:145], v[216:219], v[74:77]
	s_setprio 0
	s_setprio 1
	v_mfma_f32_16x16x32_bf16 v[118:121], v[146:149], v[178:181], v[118:121]
	v_mfma_f32_16x16x32_bf16 v[118:121], v[150:153], v[184:187], v[118:121]
	v_mfma_f32_16x16x32_bf16 v[114:117], v[170:173], v[178:181], v[114:117]
	v_mfma_f32_16x16x32_bf16 v[114:117], v[174:177], v[184:187], v[114:117]
	v_mfma_f32_16x16x32_bf16 v[102:105], v[146:149], v[196:199], v[102:105]
	v_mfma_f32_16x16x32_bf16 v[102:105], v[150:153], v[200:203], v[102:105]
	v_mfma_f32_16x16x32_bf16 v[98:101], v[170:173], v[196:199], v[98:101]
	v_mfma_f32_16x16x32_bf16 v[98:101], v[174:177], v[200:203], v[98:101]
	v_mfma_f32_16x16x32_bf16 v[86:89], v[146:149], v[204:207], v[86:89]
	v_mfma_f32_16x16x32_bf16 v[86:89], v[150:153], v[208:211], v[86:89]
	v_mfma_f32_16x16x32_bf16 v[82:85], v[170:173], v[204:207], v[82:85]
	v_mfma_f32_16x16x32_bf16 v[82:85], v[174:177], v[208:211], v[82:85]
	v_mfma_f32_16x16x32_bf16 v[70:73], v[146:149], v[212:215], v[70:73]
	v_mfma_f32_16x16x32_bf16 v[70:73], v[150:153], v[216:219], v[70:73]
	v_mfma_f32_16x16x32_bf16 v[66:69], v[170:173], v[212:215], v[66:69]
	v_mfma_f32_16x16x32_bf16 v[66:69], v[174:177], v[216:219], v[66:69]
	s_setprio 0
	s_barrier
; #define PG8_STAGE(bufoff, gbase, voff) do { _Pragma("unroll") for (int _i = 0; _i < 2; ++_i) \
;         __builtin_amdgcn_global_load_lds((const unsigned*)((const char*)(gbase) + (voff)[_i]), (LAS unsigned*)(lds + (bufoff) + ldsw + _i * 8192), 16, 0, 0); } while (0)
; #define PG8_LDA(dst, b, h) do { _Pragma("unroll") for (int m = 0; m < 4; ++m) _Pragma("unroll") for (int k = 0; k < 2; ++k) dst[m][k] = *(const LAS bf16x8*)(lds + PG8_SA(b, h) + aoff + m * 2048 + k * 1024); } while (0)
; #define PG8_WAIT_V(n) asm volatile("s_waitcnt vmcnt(" #n ")" ::: "memory")
; #define PG8_WAIT_L(n) asm volatile("s_waitcnt lgkmcnt(" #n ")" ::: "memory")
; #define PG8_BAR __builtin_amdgcn_s_barrier()
; #define PG8_SCHED __builtin_amdgcn_sched_barrier(0)
; template <class Epi, class Sched, class Ptrs, bool ALIGN_EPI, bool I8 = false>
; __device__ __forceinline__ void gemm_phase(LAS unsigned char* lds, const Ptrs& P, const Sched& S, const Epi& E) {
;     ...
;             PG8_LDA(At, 1, 1); PG8_STAGE(PG8_SB(1, 0), b3, voffB); PG8_STAGE(PG8_SB(1, 1), b3 + hstepB, voffB); PG8_STAGE(PG8_SA(1, 0), a3, voffA);
;             PG8_WAIT_V(8); PG8_WAIT_L(0); PG8_BAR; PG8_MMA(1, 0, At, B0); PG8_MMA(1, 1, At, B1); PG8_BAR; PG8_SCHED;
;         }
;         if constexpr (ALIGN_EPI) { if (wr == 0) PG8_BAR; }
	s_add_i32 s34, s49, s3
	v_lshl_add_u64 v[188:189], v[188:189], 0, s[16:17]
	s_mov_b32 m0, s34
	ds_read_b128 v[178:181], v194 offset:49152
	ds_read_b128 v[184:187], v194 offset:50176
	ds_read_b128 v[196:199], v194 offset:51200
	ds_read_b128 v[200:203], v194 offset:52224
	ds_read_b128 v[204:207], v194 offset:53248
	ds_read_b128 v[208:211], v194 offset:54272
	ds_read_b128 v[212:215], v194 offset:55296
	ds_read_b128 v[216:219], v194 offset:56320
	global_load_lds_dwordx4 v[188:189], off
	s_add_i32 m0, s34, 0x2000
	s_add_u32 s30, s30, 0x40080
	v_lshl_add_u64 v[188:189], v[220:221], 0, s[16:17]
	s_addc_u32 s31, s31, 0
	s_add_i32 s34, s50, s3
	global_load_lds_dwordx4 v[188:189], off
	v_lshl_add_u64 v[188:189], s[30:31], 0, v[156:157]
	s_mov_b32 m0, s34
	s_nop 0
	global_load_lds_dwordx4 v[188:189], off
	v_lshl_add_u64 v[188:189], s[30:31], 0, v[160:161]
	s_add_i32 m0, s34, 0x2000
	s_nop 0
	global_load_lds_dwordx4 v[188:189], off
	v_lshl_add_u64 v[188:189], v[222:223], 0, s[16:17]
	s_mov_b32 m0, s40
	s_nop 0
	global_load_lds_dwordx4 v[188:189], off
	v_lshl_add_u64 v[188:189], v[224:225], 0, s[16:17]
	s_mov_b32 m0, s41
	s_nop 0
	global_load_lds_dwordx4 v[188:189], off
	s_waitcnt vmcnt(8)
	s_waitcnt lgkmcnt(0)
	s_barrier
	s_setprio 1
	s_waitcnt lgkmcnt(0)
	v_mfma_f32_16x16x32_bf16 v[62:65], v[130:133], v[178:181], v[62:65]
	v_mfma_f32_16x16x32_bf16 v[62:65], v[134:137], v[184:187], v[62:65]
	v_mfma_f32_16x16x32_bf16 v[58:61], v[138:141], v[178:181], v[58:61]
	v_mfma_f32_16x16x32_bf16 v[58:61], v[142:145], v[184:187], v[58:61]
	v_mfma_f32_16x16x32_bf16 v[46:49], v[130:133], v[196:199], v[46:49]
	v_mfma_f32_16x16x32_bf16 v[46:49], v[134:137], v[200:203], v[46:49]
	v_mfma_f32_16x16x32_bf16 v[42:45], v[138:141], v[196:199], v[42:45]
	v_mfma_f32_16x16x32_bf16 v[42:45], v[142:145], v[200:203], v[42:45]
	v_mfma_f32_16x16x32_bf16 v[30:33], v[130:133], v[204:207], v[30:33]
	v_mfma_f32_16x16x32_bf16 v[30:33], v[134:137], v[208:211], v[30:33]
	v_mfma_f32_16x16x32_bf16 v[26:29], v[138:141], v[204:207], v[26:29]
	v_mfma_f32_16x16x32_bf16 v[26:29], v[142:145], v[208:211], v[26:29]
	v_mfma_f32_16x16x32_bf16 v[14:17], v[130:133], v[212:215], v[14:17]
	v_mfma_f32_16x16x32_bf16 v[14:17], v[134:137], v[216:219], v[14:17]
	v_mfma_f32_16x16x32_bf16 v[10:13], v[138:141], v[212:215], v[10:13]
	v_mfma_f32_16x16x32_bf16 v[10:13], v[142:145], v[216:219], v[10:13]
	s_setprio 0
	s_setprio 1
	v_mfma_f32_16x16x32_bf16 v[54:57], v[146:149], v[178:181], v[54:57]
	v_mfma_f32_16x16x32_bf16 v[54:57], v[150:153], v[184:187], v[54:57]
	v_mfma_f32_16x16x32_bf16 v[50:53], v[170:173], v[178:181], v[50:53]
	v_mfma_f32_16x16x32_bf16 v[50:53], v[174:177], v[184:187], v[50:53]
	v_mfma_f32_16x16x32_bf16 v[38:41], v[146:149], v[196:199], v[38:41]
	v_mfma_f32_16x16x32_bf16 v[38:41], v[150:153], v[200:203], v[38:41]
	v_mfma_f32_16x16x32_bf16 v[34:37], v[170:173], v[196:199], v[34:37]
	v_mfma_f32_16x16x32_bf16 v[34:37], v[174:177], v[200:203], v[34:37]
	v_mfma_f32_16x16x32_bf16 v[22:25], v[146:149], v[204:207], v[22:25]
	v_mfma_f32_16x16x32_bf16 v[22:25], v[150:153], v[208:211], v[22:25]
	v_mfma_f32_16x16x32_bf16 v[18:21], v[170:173], v[204:207], v[18:21]
	v_mfma_f32_16x16x32_bf16 v[18:21], v[174:177], v[208:211], v[18:21]
	v_mfma_f32_16x16x32_bf16 v[6:9], v[146:149], v[212:215], v[6:9]
	v_mfma_f32_16x16x32_bf16 v[6:9], v[150:153], v[216:219], v[6:9]
	v_mfma_f32_16x16x32_bf16 v[2:5], v[170:173], v[212:215], v[2:5]
	v_mfma_f32_16x16x32_bf16 v[2:5], v[174:177], v[216:219], v[2:5]
	s_setprio 0
	s_barrier
	s_add_i32 s48, s48, 2
	s_add_u32 s8, s8, 0x100
	s_addc_u32 s9, s9, 0
	s_add_u32 s29, s29, 0x100
	s_addc_u32 s47, s47, 0
	s_cmp_gt_u32 s48, 13
	s_cbranch_scc0 .LBB0_1309
	s_and_b64 vcc, exec, s[18:19]
	s_cbranch_vccz .LBB0_1312
	s_barrier

; #define PG8_STAGE(bufoff, gbase, voff) do { _Pragma("unroll") for (int _i = 0; _i < 2; ++_i) \
;         __builtin_amdgcn_global_load_lds((const unsigned*)((const char*)(gbase) + (voff)[_i]), (LAS unsigned*)(lds + (bufoff) + ldsw + _i * 8192), 16, 0, 0); } while (0)
; #define PG8_LDA(dst, b, h) do { _Pragma("unroll") for (int m = 0; m < 4; ++m) _Pragma("unroll") for (int k = 0; k < 2; ++k) dst[m][k] = *(const LAS bf16x8*)(lds + PG8_SA(b, h) + aoff + m * 2048 + k * 1024); } while (0)
; #define PG8_LDB(dst, b, h) do { _Pragma("unroll") for (int n = 0; n < 2; ++n) _Pragma("unroll") for (int k = 0; k < 2; ++k) dst[n][k] = *(const LAS bf16x8*)(lds + PG8_SB(b, h) + boff + n * 2048 + k * 1024); } while (0)
; #define PG8_WAIT_V(n) asm volatile("s_waitcnt vmcnt(" #n ")" ::: "memory")
; #define PG8_WAIT_L(n) asm volatile("s_waitcnt lgkmcnt(" #n ")" ::: "memory")
; #define PG8_BAR __builtin_amdgcn_s_barrier()
; #define PG8_SCHED __builtin_amdgcn_sched_barrier(0)
; template <class Epi, class Sched, class Ptrs, bool ALIGN_EPI, bool I8 = false>
; __device__ __forceinline__ void gemm_phase(LAS unsigned char* lds, const Ptrs& P, const Sched& S, const Epi& E) {
;     ...
;             PG8_LDB(B0, 0, 0); PG8_LDB(B1, 0, 1); PG8_SCHED; PG8_LDA(At, 0, 0); PG8_STAGE(PG8_SA(1, 1), a1 + hstepA, voffA);
;             PG8_WAIT_V(8); PG8_WAIT_L(0); PG8_BAR; PG8_MMA(0, 0, At, B0); PG8_MMA(0, 1, At, B1); PG8_BAR; PG8_SCHED;
;             PG8_LDA(At, 0, 1); PG8_STAGE(PG8_SB(0, 0), b2, voffB); PG8_STAGE(PG8_SB(0, 1), b2 + hstepB, voffB); PG8_STAGE(PG8_SA(0, 0), a2, voffA);
;             PG8_WAIT_V(8); PG8_WAIT_L(0); PG8_BAR; PG8_MMA(1, 0, At, B0); PG8_MMA(1, 1, At, B1); PG8_BAR; PG8_SCHED;
.LBB0_1478:
	ds_read_b128 v[106:109], v167
	ds_read_b128 v[110:113], v167 offset:1024
	ds_read_b128 v[122:125], v167 offset:2048
	ds_read_b128 v[126:129], v167 offset:3072
	ds_read_b128 v[170:173], v168
	ds_read_b128 v[174:177], v168 offset:1024
	ds_read_b128 v[178:181], v168 offset:2048
	ds_read_b128 v[184:187], v168 offset:3072
	s_add_u32 s40, s38, 0xfff80080
	s_addc_u32 s41, s39, -1
	s_cmp_eq_u32 s61, 28
	s_cselect_b32 s43, s29, s41
	s_cselect_b32 s42, s57, s40
	s_cselect_b32 s41, s27, s60
	s_cselect_b32 s40, s58, s59
	v_lshl_add_u64 v[162:163], s[38:39], 0, v[154:155]
	s_add_i32 m0, s37, 0xc000
	ds_read_b128 v[188:191], v169
	ds_read_b128 v[192:195], v169 offset:1024
	ds_read_b128 v[196:199], v169 offset:2048
	ds_read_b128 v[200:203], v169 offset:3072
	ds_read_b128 v[204:207], v169 offset:4096
	ds_read_b128 v[208:211], v169 offset:5120
	ds_read_b128 v[212:215], v169 offset:6144
	ds_read_b128 v[216:219], v169 offset:7168
	global_load_lds_dwordx4 v[162:163], off
	v_lshl_add_u64 v[162:163], s[38:39], 0, v[156:157]
	s_add_i32 m0, s37, 0xe000
	s_nop 0
	global_load_lds_dwordx4 v[162:163], off
	s_waitcnt vmcnt(8)
	s_waitcnt lgkmcnt(0)
	s_barrier
	s_setprio 1
	s_waitcnt lgkmcnt(0)
	v_mfma_i32_16x16x64_i8 v[142:145], v[106:109], v[188:191], v[142:145]
	v_mfma_i32_16x16x64_i8 v[142:145], v[110:113], v[192:195], v[142:145]
	v_mfma_i32_16x16x64_i8 v[138:141], v[122:125], v[188:191], v[138:141]
	v_mfma_i32_16x16x64_i8 v[138:141], v[126:129], v[192:195], v[138:141]
	v_mfma_i32_16x16x64_i8 v[118:121], v[106:109], v[196:199], v[118:121]
	v_mfma_i32_16x16x64_i8 v[118:121], v[110:113], v[200:203], v[118:121]
	v_mfma_i32_16x16x64_i8 v[114:117], v[122:125], v[196:199], v[114:117]
	v_mfma_i32_16x16x64_i8 v[114:117], v[126:129], v[200:203], v[114:117]
	v_mfma_i32_16x16x64_i8 v[94:97], v[106:109], v[204:207], v[94:97]
	v_mfma_i32_16x16x64_i8 v[94:97], v[110:113], v[208:211], v[94:97]
	v_mfma_i32_16x16x64_i8 v[90:93], v[122:125], v[204:207], v[90:93]
	v_mfma_i32_16x16x64_i8 v[90:93], v[126:129], v[208:211], v[90:93]
	v_mfma_i32_16x16x64_i8 v[78:81], v[106:109], v[212:215], v[78:81]
	v_mfma_i32_16x16x64_i8 v[78:81], v[110:113], v[216:219], v[78:81]
	v_mfma_i32_16x16x64_i8 v[74:77], v[122:125], v[212:215], v[74:77]
	v_mfma_i32_16x16x64_i8 v[74:77], v[126:129], v[216:219], v[74:77]
	s_setprio 0
	s_setprio 1
	v_mfma_i32_16x16x64_i8 v[134:137], v[170:173], v[188:191], v[134:137]
	v_mfma_i32_16x16x64_i8 v[134:137], v[174:177], v[192:195], v[134:137]
	v_mfma_i32_16x16x64_i8 v[130:133], v[178:181], v[188:191], v[130:133]
	v_mfma_i32_16x16x64_i8 v[130:133], v[184:187], v[192:195], v[130:133]
	v_mfma_i32_16x16x64_i8 v[102:105], v[170:173], v[196:199], v[102:105]
	v_mfma_i32_16x16x64_i8 v[102:105], v[174:177], v[200:203], v[102:105]
	v_mfma_i32_16x16x64_i8 v[98:101], v[178:181], v[196:199], v[98:101]
	v_mfma_i32_16x16x64_i8 v[98:101], v[184:187], v[200:203], v[98:101]
	v_mfma_i32_16x16x64_i8 v[86:89], v[170:173], v[204:207], v[86:89]
	v_mfma_i32_16x16x64_i8 v[86:89], v[174:177], v[208:211], v[86:89]
	v_mfma_i32_16x16x64_i8 v[82:85], v[178:181], v[204:207], v[82:85]
	v_mfma_i32_16x16x64_i8 v[82:85], v[184:187], v[208:211], v[82:85]
	v_mfma_i32_16x16x64_i8 v[70:73], v[170:173], v[212:215], v[70:73]
	v_mfma_i32_16x16x64_i8 v[70:73], v[174:177], v[216:219], v[70:73]
	v_mfma_i32_16x16x64_i8 v[66:69], v[178:181], v[212:215], v[66:69]
	v_mfma_i32_16x16x64_i8 v[66:69], v[184:187], v[216:219], v[66:69]
	s_setprio 0
	s_barrier
	s_add_i32 s62, s53, s33
	v_lshl_add_u64 v[162:163], s[40:41], 0, v[148:149]
	s_mov_b32 m0, s62
	ds_read_b128 v[188:191], v169 offset:16384
	ds_read_b128 v[192:195], v169 offset:17408
	ds_read_b128 v[196:199], v169 offset:18432
	ds_read_b128 v[200:203], v169 offset:19456
	ds_read_b128 v[204:207], v169 offset:20480
	ds_read_b128 v[208:211], v169 offset:21504
	ds_read_b128 v[212:215], v169 offset:22528
	ds_read_b128 v[216:219], v169 offset:23552
	global_load_lds_dwordx4 v[162:163], off
	s_add_i32 m0, s62, 0x2000
	s_add_u32 s62, s40, 0x80000
	v_lshl_add_u64 v[220:221], s[40:41], 0, v[152:153]
	s_addc_u32 s63, s41, 0
	s_add_i32 s64, s54, s33
	global_load_lds_dwordx4 v[220:221], off
	v_lshl_add_u64 v[222:223], s[62:63], 0, v[148:149]
	s_mov_b32 m0, s64
	v_lshl_add_u64 v[224:225], s[42:43], 0, v[150:151]
	global_load_lds_dwordx4 v[222:223], off
	v_lshl_add_u64 v[222:223], s[62:63], 0, v[152:153]
	s_add_i32 m0, s64, 0x2000
	s_nop 0
	global_load_lds_dwordx4 v[222:223], off
	v_lshl_add_u64 v[222:223], s[42:43], 0, v[146:147]
	s_mov_b32 m0, s37
	s_nop 0
	global_load_lds_dwordx4 v[222:223], off
	s_mov_b32 m0, s46
	s_nop 0
	global_load_lds_dwordx4 v[224:225], off
	s_waitcnt vmcnt(8)
	s_waitcnt lgkmcnt(0)
	s_barrier
; #define PG8_STAGE(bufoff, gbase, voff) do { _Pragma("unroll") for (int _i = 0; _i < 2; ++_i) \
;         __builtin_amdgcn_global_load_lds((const unsigned*)((const char*)(gbase) + (voff)[_i]), (LAS unsigned*)(lds + (bufoff) + ldsw + _i * 8192), 16, 0, 0); } while (0)
; #define PG8_LDA(dst, b, h) do { _Pragma("unroll") for (int m = 0; m < 4; ++m) _Pragma("unroll") for (int k = 0; k < 2; ++k) dst[m][k] = *(const LAS bf16x8*)(lds + PG8_SA(b, h) + aoff + m * 2048 + k * 1024); } while (0)
; #define PG8_LDB(dst, b, h) do { _Pragma("unroll") for (int n = 0; n < 2; ++n) _Pragma("unroll") for (int k = 0; k < 2; ++k) dst[n][k] = *(const LAS bf16x8*)(lds + PG8_SB(b, h) + boff + n * 2048 + k * 1024); } while (0)
; #define PG8_WAIT_V(n) asm volatile("s_waitcnt vmcnt(" #n ")" ::: "memory")
; #define PG8_WAIT_L(n) asm volatile("s_waitcnt lgkmcnt(" #n ")" ::: "memory")
; #define PG8_BAR __builtin_amdgcn_s_barrier()
; #define PG8_SCHED __builtin_amdgcn_sched_barrier(0)
; template <class Epi, class Sched, class Ptrs, bool ALIGN_EPI, bool I8 = false>
; __device__ __forceinline__ void gemm_phase(LAS unsigned char* lds, const Ptrs& P, const Sched& S, const Epi& E) {
;     ...
;             PG8_LDA(At, 0, 1); PG8_STAGE(PG8_SB(0, 0), b2, voffB); PG8_STAGE(PG8_SB(0, 1), b2 + hstepB, voffB); PG8_STAGE(PG8_SA(0, 0), a2, voffA);
;             PG8_WAIT_V(8); PG8_WAIT_L(0); PG8_BAR; PG8_MMA(1, 0, At, B0); PG8_MMA(1, 1, At, B1); PG8_BAR; PG8_SCHED;
;             PG8_LDB(B0, 1, 0); PG8_LDB(B1, 1, 1); PG8_SCHED; PG8_LDA(At, 1, 0); PG8_STAGE(PG8_SA(0, 1), a2 + hstepA, voffA);
;             PG8_WAIT_V(8); PG8_WAIT_L(0); PG8_BAR; PG8_MMA(0, 0, At, B0); PG8_MMA(0, 1, At, B1); PG8_BAR; PG8_SCHED;
;             PG8_LDA(At, 1, 1); PG8_STAGE(PG8_SB(1, 0), b3, voffB); PG8_STAGE(PG8_SB(1, 1), b3 + hstepB, voffB); PG8_STAGE(PG8_SA(1, 0), a3, voffA);
	s_setprio 1
	s_waitcnt lgkmcnt(0)
	v_mfma_i32_16x16x64_i8 v[62:65], v[106:109], v[188:191], v[62:65]
	v_mfma_i32_16x16x64_i8 v[62:65], v[110:113], v[192:195], v[62:65]
	v_mfma_i32_16x16x64_i8 v[58:61], v[122:125], v[188:191], v[58:61]
	v_mfma_i32_16x16x64_i8 v[58:61], v[126:129], v[192:195], v[58:61]
	v_mfma_i32_16x16x64_i8 v[46:49], v[106:109], v[196:199], v[46:49]
	v_mfma_i32_16x16x64_i8 v[46:49], v[110:113], v[200:203], v[46:49]
	v_mfma_i32_16x16x64_i8 v[42:45], v[122:125], v[196:199], v[42:45]
	v_mfma_i32_16x16x64_i8 v[42:45], v[126:129], v[200:203], v[42:45]
	v_mfma_i32_16x16x64_i8 v[30:33], v[106:109], v[204:207], v[30:33]
	v_mfma_i32_16x16x64_i8 v[30:33], v[110:113], v[208:211], v[30:33]
	v_mfma_i32_16x16x64_i8 v[26:29], v[122:125], v[204:207], v[26:29]
	v_mfma_i32_16x16x64_i8 v[26:29], v[126:129], v[208:211], v[26:29]
	v_mfma_i32_16x16x64_i8 v[14:17], v[106:109], v[212:215], v[14:17]
	v_mfma_i32_16x16x64_i8 v[14:17], v[110:113], v[216:219], v[14:17]
	v_mfma_i32_16x16x64_i8 v[10:13], v[122:125], v[212:215], v[10:13]
	v_mfma_i32_16x16x64_i8 v[10:13], v[126:129], v[216:219], v[10:13]
	s_setprio 0
	s_setprio 1
	v_mfma_i32_16x16x64_i8 v[54:57], v[170:173], v[188:191], v[54:57]
	v_mfma_i32_16x16x64_i8 v[54:57], v[174:177], v[192:195], v[54:57]
	v_mfma_i32_16x16x64_i8 v[50:53], v[178:181], v[188:191], v[50:53]
	v_mfma_i32_16x16x64_i8 v[50:53], v[184:187], v[192:195], v[50:53]
	v_mfma_i32_16x16x64_i8 v[38:41], v[170:173], v[196:199], v[38:41]
	v_mfma_i32_16x16x64_i8 v[38:41], v[174:177], v[200:203], v[38:41]
	v_mfma_i32_16x16x64_i8 v[34:37], v[178:181], v[196:199], v[34:37]
	v_mfma_i32_16x16x64_i8 v[34:37], v[184:187], v[200:203], v[34:37]
	v_mfma_i32_16x16x64_i8 v[22:25], v[170:173], v[204:207], v[22:25]
	v_mfma_i32_16x16x64_i8 v[22:25], v[174:177], v[208:211], v[22:25]
	v_mfma_i32_16x16x64_i8 v[18:21], v[178:181], v[204:207], v[18:21]
	v_mfma_i32_16x16x64_i8 v[18:21], v[184:187], v[208:211], v[18:21]
	v_mfma_i32_16x16x64_i8 v[6:9], v[170:173], v[212:215], v[6:9]
	v_mfma_i32_16x16x64_i8 v[6:9], v[174:177], v[216:219], v[6:9]
	v_mfma_i32_16x16x64_i8 v[2:5], v[178:181], v[212:215], v[2:5]
	v_mfma_i32_16x16x64_i8 v[2:5], v[184:187], v[216:219], v[2:5]
	s_setprio 0
	s_barrier
	s_add_i32 s62, 0, 0x18000
	s_add_i32 s63, 0, 0x1c000
	v_add_u32_e32 v126, s62, v165
	v_add_u32_e32 v183, s63, v165
	ds_read_b128 v[106:109], v126
	ds_read_b128 v[110:113], v126 offset:1024
	ds_read_b128 v[122:125], v126 offset:2048
	ds_read_b128 v[126:129], v126 offset:3072
	ds_read_b128 v[170:173], v183
	ds_read_b128 v[174:177], v183 offset:1024
	ds_read_b128 v[178:181], v183 offset:2048
	ds_read_b128 v[184:187], v183 offset:3072
	s_add_u32 s42, s42, 0x80000
	s_addc_u32 s43, s43, 0
	s_mov_b32 m0, s47
	v_lshl_add_u64 v[226:227], s[42:43], 0, v[146:147]
	ds_read_b128 v[188:191], v169 offset:32768
	ds_read_b128 v[192:195], v169 offset:33792
	ds_read_b128 v[196:199], v169 offset:34816
	ds_read_b128 v[200:203], v169 offset:35840
	ds_read_b128 v[204:207], v169 offset:36864
	ds_read_b128 v[208:211], v169 offset:37888
	ds_read_b128 v[212:215], v169 offset:38912
	ds_read_b128 v[216:219], v169 offset:39936
	global_load_lds_dwordx4 v[226:227], off
	v_lshl_add_u64 v[226:227], s[42:43], 0, v[150:151]
	s_mov_b32 m0, s48
	s_nop 0
	global_load_lds_dwordx4 v[226:227], off
	s_waitcnt vmcnt(8)
	s_waitcnt lgkmcnt(0)
	s_barrier
	s_setprio 1
	s_waitcnt lgkmcnt(0)
	v_mfma_i32_16x16x64_i8 v[142:145], v[106:109], v[188:191], v[142:145]
	v_mfma_i32_16x16x64_i8 v[142:145], v[110:113], v[192:195], v[142:145]
	v_mfma_i32_16x16x64_i8 v[138:141], v[122:125], v[188:191], v[138:141]
	v_mfma_i32_16x16x64_i8 v[138:141], v[126:129], v[192:195], v[138:141]
	v_mfma_i32_16x16x64_i8 v[118:121], v[106:109], v[196:199], v[118:121]
	v_mfma_i32_16x16x64_i8 v[118:121], v[110:113], v[200:203], v[118:121]
	v_mfma_i32_16x16x64_i8 v[114:117], v[122:125], v[196:199], v[114:117]
	v_mfma_i32_16x16x64_i8 v[114:117], v[126:129], v[200:203], v[114:117]
	v_mfma_i32_16x16x64_i8 v[94:97], v[106:109], v[204:207], v[94:97]
	v_mfma_i32_16x16x64_i8 v[94:97], v[110:113], v[208:211], v[94:97]
	v_mfma_i32_16x16x64_i8 v[90:93], v[122:125], v[204:207], v[90:93]
	v_mfma_i32_16x16x64_i8 v[90:93], v[126:129], v[208:211], v[90:93]
	v_mfma_i32_16x16x64_i8 v[78:81], v[106:109], v[212:215], v[78:81]
	v_mfma_i32_16x16x64_i8 v[78:81], v[110:113], v[216:219], v[78:81]
	v_mfma_i32_16x16x64_i8 v[74:77], v[122:125], v[212:215], v[74:77]
	v_mfma_i32_16x16x64_i8 v[74:77], v[126:129], v[216:219], v[74:77]
	s_setprio 0
	s_setprio 1
	v_mfma_i32_16x16x64_i8 v[134:137], v[170:173], v[188:191], v[134:137]
	v_mfma_i32_16x16x64_i8 v[134:137], v[174:177], v[192:195], v[134:137]
	v_mfma_i32_16x16x64_i8 v[130:133], v[178:181], v[188:191], v[130:133]
	v_mfma_i32_16x16x64_i8 v[130:133], v[184:187], v[192:195], v[130:133]
	v_mfma_i32_16x16x64_i8 v[102:105], v[170:173], v[196:199], v[102:105]
	v_mfma_i32_16x16x64_i8 v[102:105], v[174:177], v[200:203], v[102:105]
	v_mfma_i32_16x16x64_i8 v[98:101], v[178:181], v[196:199], v[98:101]
	v_mfma_i32_16x16x64_i8 v[98:101], v[184:187], v[200:203], v[98:101]
	v_mfma_i32_16x16x64_i8 v[86:89], v[170:173], v[204:207], v[86:89]
	v_mfma_i32_16x16x64_i8 v[86:89], v[174:177], v[208:211], v[86:89]
	v_mfma_i32_16x16x64_i8 v[82:85], v[178:181], v[204:207], v[82:85]
	v_mfma_i32_16x16x64_i8 v[82:85], v[184:187], v[208:211], v[82:85]
	v_mfma_i32_16x16x64_i8 v[70:73], v[170:173], v[212:215], v[70:73]
	v_mfma_i32_16x16x64_i8 v[70:73], v[174:177], v[216:219], v[70:73]
	v_mfma_i32_16x16x64_i8 v[66:69], v[178:181], v[212:215], v[66:69]
	v_mfma_i32_16x16x64_i8 v[66:69], v[184:187], v[216:219], v[66:69]
	s_setprio 0
	s_barrier
; #define PG8_STAGE(bufoff, gbase, voff) do { _Pragma("unroll") for (int _i = 0; _i < 2; ++_i) \
;         __builtin_amdgcn_global_load_lds((const unsigned*)((const char*)(gbase) + (voff)[_i]), (LAS unsigned*)(lds + (bufoff) + ldsw + _i * 8192), 16, 0, 0); } while (0)
; #define PG8_LDA(dst, b, h) do { _Pragma("unroll") for (int m = 0; m < 4; ++m) _Pragma("unroll") for (int k = 0; k < 2; ++k) dst[m][k] = *(const LAS bf16x8*)(lds + PG8_SA(b, h) + aoff + m * 2048 + k * 1024); } while (0)
; #define PG8_WAIT_V(n) asm volatile("s_waitcnt vmcnt(" #n ")" ::: "memory")
; #define PG8_WAIT_L(n) asm volatile("s_waitcnt lgkmcnt(" #n ")" ::: "memory")
; #define PG8_BAR __builtin_amdgcn_s_barrier()
; #define PG8_SCHED __builtin_amdgcn_sched_barrier(0)
; template <class Epi, class Sched, class Ptrs, bool ALIGN_EPI, bool I8 = false>
; __device__ __forceinline__ void gemm_phase(LAS unsigned char* lds, const Ptrs& P, const Sched& S, const Epi& E) {
;     ...
;             PG8_LDA(At, 1, 1); PG8_STAGE(PG8_SB(1, 0), b3, voffB); PG8_STAGE(PG8_SB(1, 1), b3 + hstepB, voffB); PG8_STAGE(PG8_SA(1, 0), a3, voffA);
;             PG8_WAIT_V(8); PG8_WAIT_L(0); PG8_BAR; PG8_MMA(1, 0, At, B0); PG8_MMA(1, 1, At, B1); PG8_BAR; PG8_SCHED;
;         }
;         if constexpr (ALIGN_EPI) { if (wr == 0) PG8_BAR; }
	s_add_i32 s42, s62, s33
	v_lshl_add_u64 v[162:163], v[162:163], 0, s[22:23]
	s_mov_b32 m0, s42
	ds_read_b128 v[188:191], v169 offset:49152
	ds_read_b128 v[192:195], v169 offset:50176
	ds_read_b128 v[196:199], v169 offset:51200
	ds_read_b128 v[200:203], v169 offset:52224
	ds_read_b128 v[204:207], v169 offset:53248
	ds_read_b128 v[208:211], v169 offset:54272
	ds_read_b128 v[212:215], v169 offset:55296
	ds_read_b128 v[216:219], v169 offset:56320
	global_load_lds_dwordx4 v[162:163], off
	s_add_i32 m0, s42, 0x2000
	s_add_u32 s40, s40, 0x80080
	v_lshl_add_u64 v[162:163], v[220:221], 0, s[22:23]
	s_addc_u32 s41, s41, 0
	s_add_i32 s42, s63, s33
	global_load_lds_dwordx4 v[162:163], off
	v_lshl_add_u64 v[162:163], s[40:41], 0, v[148:149]
	s_mov_b32 m0, s42
	s_nop 0
	global_load_lds_dwordx4 v[162:163], off
	v_lshl_add_u64 v[162:163], s[40:41], 0, v[152:153]
	s_add_i32 m0, s42, 0x2000
	s_nop 0
	global_load_lds_dwordx4 v[162:163], off
	v_lshl_add_u64 v[162:163], v[222:223], 0, s[22:23]
	s_mov_b32 m0, s50
	s_nop 0
	global_load_lds_dwordx4 v[162:163], off
	v_lshl_add_u64 v[162:163], v[224:225], 0, s[22:23]
	s_mov_b32 m0, s51
	s_nop 0
	global_load_lds_dwordx4 v[162:163], off
	s_waitcnt vmcnt(8)
	s_waitcnt lgkmcnt(0)
	s_barrier
	s_setprio 1
	s_waitcnt lgkmcnt(0)
	v_mfma_i32_16x16x64_i8 v[62:65], v[106:109], v[188:191], v[62:65]
	v_mfma_i32_16x16x64_i8 v[62:65], v[110:113], v[192:195], v[62:65]
	v_mfma_i32_16x16x64_i8 v[58:61], v[122:125], v[188:191], v[58:61]
	v_mfma_i32_16x16x64_i8 v[58:61], v[126:129], v[192:195], v[58:61]
	v_mfma_i32_16x16x64_i8 v[46:49], v[106:109], v[196:199], v[46:49]
	v_mfma_i32_16x16x64_i8 v[46:49], v[110:113], v[200:203], v[46:49]
	v_mfma_i32_16x16x64_i8 v[42:45], v[122:125], v[196:199], v[42:45]
	v_mfma_i32_16x16x64_i8 v[42:45], v[126:129], v[200:203], v[42:45]
	v_mfma_i32_16x16x64_i8 v[30:33], v[106:109], v[204:207], v[30:33]
	v_mfma_i32_16x16x64_i8 v[30:33], v[110:113], v[208:211], v[30:33]
	v_mfma_i32_16x16x64_i8 v[26:29], v[122:125], v[204:207], v[26:29]
	v_mfma_i32_16x16x64_i8 v[26:29], v[126:129], v[208:211], v[26:29]
	v_mfma_i32_16x16x64_i8 v[14:17], v[106:109], v[212:215], v[14:17]
	v_mfma_i32_16x16x64_i8 v[14:17], v[110:113], v[216:219], v[14:17]
	v_mfma_i32_16x16x64_i8 v[10:13], v[122:125], v[212:215], v[10:13]
	v_mfma_i32_16x16x64_i8 v[10:13], v[126:129], v[216:219], v[10:13]
	s_setprio 0
	s_setprio 1
	v_mfma_i32_16x16x64_i8 v[54:57], v[170:173], v[188:191], v[54:57]
	v_mfma_i32_16x16x64_i8 v[54:57], v[174:177], v[192:195], v[54:57]
	v_mfma_i32_16x16x64_i8 v[50:53], v[178:181], v[188:191], v[50:53]
	v_mfma_i32_16x16x64_i8 v[50:53], v[184:187], v[192:195], v[50:53]
	v_mfma_i32_16x16x64_i8 v[38:41], v[170:173], v[196:199], v[38:41]
	v_mfma_i32_16x16x64_i8 v[38:41], v[174:177], v[200:203], v[38:41]
	v_mfma_i32_16x16x64_i8 v[34:37], v[178:181], v[196:199], v[34:37]
	v_mfma_i32_16x16x64_i8 v[34:37], v[184:187], v[200:203], v[34:37]
	v_mfma_i32_16x16x64_i8 v[22:25], v[170:173], v[204:207], v[22:25]
	v_mfma_i32_16x16x64_i8 v[22:25], v[174:177], v[208:211], v[22:25]
	v_mfma_i32_16x16x64_i8 v[18:21], v[178:181], v[204:207], v[18:21]
	v_mfma_i32_16x16x64_i8 v[18:21], v[184:187], v[208:211], v[18:21]
	v_mfma_i32_16x16x64_i8 v[6:9], v[170:173], v[212:215], v[6:9]
	v_mfma_i32_16x16x64_i8 v[6:9], v[174:177], v[216:219], v[6:9]
	v_mfma_i32_16x16x64_i8 v[2:5], v[178:181], v[212:215], v[2:5]
	v_mfma_i32_16x16x64_i8 v[2:5], v[184:187], v[216:219], v[2:5]
	s_setprio 0
	s_barrier
	s_add_i32 s61, s61, 2
	s_add_u32 s38, s38, 0x100
	s_addc_u32 s39, s39, 0
	s_add_u32 s59, s59, 0x100
	s_addc_u32 s60, s60, 0
	s_cmp_gt_u32 s61, 29
	s_cbranch_scc0 .LBB0_1478
	s_and_b64 vcc, exec, s[24:25]
	s_cbranch_vccz .LBB0_1481
	s_barrier

; #define PG8_STAGE(bufoff, gbase, voff) do { _Pragma("unroll") for (int _i = 0; _i < 2; ++_i) \
;         __builtin_amdgcn_global_load_lds((const unsigned*)((const char*)(gbase) + (voff)[_i]), (LAS unsigned*)(lds + (bufoff) + ldsw + _i * 8192), 16, 0, 0); } while (0)
; #define PG8_LDA(dst, b, h) do { _Pragma("unroll") for (int m = 0; m < 4; ++m) _Pragma("unroll") for (int k = 0; k < 2; ++k) dst[m][k] = *(const LAS bf16x8*)(lds + PG8_SA(b, h) + aoff + m * 2048 + k * 1024); } while (0)
; #define PG8_LDB(dst, b, h) do { _Pragma("unroll") for (int n = 0; n < 2; ++n) _Pragma("unroll") for (int k = 0; k < 2; ++k) dst[n][k] = *(const LAS bf16x8*)(lds + PG8_SB(b, h) + boff + n * 2048 + k * 1024); } while (0)
; #define PG8_WAIT_V(n) asm volatile("s_waitcnt vmcnt(" #n ")" ::: "memory")
; #define PG8_WAIT_L(n) asm volatile("s_waitcnt lgkmcnt(" #n ")" ::: "memory")
; #define PG8_BAR __builtin_amdgcn_s_barrier()
; #define PG8_SCHED __builtin_amdgcn_sched_barrier(0)
; template <class Epi, class Sched, class Ptrs, bool ALIGN_EPI, bool I8 = false>
; __device__ __forceinline__ void gemm_phase(LAS unsigned char* lds, const Ptrs& P, const Sched& S, const Epi& E) {
;     ...
;             PG8_LDB(B0, 0, 0); PG8_LDB(B1, 0, 1); PG8_SCHED; PG8_LDA(At, 0, 0); PG8_STAGE(PG8_SA(1, 1), a1 + hstepA, voffA);
;             PG8_WAIT_V(8); PG8_WAIT_L(0); PG8_BAR; PG8_MMA(0, 0, At, B0); PG8_MMA(0, 1, At, B1); PG8_BAR; PG8_SCHED;
;             PG8_LDA(At, 0, 1); PG8_STAGE(PG8_SB(0, 0), b2, voffB); PG8_STAGE(PG8_SB(0, 1), b2 + hstepB, voffB); PG8_STAGE(PG8_SA(0, 0), a2, voffA);
;             PG8_WAIT_V(8); PG8_WAIT_L(0); PG8_BAR; PG8_MMA(1, 0, At, B0); PG8_MMA(1, 1, At, B1); PG8_BAR; PG8_SCHED;
.LBB0_1634:
	ds_read_b128 v[64:67], v217
	ds_read_b128 v[68:71], v217 offset:1024
	ds_read_b128 v[72:75], v217 offset:2048
	ds_read_b128 v[76:79], v217 offset:3072
	ds_read_b128 v[80:83], v219
	ds_read_b128 v[92:95], v219 offset:1024
	ds_read_b128 v[152:155], v219 offset:2048
	ds_read_b128 v[156:159], v219 offset:3072
	s_add_u32 s36, s34, 0xffdfc080
	s_addc_u32 s37, s35, -1
	s_cmpk_eq_i32 s56, 0x7c
	s_cselect_b32 s39, s9, s37
	s_cselect_b32 s38, s8, s36
	s_cselect_b32 s37, s31, s55
	s_cselect_b32 s36, s30, s54
	v_lshl_add_u64 v[206:207], s[34:35], 0, v[186:187]
	s_add_i32 m0, s33, 0xc000
	ds_read_b128 v[160:163], v225
	ds_read_b128 v[164:167], v225 offset:1024
	ds_read_b128 v[168:171], v225 offset:2048
	ds_read_b128 v[172:175], v225 offset:3072
	ds_read_b128 v[194:197], v225 offset:4096
	ds_read_b128 v[198:201], v225 offset:5120
	ds_read_b128 v[202:205], v225 offset:6144
	ds_read_b128 v[212:215], v225 offset:7168
	global_load_lds_dwordx4 v[206:207], off
	v_lshl_add_u64 v[206:207], s[34:35], 0, v[188:189]
	s_add_i32 m0, s33, 0xe000
	s_nop 0
	global_load_lds_dwordx4 v[206:207], off
	s_waitcnt vmcnt(8)
	s_waitcnt lgkmcnt(0)
	s_barrier
	s_setprio 1
	s_waitcnt lgkmcnt(0)
	v_mfma_i32_16x16x64_i8 v[88:91], v[64:67], v[160:163], v[88:91]
	v_mfma_i32_16x16x64_i8 v[88:91], v[68:71], v[164:167], v[88:91]
	v_mfma_i32_16x16x64_i8 v[84:87], v[72:75], v[160:163], v[84:87]
	v_mfma_i32_16x16x64_i8 v[84:87], v[76:79], v[164:167], v[84:87]
	v_mfma_i32_16x16x64_i8 v[140:143], v[64:67], v[168:171], v[140:143]
	v_mfma_i32_16x16x64_i8 v[140:143], v[68:71], v[172:175], v[140:143]
	v_mfma_i32_16x16x64_i8 v[136:139], v[72:75], v[168:171], v[136:139]
	v_mfma_i32_16x16x64_i8 v[136:139], v[76:79], v[172:175], v[136:139]
	v_mfma_i32_16x16x64_i8 v[124:127], v[64:67], v[194:197], v[124:127]
	v_mfma_i32_16x16x64_i8 v[124:127], v[68:71], v[198:201], v[124:127]
	v_mfma_i32_16x16x64_i8 v[120:123], v[72:75], v[194:197], v[120:123]
	v_mfma_i32_16x16x64_i8 v[120:123], v[76:79], v[198:201], v[120:123]
	v_mfma_i32_16x16x64_i8 v[108:111], v[64:67], v[202:205], v[108:111]
	v_mfma_i32_16x16x64_i8 v[108:111], v[68:71], v[212:215], v[108:111]
	v_mfma_i32_16x16x64_i8 v[104:107], v[72:75], v[202:205], v[104:107]
	v_mfma_i32_16x16x64_i8 v[104:107], v[76:79], v[212:215], v[104:107]
	s_setprio 0
	s_setprio 1
	v_mfma_i32_16x16x64_i8 v[148:151], v[80:83], v[160:163], v[148:151]
	v_mfma_i32_16x16x64_i8 v[148:151], v[92:95], v[164:167], v[148:151]
	v_mfma_i32_16x16x64_i8 v[144:147], v[152:155], v[160:163], v[144:147]
	v_mfma_i32_16x16x64_i8 v[144:147], v[156:159], v[164:167], v[144:147]
	v_mfma_i32_16x16x64_i8 v[132:135], v[80:83], v[168:171], v[132:135]
	v_mfma_i32_16x16x64_i8 v[132:135], v[92:95], v[172:175], v[132:135]
	v_mfma_i32_16x16x64_i8 v[128:131], v[152:155], v[168:171], v[128:131]
	v_mfma_i32_16x16x64_i8 v[128:131], v[156:159], v[172:175], v[128:131]
	v_mfma_i32_16x16x64_i8 v[116:119], v[80:83], v[194:197], v[116:119]
	v_mfma_i32_16x16x64_i8 v[116:119], v[92:95], v[198:201], v[116:119]
	v_mfma_i32_16x16x64_i8 v[112:115], v[152:155], v[194:197], v[112:115]
	v_mfma_i32_16x16x64_i8 v[112:115], v[156:159], v[198:201], v[112:115]
	v_mfma_i32_16x16x64_i8 v[100:103], v[80:83], v[202:205], v[100:103]
	v_mfma_i32_16x16x64_i8 v[100:103], v[92:95], v[212:215], v[100:103]
	v_mfma_i32_16x16x64_i8 v[96:99], v[152:155], v[202:205], v[96:99]
	v_mfma_i32_16x16x64_i8 v[96:99], v[156:159], v[212:215], v[96:99]
	s_setprio 0
	s_barrier
	s_add_i32 s57, s48, s3
	v_lshl_add_u64 v[206:207], s[36:37], 0, v[178:179]
	s_mov_b32 m0, s57
	ds_read_b128 v[160:163], v225 offset:16384
	ds_read_b128 v[164:167], v225 offset:17408
	ds_read_b128 v[168:171], v225 offset:18432
	ds_read_b128 v[172:175], v225 offset:19456
	ds_read_b128 v[194:197], v225 offset:20480
	ds_read_b128 v[198:201], v225 offset:21504
	ds_read_b128 v[202:205], v225 offset:22528
	ds_read_b128 v[212:215], v225 offset:23552
	global_load_lds_dwordx4 v[206:207], off
	s_add_i32 m0, s57, 0x2000
	s_add_u32 s58, s36, 0x204000
	v_lshl_add_u64 v[220:221], s[36:37], 0, v[184:185]
	s_addc_u32 s59, s37, 0
	s_add_i32 s57, s49, s3
	global_load_lds_dwordx4 v[220:221], off
	v_lshl_add_u64 v[222:223], s[58:59], 0, v[178:179]
	s_mov_b32 m0, s57
	v_lshl_add_u64 v[228:229], s[38:39], 0, v[180:181]
	global_load_lds_dwordx4 v[222:223], off
	v_lshl_add_u64 v[222:223], s[58:59], 0, v[184:185]
	s_add_i32 m0, s57, 0x2000
	s_nop 0
	global_load_lds_dwordx4 v[222:223], off
	v_lshl_add_u64 v[222:223], s[38:39], 0, v[176:177]
	s_mov_b32 m0, s33
	s_nop 0
	global_load_lds_dwordx4 v[222:223], off
	s_mov_b32 m0, s40
	s_nop 0
	global_load_lds_dwordx4 v[228:229], off
	s_waitcnt vmcnt(8)
	s_waitcnt lgkmcnt(0)
	s_barrier
; #define PG8_STAGE(bufoff, gbase, voff) do { _Pragma("unroll") for (int _i = 0; _i < 2; ++_i) \
;         __builtin_amdgcn_global_load_lds((const unsigned*)((const char*)(gbase) + (voff)[_i]), (LAS unsigned*)(lds + (bufoff) + ldsw + _i * 8192), 16, 0, 0); } while (0)
; #define PG8_LDA(dst, b, h) do { _Pragma("unroll") for (int m = 0; m < 4; ++m) _Pragma("unroll") for (int k = 0; k < 2; ++k) dst[m][k] = *(const LAS bf16x8*)(lds + PG8_SA(b, h) + aoff + m * 2048 + k * 1024); } while (0)
; #define PG8_LDB(dst, b, h) do { _Pragma("unroll") for (int n = 0; n < 2; ++n) _Pragma("unroll") for (int k = 0; k < 2; ++k) dst[n][k] = *(const LAS bf16x8*)(lds + PG8_SB(b, h) + boff + n * 2048 + k * 1024); } while (0)
; #define PG8_WAIT_V(n) asm volatile("s_waitcnt vmcnt(" #n ")" ::: "memory")
; #define PG8_WAIT_L(n) asm volatile("s_waitcnt lgkmcnt(" #n ")" ::: "memory")
; #define PG8_BAR __builtin_amdgcn_s_barrier()
; #define PG8_SCHED __builtin_amdgcn_sched_barrier(0)
; template <class Epi, class Sched, class Ptrs, bool ALIGN_EPI, bool I8 = false>
; __device__ __forceinline__ void gemm_phase(LAS unsigned char* lds, const Ptrs& P, const Sched& S, const Epi& E) {
;     ...
;             PG8_LDA(At, 0, 1); PG8_STAGE(PG8_SB(0, 0), b2, voffB); PG8_STAGE(PG8_SB(0, 1), b2 + hstepB, voffB); PG8_STAGE(PG8_SA(0, 0), a2, voffA);
;             PG8_WAIT_V(8); PG8_WAIT_L(0); PG8_BAR; PG8_MMA(1, 0, At, B0); PG8_MMA(1, 1, At, B1); PG8_BAR; PG8_SCHED;
;             PG8_LDB(B0, 1, 0); PG8_LDB(B1, 1, 1); PG8_SCHED; PG8_LDA(At, 1, 0); PG8_STAGE(PG8_SA(0, 1), a2 + hstepA, voffA);
;             PG8_WAIT_V(8); PG8_WAIT_L(0); PG8_BAR; PG8_MMA(0, 0, At, B0); PG8_MMA(0, 1, At, B1); PG8_BAR; PG8_SCHED;
;             PG8_LDA(At, 1, 1); PG8_STAGE(PG8_SB(1, 0), b3, voffB); PG8_STAGE(PG8_SB(1, 1), b3 + hstepB, voffB); PG8_STAGE(PG8_SA(1, 0), a3, voffA);
	s_setprio 1
	s_waitcnt lgkmcnt(0)
	v_mfma_i32_16x16x64_i8 v[60:63], v[64:67], v[160:163], v[60:63]
	v_mfma_i32_16x16x64_i8 v[60:63], v[68:71], v[164:167], v[60:63]
	v_mfma_i32_16x16x64_i8 v[56:59], v[72:75], v[160:163], v[56:59]
	v_mfma_i32_16x16x64_i8 v[56:59], v[76:79], v[164:167], v[56:59]
	v_mfma_i32_16x16x64_i8 v[44:47], v[64:67], v[168:171], v[44:47]
	v_mfma_i32_16x16x64_i8 v[44:47], v[68:71], v[172:175], v[44:47]
	v_mfma_i32_16x16x64_i8 v[40:43], v[72:75], v[168:171], v[40:43]
	v_mfma_i32_16x16x64_i8 v[40:43], v[76:79], v[172:175], v[40:43]
	v_mfma_i32_16x16x64_i8 v[28:31], v[64:67], v[194:197], v[28:31]
	v_mfma_i32_16x16x64_i8 v[28:31], v[68:71], v[198:201], v[28:31]
	v_mfma_i32_16x16x64_i8 v[24:27], v[72:75], v[194:197], v[24:27]
	v_mfma_i32_16x16x64_i8 v[24:27], v[76:79], v[198:201], v[24:27]
	v_mfma_i32_16x16x64_i8 v[12:15], v[64:67], v[202:205], v[12:15]
	v_mfma_i32_16x16x64_i8 v[12:15], v[68:71], v[212:215], v[12:15]
	v_mfma_i32_16x16x64_i8 v[8:11], v[72:75], v[202:205], v[8:11]
	v_mfma_i32_16x16x64_i8 v[8:11], v[76:79], v[212:215], v[8:11]
	s_setprio 0
	s_setprio 1
	v_mfma_i32_16x16x64_i8 v[52:55], v[80:83], v[160:163], v[52:55]
	v_mfma_i32_16x16x64_i8 v[52:55], v[92:95], v[164:167], v[52:55]
	v_mfma_i32_16x16x64_i8 v[48:51], v[152:155], v[160:163], v[48:51]
	v_mfma_i32_16x16x64_i8 v[48:51], v[156:159], v[164:167], v[48:51]
	v_mfma_i32_16x16x64_i8 v[36:39], v[80:83], v[168:171], v[36:39]
	v_mfma_i32_16x16x64_i8 v[36:39], v[92:95], v[172:175], v[36:39]
	v_mfma_i32_16x16x64_i8 v[32:35], v[152:155], v[168:171], v[32:35]
	v_mfma_i32_16x16x64_i8 v[32:35], v[156:159], v[172:175], v[32:35]
	v_mfma_i32_16x16x64_i8 v[20:23], v[80:83], v[194:197], v[20:23]
	v_mfma_i32_16x16x64_i8 v[20:23], v[92:95], v[198:201], v[20:23]
	v_mfma_i32_16x16x64_i8 v[16:19], v[152:155], v[194:197], v[16:19]
	v_mfma_i32_16x16x64_i8 v[16:19], v[156:159], v[198:201], v[16:19]
	v_mfma_i32_16x16x64_i8 v[4:7], v[80:83], v[202:205], v[4:7]
	v_mfma_i32_16x16x64_i8 v[4:7], v[92:95], v[212:215], v[4:7]
	v_mfma_i32_16x16x64_i8 v[0:3], v[152:155], v[202:205], v[0:3]
	v_mfma_i32_16x16x64_i8 v[0:3], v[156:159], v[212:215], v[0:3]
	s_setprio 0
	s_barrier
	s_add_i32 s57, 0, 0x18000
	s_add_i32 s58, 0, 0x1c000
	v_add_u32_e32 v76, s57, v209
	v_add_u32_e32 v156, s58, v209
	ds_read_b128 v[64:67], v76
	ds_read_b128 v[68:71], v76 offset:1024
	ds_read_b128 v[72:75], v76 offset:2048
	ds_read_b128 v[76:79], v76 offset:3072
	ds_read_b128 v[80:83], v156
	ds_read_b128 v[92:95], v156 offset:1024
	ds_read_b128 v[152:155], v156 offset:2048
	ds_read_b128 v[156:159], v156 offset:3072
	s_add_u32 s38, s38, 0x204000
	s_addc_u32 s39, s39, 0
	s_mov_b32 m0, s41
	v_lshl_add_u64 v[230:231], s[38:39], 0, v[176:177]
	ds_read_b128 v[160:163], v225 offset:32768
	ds_read_b128 v[164:167], v225 offset:33792
	ds_read_b128 v[168:171], v225 offset:34816
	ds_read_b128 v[172:175], v225 offset:35840
	ds_read_b128 v[194:197], v225 offset:36864
	ds_read_b128 v[198:201], v225 offset:37888
	ds_read_b128 v[202:205], v225 offset:38912
	ds_read_b128 v[212:215], v225 offset:39936
	global_load_lds_dwordx4 v[230:231], off
	v_lshl_add_u64 v[230:231], s[38:39], 0, v[180:181]
	s_mov_b32 m0, s42
	s_nop 0
	global_load_lds_dwordx4 v[230:231], off
	s_waitcnt vmcnt(8)
	s_waitcnt lgkmcnt(0)
	s_barrier
	s_setprio 1
	s_waitcnt lgkmcnt(0)
	v_mfma_i32_16x16x64_i8 v[88:91], v[64:67], v[160:163], v[88:91]
	v_mfma_i32_16x16x64_i8 v[88:91], v[68:71], v[164:167], v[88:91]
	v_mfma_i32_16x16x64_i8 v[84:87], v[72:75], v[160:163], v[84:87]
	v_mfma_i32_16x16x64_i8 v[84:87], v[76:79], v[164:167], v[84:87]
	v_mfma_i32_16x16x64_i8 v[140:143], v[64:67], v[168:171], v[140:143]
	v_mfma_i32_16x16x64_i8 v[140:143], v[68:71], v[172:175], v[140:143]
	v_mfma_i32_16x16x64_i8 v[136:139], v[72:75], v[168:171], v[136:139]
	v_mfma_i32_16x16x64_i8 v[136:139], v[76:79], v[172:175], v[136:139]
	v_mfma_i32_16x16x64_i8 v[124:127], v[64:67], v[194:197], v[124:127]
	v_mfma_i32_16x16x64_i8 v[124:127], v[68:71], v[198:201], v[124:127]
	v_mfma_i32_16x16x64_i8 v[120:123], v[72:75], v[194:197], v[120:123]
	v_mfma_i32_16x16x64_i8 v[120:123], v[76:79], v[198:201], v[120:123]
	v_mfma_i32_16x16x64_i8 v[108:111], v[64:67], v[202:205], v[108:111]
	v_mfma_i32_16x16x64_i8 v[108:111], v[68:71], v[212:215], v[108:111]
	v_mfma_i32_16x16x64_i8 v[104:107], v[72:75], v[202:205], v[104:107]
	v_mfma_i32_16x16x64_i8 v[104:107], v[76:79], v[212:215], v[104:107]
	s_setprio 0
	s_setprio 1
	v_mfma_i32_16x16x64_i8 v[148:151], v[80:83], v[160:163], v[148:151]
	v_mfma_i32_16x16x64_i8 v[148:151], v[92:95], v[164:167], v[148:151]
	v_mfma_i32_16x16x64_i8 v[144:147], v[152:155], v[160:163], v[144:147]
	v_mfma_i32_16x16x64_i8 v[144:147], v[156:159], v[164:167], v[144:147]
	v_mfma_i32_16x16x64_i8 v[132:135], v[80:83], v[168:171], v[132:135]
	v_mfma_i32_16x16x64_i8 v[132:135], v[92:95], v[172:175], v[132:135]
	v_mfma_i32_16x16x64_i8 v[128:131], v[152:155], v[168:171], v[128:131]
	v_mfma_i32_16x16x64_i8 v[128:131], v[156:159], v[172:175], v[128:131]
	v_mfma_i32_16x16x64_i8 v[116:119], v[80:83], v[194:197], v[116:119]
	v_mfma_i32_16x16x64_i8 v[116:119], v[92:95], v[198:201], v[116:119]
	v_mfma_i32_16x16x64_i8 v[112:115], v[152:155], v[194:197], v[112:115]
	v_mfma_i32_16x16x64_i8 v[112:115], v[156:159], v[198:201], v[112:115]
	v_mfma_i32_16x16x64_i8 v[100:103], v[80:83], v[202:205], v[100:103]
	v_mfma_i32_16x16x64_i8 v[100:103], v[92:95], v[212:215], v[100:103]
	v_mfma_i32_16x16x64_i8 v[96:99], v[152:155], v[202:205], v[96:99]
	v_mfma_i32_16x16x64_i8 v[96:99], v[156:159], v[212:215], v[96:99]
	s_setprio 0
	s_barrier
; #define PG8_STAGE(bufoff, gbase, voff) do { _Pragma("unroll") for (int _i = 0; _i < 2; ++_i) \
;         __builtin_amdgcn_global_load_lds((const unsigned*)((const char*)(gbase) + (voff)[_i]), (LAS unsigned*)(lds + (bufoff) + ldsw + _i * 8192), 16, 0, 0); } while (0)
; #define PG8_LDA(dst, b, h) do { _Pragma("unroll") for (int m = 0; m < 4; ++m) _Pragma("unroll") for (int k = 0; k < 2; ++k) dst[m][k] = *(const LAS bf16x8*)(lds + PG8_SA(b, h) + aoff + m * 2048 + k * 1024); } while (0)
; #define PG8_WAIT_V(n) asm volatile("s_waitcnt vmcnt(" #n ")" ::: "memory")
; #define PG8_WAIT_L(n) asm volatile("s_waitcnt lgkmcnt(" #n ")" ::: "memory")
; #define PG8_BAR __builtin_amdgcn_s_barrier()
; #define PG8_SCHED __builtin_amdgcn_sched_barrier(0)
; template <class Epi, class Sched, class Ptrs, bool ALIGN_EPI, bool I8 = false>
; __device__ __forceinline__ void gemm_phase(LAS unsigned char* lds, const Ptrs& P, const Sched& S, const Epi& E) {
;     ...
;             PG8_LDA(At, 1, 1); PG8_STAGE(PG8_SB(1, 0), b3, voffB); PG8_STAGE(PG8_SB(1, 1), b3 + hstepB, voffB); PG8_STAGE(PG8_SA(1, 0), a3, voffA);
;             PG8_WAIT_V(8); PG8_WAIT_L(0); PG8_BAR; PG8_MMA(1, 0, At, B0); PG8_MMA(1, 1, At, B1); PG8_BAR; PG8_SCHED;
;         }
;         if constexpr (ALIGN_EPI) { if (wr == 0) PG8_BAR; }
	s_add_i32 s38, s57, s3
	v_lshl_add_u64 v[206:207], v[206:207], 0, s[26:27]
	s_mov_b32 m0, s38
	ds_read_b128 v[160:163], v225 offset:49152
	ds_read_b128 v[164:167], v225 offset:50176
	ds_read_b128 v[168:171], v225 offset:51200
	ds_read_b128 v[172:175], v225 offset:52224
	ds_read_b128 v[194:197], v225 offset:53248
	ds_read_b128 v[198:201], v225 offset:54272
	ds_read_b128 v[202:205], v225 offset:55296
	ds_read_b128 v[212:215], v225 offset:56320
	global_load_lds_dwordx4 v[206:207], off
	s_add_i32 m0, s38, 0x2000
	s_add_u32 s36, s36, 0x204080
	v_lshl_add_u64 v[206:207], v[220:221], 0, s[26:27]
	s_addc_u32 s37, s37, 0
	s_add_i32 s38, s58, s3
	global_load_lds_dwordx4 v[206:207], off
	v_lshl_add_u64 v[206:207], s[36:37], 0, v[178:179]
	s_mov_b32 m0, s38
	s_nop 0
	global_load_lds_dwordx4 v[206:207], off
	v_lshl_add_u64 v[206:207], s[36:37], 0, v[184:185]
	s_add_i32 m0, s38, 0x2000
	s_nop 0
	global_load_lds_dwordx4 v[206:207], off
	v_lshl_add_u64 v[206:207], v[222:223], 0, s[26:27]
	s_mov_b32 m0, s44
	s_nop 0
	global_load_lds_dwordx4 v[206:207], off
	v_lshl_add_u64 v[206:207], v[228:229], 0, s[26:27]
	s_mov_b32 m0, s45
	s_nop 0
	global_load_lds_dwordx4 v[206:207], off
	s_waitcnt vmcnt(8)
	s_waitcnt lgkmcnt(0)
	s_barrier
	s_setprio 1
	s_waitcnt lgkmcnt(0)
	v_mfma_i32_16x16x64_i8 v[60:63], v[64:67], v[160:163], v[60:63]
	v_mfma_i32_16x16x64_i8 v[60:63], v[68:71], v[164:167], v[60:63]
	v_mfma_i32_16x16x64_i8 v[56:59], v[72:75], v[160:163], v[56:59]
	v_mfma_i32_16x16x64_i8 v[56:59], v[76:79], v[164:167], v[56:59]
	v_mfma_i32_16x16x64_i8 v[44:47], v[64:67], v[168:171], v[44:47]
	v_mfma_i32_16x16x64_i8 v[44:47], v[68:71], v[172:175], v[44:47]
	v_mfma_i32_16x16x64_i8 v[40:43], v[72:75], v[168:171], v[40:43]
	v_mfma_i32_16x16x64_i8 v[40:43], v[76:79], v[172:175], v[40:43]
	v_mfma_i32_16x16x64_i8 v[28:31], v[64:67], v[194:197], v[28:31]
	v_mfma_i32_16x16x64_i8 v[28:31], v[68:71], v[198:201], v[28:31]
	v_mfma_i32_16x16x64_i8 v[24:27], v[72:75], v[194:197], v[24:27]
	v_mfma_i32_16x16x64_i8 v[24:27], v[76:79], v[198:201], v[24:27]
	v_mfma_i32_16x16x64_i8 v[12:15], v[64:67], v[202:205], v[12:15]
	v_mfma_i32_16x16x64_i8 v[12:15], v[68:71], v[212:215], v[12:15]
	v_mfma_i32_16x16x64_i8 v[8:11], v[72:75], v[202:205], v[8:11]
	v_mfma_i32_16x16x64_i8 v[8:11], v[76:79], v[212:215], v[8:11]
	s_setprio 0
	s_setprio 1
	v_mfma_i32_16x16x64_i8 v[52:55], v[80:83], v[160:163], v[52:55]
	v_mfma_i32_16x16x64_i8 v[52:55], v[92:95], v[164:167], v[52:55]
	v_mfma_i32_16x16x64_i8 v[48:51], v[152:155], v[160:163], v[48:51]
	v_mfma_i32_16x16x64_i8 v[48:51], v[156:159], v[164:167], v[48:51]
	v_mfma_i32_16x16x64_i8 v[36:39], v[80:83], v[168:171], v[36:39]
	v_mfma_i32_16x16x64_i8 v[36:39], v[92:95], v[172:175], v[36:39]
	v_mfma_i32_16x16x64_i8 v[32:35], v[152:155], v[168:171], v[32:35]
	v_mfma_i32_16x16x64_i8 v[32:35], v[156:159], v[172:175], v[32:35]
	v_mfma_i32_16x16x64_i8 v[20:23], v[80:83], v[194:197], v[20:23]
	v_mfma_i32_16x16x64_i8 v[20:23], v[92:95], v[198:201], v[20:23]
	v_mfma_i32_16x16x64_i8 v[16:19], v[152:155], v[194:197], v[16:19]
	v_mfma_i32_16x16x64_i8 v[16:19], v[156:159], v[198:201], v[16:19]
	v_mfma_i32_16x16x64_i8 v[4:7], v[80:83], v[202:205], v[4:7]
	v_mfma_i32_16x16x64_i8 v[4:7], v[92:95], v[212:215], v[4:7]
	v_mfma_i32_16x16x64_i8 v[0:3], v[152:155], v[202:205], v[0:3]
	v_mfma_i32_16x16x64_i8 v[0:3], v[156:159], v[212:215], v[0:3]
	s_setprio 0
	s_barrier
	s_add_i32 s56, s56, 2
	s_add_u32 s34, s34, 0x100
	s_addc_u32 s35, s35, 0
	s_add_u32 s54, s54, 0x100
	s_addc_u32 s55, s55, 0
	s_cmpk_gt_u32 s56, 0x7d
	s_cbranch_scc0 .LBB0_1634
	s_and_b64 vcc, exec, s[28:29]
	s_cbranch_vccz .LBB0_1637
	s_barrier
